# combine routine restructured for ILP (4 dwords in lockstep); attention epilogue row-sum shuffles via DPP instead of ds_bpermute
# baseline (speedup 1.0000x reference)
.LBB0_447:
	v_add_u32_e32 v182, s19, v220
	ds_read_b64_tr_b16 v[184:185], v182 offset:24576
	ds_read_b64_tr_b16 v[186:187], v182 offset:25088
	v_add_f32_e32 v84, v64, v65
	v_add_f32_e32 v84, v66, v84
	v_add_f32_e32 v84, v67, v84
	v_add_f32_e32 v84, v68, v84
	v_add_f32_e32 v84, v69, v84
	v_cvt_pk_bf16_f32 v156, v64, v65
	v_cvt_pk_bf16_f32 v157, v66, v67
	s_waitcnt lgkmcnt(9)
	v_mfma_f32_32x32x16_bf16 v[96:111], v[80:83], v[140:143], v[32:47]
	ds_read_b64_tr_b16 v[64:65], v182 offset:28672
	ds_read_b64_tr_b16 v[66:67], v182 offset:29184
	v_add_f32_e32 v80, v70, v84
	v_add_f32_e32 v80, v71, v80
	v_add_f32_e32 v80, v72, v80
	v_add_f32_e32 v136, v73, v80
	s_waitcnt lgkmcnt(10)
	v_mfma_f32_32x32x16_bf16 v[80:95], v[168:171], v[140:143], v[32:47]
	v_cvt_pk_bf16_f32 v158, v68, v69
	v_cvt_pk_bf16_f32 v159, v70, v71
	ds_read_b64_tr_b16 v[68:69], v182 offset:25600
	ds_read_b64_tr_b16 v[70:71], v182 offset:26112
	v_add_f32_e32 v136, v74, v136
	v_add_f32_e32 v136, v75, v136
	v_add_f32_e32 v136, v76, v136
	v_add_f32_e32 v136, v77, v136
	v_cvt_pk_bf16_f32 v152, v72, v73
	v_cvt_pk_bf16_f32 v153, v74, v75
	s_waitcnt lgkmcnt(11)
	v_mfma_f32_32x32x16_bf16 v[96:111], v[164:167], v[132:135], v[96:111]
	ds_read_b64_tr_b16 v[72:73], v182 offset:29696
	ds_read_b64_tr_b16 v[74:75], v182 offset:30208
	s_waitcnt lgkmcnt(12)
	v_mfma_f32_32x32x16_bf16 v[80:95], v[160:163], v[132:135], v[80:95]
	v_add_f32_e32 v136, v78, v136
	v_add_f32_e32 v136, v79, v136
	v_add_f32_e32 v136, v48, v136
	v_add_f32_e32 v136, v49, v136
	v_cvt_pk_bf16_f32 v154, v76, v77
	v_cvt_pk_bf16_f32 v155, v78, v79
	ds_read_b64_tr_b16 v[76:77], v182 offset:26624
	ds_read_b64_tr_b16 v[78:79], v182 offset:27136
	v_add_f32_e32 v136, v50, v136
	v_add_f32_e32 v136, v51, v136
	v_add_f32_e32 v136, v52, v136
	v_add_f32_e32 v136, v53, v136
	v_cvt_pk_bf16_f32 v144, v48, v49
	v_cvt_pk_bf16_f32 v145, v50, v51
	s_waitcnt lgkmcnt(13)
	v_mfma_f32_32x32x16_bf16 v[96:111], v[124:127], v[128:131], v[96:111]
	ds_read_b64_tr_b16 v[48:49], v182 offset:30720
	ds_read_b64_tr_b16 v[50:51], v182 offset:31232
	s_waitcnt lgkmcnt(14)
	v_mfma_f32_32x32x16_bf16 v[80:95], v[120:123], v[128:131], v[80:95]
	v_add_f32_e32 v124, v54, v136
	v_add_f32_e32 v124, v55, v124
	v_add_f32_e32 v124, v56, v124
	v_add_f32_e32 v124, v57, v124
	v_cvt_pk_bf16_f32 v146, v52, v53
	v_cvt_pk_bf16_f32 v147, v54, v55
	ds_read_b64_tr_b16 v[52:53], v182 offset:27648
	ds_read_b64_tr_b16 v[54:55], v182 offset:28160
	v_add_f32_e32 v120, v58, v124
	v_add_f32_e32 v120, v59, v120
	v_add_f32_e32 v120, v60, v120
	v_add_f32_e32 v120, v61, v120
	v_cvt_pk_bf16_f32 v136, v56, v57
	v_cvt_pk_bf16_f32 v137, v58, v59
	s_waitcnt lgkmcnt(14)
	v_mfma_f32_32x32x16_bf16 v[96:111], v[116:119], v[148:151], v[96:111]
	ds_read_b64_tr_b16 v[56:57], v182 offset:31744
	ds_read_b64_tr_b16 v[58:59], v182 offset:32256
	v_mfma_f32_32x32x16_bf16 v[80:95], v[112:115], v[148:151], v[80:95]
	v_add_f32_e32 v116, v62, v120
	v_add_f32_e32 v116, v63, v116
	v_add_f32_e32 v182, 0, v116
	v_cvt_pk_bf16_f32 v138, v60, v61
	v_cvt_pk_bf16_f32 v139, v62, v63
	v_lshl_add_u64 v[60:61], v[176:177], 0, s[40:41]
	s_add_i32 s10, s18, s76
	s_mov_b32 s16, m0
	s_mov_b32 m0, s10
	s_nop 0
	global_load_lds_dwordx4 v[60:61], off
	s_mov_b32 m0, s16
	v_lshl_add_u64 v[60:61], v[178:179], 0, s[14:15]
	s_add_i32 s10, s5, s57
	s_mov_b32 s16, m0
	s_mov_b32 m0, s10
	s_nop 0
	global_load_lds_dwordx4 v[60:61], off
	s_mov_b32 m0, s16
	s_waitcnt lgkmcnt(14)
	v_mfma_f32_32x32x16_bf16 v[0:15], v[156:159], v[184:187], v[0:15]
	v_exp_f32_e32 v96, v96
	v_exp_f32_e32 v97, v97
	v_exp_f32_e32 v98, v98
	v_exp_f32_e32 v99, v99
	s_waitcnt lgkmcnt(12)
	v_mfma_f32_32x32x16_bf16 v[16:31], v[156:159], v[64:67], v[16:31]
	v_exp_f32_e32 v100, v100
	v_exp_f32_e32 v101, v101
	v_exp_f32_e32 v102, v102
	v_exp_f32_e32 v103, v103
	v_add_u32_e32 v64, s5, v199
	ds_read_b128 v[60:63], v64
	ds_read_b128 v[112:115], v64 offset:512
	s_waitcnt lgkmcnt(12)
	v_mfma_f32_32x32x16_bf16 v[0:15], v[152:155], v[68:71], v[0:15]
	v_exp_f32_e32 v104, v104
	v_exp_f32_e32 v105, v105
	v_exp_f32_e32 v106, v106
	v_exp_f32_e32 v107, v107
	ds_read_b128 v[116:119], v64 offset:2048
	ds_read_b128 v[120:123], v64 offset:2560
	s_waitcnt lgkmcnt(12)
	v_mfma_f32_32x32x16_bf16 v[16:31], v[152:155], v[72:75], v[16:31]
	v_exp_f32_e32 v108, v108
	v_exp_f32_e32 v109, v109
	v_exp_f32_e32 v110, v110
	v_exp_f32_e32 v111, v111
	ds_read_b128 v[124:127], v64 offset:4096
	ds_read_b128 v[160:163], v64 offset:4608
	s_waitcnt lgkmcnt(12)
	v_mfma_f32_32x32x16_bf16 v[0:15], v[144:147], v[76:79], v[0:15]
	v_exp_f32_e32 v80, v80
	v_exp_f32_e32 v81, v81
	v_exp_f32_e32 v82, v82
	v_exp_f32_e32 v83, v83
	ds_read_b128 v[164:167], v64 offset:6144
	ds_read_b128 v[168:171], v64 offset:6656
	s_waitcnt lgkmcnt(12)
	v_mfma_f32_32x32x16_bf16 v[16:31], v[144:147], v[48:51], v[16:31]
	v_exp_f32_e32 v84, v84
	v_exp_f32_e32 v85, v85
	v_exp_f32_e32 v86, v86
	v_exp_f32_e32 v87, v87
	s_waitcnt lgkmcnt(10)
	v_mfma_f32_32x32x16_bf16 v[0:15], v[136:139], v[52:55], v[0:15]
	v_exp_f32_e32 v88, v88
	v_exp_f32_e32 v89, v89
	v_exp_f32_e32 v90, v90
	v_exp_f32_e32 v91, v91
	s_waitcnt lgkmcnt(8)
	v_mfma_f32_32x32x16_bf16 v[16:31], v[136:139], v[56:59], v[16:31]
	v_exp_f32_e32 v92, v92
	v_exp_f32_e32 v93, v93
	v_exp_f32_e32 v94, v94
	v_exp_f32_e32 v95, v95
	s_waitcnt vmcnt(2) lgkmcnt(0)
	s_barrier
	s_add_i32 s10, s5, 0x2000
	s_cmpk_lg_i32 s5, 0x4000
	s_cselect_b32 s10, s10, 0
	v_add_u32_e32 v183, s18, v220
	ds_read_b64_tr_b16 v[184:185], v183 offset:24576
	ds_read_b64_tr_b16 v[186:187], v183 offset:25088
	s_waitcnt lgkmcnt(9)
	v_mfma_f32_32x32x16_bf16 v[64:79], v[60:63], v[140:143], v[32:47]
	v_add_f32_e32 v48, v96, v97
	v_add_f32_e32 v48, v98, v48
	v_add_f32_e32 v48, v99, v48
	v_add_f32_e32 v48, v100, v48
	v_add_f32_e32 v48, v101, v48
	v_cvt_pk_bf16_f32 v156, v96, v97
	v_cvt_pk_bf16_f32 v157, v98, v99
	ds_read_b64_tr_b16 v[96:97], v183 offset:28672
	ds_read_b64_tr_b16 v[98:99], v183 offset:29184
	v_add_f32_e32 v48, v102, v48
	v_add_f32_e32 v48, v103, v48
	v_add_f32_e32 v48, v104, v48
	v_add_f32_e32 v136, v105, v48
	s_waitcnt lgkmcnt(10)
	v_mfma_f32_32x32x16_bf16 v[48:63], v[112:115], v[140:143], v[32:47]
	v_cvt_pk_bf16_f32 v158, v100, v101
	v_cvt_pk_bf16_f32 v159, v102, v103
	ds_read_b64_tr_b16 v[100:101], v183 offset:25600
	ds_read_b64_tr_b16 v[102:103], v183 offset:26112
	s_waitcnt lgkmcnt(11)
	v_mfma_f32_32x32x16_bf16 v[64:79], v[116:119], v[132:135], v[64:79]
	v_add_f32_e32 v112, v106, v136
	v_add_f32_e32 v112, v107, v112
	v_add_f32_e32 v112, v108, v112
	v_add_f32_e32 v112, v109, v112
	v_cvt_pk_bf16_f32 v152, v104, v105
	v_cvt_pk_bf16_f32 v153, v106, v107
	ds_read_b64_tr_b16 v[104:105], v183 offset:29696
	ds_read_b64_tr_b16 v[106:107], v183 offset:30208
	s_waitcnt lgkmcnt(12)
	v_mfma_f32_32x32x16_bf16 v[48:63], v[120:123], v[132:135], v[48:63]
	v_add_f32_e32 v112, v110, v112
	v_add_f32_e32 v112, v111, v112
	v_add_f32_e32 v112, v80, v112
	v_add_f32_e32 v112, v81, v112
	v_cvt_pk_bf16_f32 v154, v108, v109
	v_cvt_pk_bf16_f32 v155, v110, v111
	ds_read_b64_tr_b16 v[108:109], v183 offset:26624
	ds_read_b64_tr_b16 v[110:111], v183 offset:27136
	s_waitcnt lgkmcnt(13)
	v_mfma_f32_32x32x16_bf16 v[64:79], v[124:127], v[128:131], v[64:79]
	v_add_f32_e32 v112, v82, v112
	v_add_f32_e32 v112, v83, v112
	v_add_f32_e32 v112, v84, v112
	v_add_f32_e32 v112, v85, v112
	v_cvt_pk_bf16_f32 v144, v80, v81
	v_cvt_pk_bf16_f32 v145, v82, v83
	ds_read_b64_tr_b16 v[212:213], v183 offset:30720
	ds_read_b64_tr_b16 v[214:215], v183 offset:31232
	s_waitcnt lgkmcnt(14)
	v_mfma_f32_32x32x16_bf16 v[48:63], v[160:163], v[128:131], v[48:63]
	v_add_f32_e32 v80, v86, v112
	v_add_f32_e32 v80, v87, v80
	v_add_f32_e32 v80, v88, v80
	v_add_f32_e32 v80, v89, v80
	v_cvt_pk_bf16_f32 v146, v84, v85
	v_cvt_pk_bf16_f32 v147, v86, v87
	ds_read_b64_tr_b16 v[84:85], v183 offset:27648
	ds_read_b64_tr_b16 v[86:87], v183 offset:28160
	s_waitcnt lgkmcnt(14)
	v_mfma_f32_32x32x16_bf16 v[64:79], v[164:167], v[148:151], v[64:79]
	v_add_f32_e32 v80, v90, v80
	v_add_f32_e32 v80, v91, v80
	v_add_f32_e32 v80, v92, v80
	v_add_f32_e32 v80, v93, v80
	v_cvt_pk_bf16_f32 v136, v88, v89
	v_cvt_pk_bf16_f32 v137, v90, v91
	ds_read_b64_tr_b16 v[88:89], v183 offset:31744
	ds_read_b64_tr_b16 v[90:91], v183 offset:32256
	v_mfma_f32_32x32x16_bf16 v[48:63], v[168:171], v[148:151], v[48:63]
	v_add_f32_e32 v80, v94, v80
	v_add_f32_e32 v80, v95, v80
	v_add_f32_e32 v183, 0, v80
	v_cvt_pk_bf16_f32 v138, v92, v93
	v_cvt_pk_bf16_f32 v139, v94, v95
	v_lshl_add_u64 v[80:81], v[176:177], 0, s[42:43]
	s_add_i32 s16, s5, s76
	s_mov_b32 s18, m0
	s_mov_b32 m0, s16
	s_nop 0
	global_load_lds_dwordx4 v[80:81], off
	s_mov_b32 m0, s18
	v_lshl_add_u64 v[178:179], v[178:179], 0, s[24:25]
	s_add_i32 s16, s10, s57
	s_mov_b32 s18, m0
	s_mov_b32 m0, s16
	s_nop 0
	global_load_lds_dwordx4 v[178:179], off
	s_mov_b32 m0, s18
	s_waitcnt lgkmcnt(14)
	v_mfma_f32_32x32x16_bf16 v[0:15], v[156:159], v[184:187], v[0:15]
	v_exp_f32_e32 v64, v64
	v_exp_f32_e32 v65, v65
	v_exp_f32_e32 v66, v66
	v_exp_f32_e32 v67, v67
	s_waitcnt lgkmcnt(12)
	v_mfma_f32_32x32x16_bf16 v[16:31], v[156:159], v[96:99], v[16:31]
	v_exp_f32_e32 v68, v68
	v_exp_f32_e32 v69, v69
	v_exp_f32_e32 v70, v70
	v_exp_f32_e32 v71, v71
	v_add_u32_e32 v92, s10, v199
	ds_read_b128 v[80:83], v92
	ds_read_b128 v[168:171], v92 offset:512
	s_waitcnt lgkmcnt(12)
	v_mfma_f32_32x32x16_bf16 v[0:15], v[152:155], v[100:103], v[0:15]
	v_exp_f32_e32 v72, v72
	v_exp_f32_e32 v73, v73
	v_exp_f32_e32 v74, v74
	v_exp_f32_e32 v75, v75
	ds_read_b128 v[164:167], v92 offset:2048
	ds_read_b128 v[160:163], v92 offset:2560
	s_waitcnt lgkmcnt(12)
	v_mfma_f32_32x32x16_bf16 v[16:31], v[152:155], v[104:107], v[16:31]
	v_exp_f32_e32 v76, v76
	v_exp_f32_e32 v77, v77
	v_exp_f32_e32 v78, v78
	v_exp_f32_e32 v79, v79
	ds_read_b128 v[124:127], v92 offset:4096
	ds_read_b128 v[120:123], v92 offset:4608
	s_waitcnt lgkmcnt(12)
	v_mfma_f32_32x32x16_bf16 v[0:15], v[144:147], v[108:111], v[0:15]
	v_exp_f32_e32 v48, v48
	v_exp_f32_e32 v49, v49
	v_exp_f32_e32 v50, v50
	v_exp_f32_e32 v51, v51
	ds_read_b128 v[116:119], v92 offset:6144
	ds_read_b128 v[112:115], v92 offset:6656
	s_waitcnt lgkmcnt(12)
	v_mfma_f32_32x32x16_bf16 v[16:31], v[144:147], v[212:215], v[16:31]
	v_exp_f32_e32 v52, v52
	v_exp_f32_e32 v53, v53
	v_exp_f32_e32 v54, v54
	v_exp_f32_e32 v55, v55
	s_waitcnt lgkmcnt(10)
	v_mfma_f32_32x32x16_bf16 v[0:15], v[136:139], v[84:87], v[0:15]
	v_exp_f32_e32 v56, v56
	v_exp_f32_e32 v57, v57
	v_exp_f32_e32 v58, v58
	v_exp_f32_e32 v59, v59
	s_waitcnt lgkmcnt(8)
	v_mfma_f32_32x32x16_bf16 v[16:31], v[136:139], v[88:91], v[16:31]
	v_exp_f32_e32 v60, v60
	v_exp_f32_e32 v61, v61
	v_exp_f32_e32 v62, v62
	v_exp_f32_e32 v63, v63
	s_add_i32 s16, s10, 0x2000
	s_waitcnt vmcnt(2) lgkmcnt(0)
	s_barrier
	s_cmpk_lg_i32 s10, 0x4000
	v_add_f32_e32 v84, v181, v182
	s_mov_b32 s19, s5
	s_cselect_b32 s5, s16, 0
	s_add_i32 s4, s4, 2
	v_lshl_add_u64 v[176:177], v[176:177], 0, s[24:25]
	s_mov_b32 s18, s10
	v_add_f32_e32 v181, v84, v183
	s_cmp_gt_u32 s4, 24
	s_cbranch_scc0 .LBB0_447
	s_and_b32 s4, s77, 0x3fffffc0
	s_lshl_b32 s4, s4, 2
	s_add_i32 s10, s4, 0
	ds_read_b64_tr_b16 v[176:177], v220 offset:40960
	ds_read_b64_tr_b16 v[178:179], v220 offset:41472
	v_add_f32_e32 v84, v64, v65
	v_add_f32_e32 v84, v66, v84
	v_add_f32_e32 v84, v67, v84
	v_add_f32_e32 v84, v68, v84
	v_add_f32_e32 v84, v69, v84
	v_cvt_pk_bf16_f32 v156, v64, v65
	v_cvt_pk_bf16_f32 v157, v66, v67
	s_waitcnt lgkmcnt(9)
	v_mfma_f32_32x32x16_bf16 v[96:111], v[80:83], v[140:143], v[32:47]
	ds_read_b64_tr_b16 v[64:65], v220 offset:45056
	ds_read_b64_tr_b16 v[66:67], v220 offset:45568
	v_add_f32_e32 v80, v70, v84
	v_add_f32_e32 v80, v71, v80
	v_add_f32_e32 v80, v72, v80
	v_add_f32_e32 v136, v73, v80
	v_cvt_pk_bf16_f32 v158, v68, v69
	v_cvt_pk_bf16_f32 v159, v70, v71
	s_waitcnt lgkmcnt(10)
	v_mfma_f32_32x32x16_bf16 v[80:95], v[168:171], v[140:143], v[32:47]
	ds_read_b64_tr_b16 v[68:69], v220 offset:41984
	ds_read_b64_tr_b16 v[70:71], v220 offset:42496
	v_add_f32_e32 v136, v74, v136
	v_add_f32_e32 v136, v75, v136
	v_add_f32_e32 v136, v76, v136
	v_add_f32_e32 v136, v77, v136
	v_cvt_pk_bf16_f32 v152, v72, v73
	v_cvt_pk_bf16_f32 v153, v74, v75
	s_waitcnt lgkmcnt(11)
	v_mfma_f32_32x32x16_bf16 v[96:111], v[164:167], v[132:135], v[96:111]
	ds_read_b64_tr_b16 v[72:73], v220 offset:46080
	ds_read_b64_tr_b16 v[74:75], v220 offset:46592
	v_add_f32_e32 v136, v78, v136
	v_add_f32_e32 v136, v79, v136
	v_add_f32_e32 v136, v48, v136
	v_add_f32_e32 v136, v49, v136
	v_cvt_pk_bf16_f32 v154, v76, v77
	v_cvt_pk_bf16_f32 v155, v78, v79
	s_waitcnt lgkmcnt(12)
	v_mfma_f32_32x32x16_bf16 v[80:95], v[160:163], v[132:135], v[80:95]
	ds_read_b64_tr_b16 v[76:77], v220 offset:43008
	ds_read_b64_tr_b16 v[78:79], v220 offset:43520
	v_add_f32_e32 v136, v50, v136
	v_add_f32_e32 v136, v51, v136
	v_add_f32_e32 v136, v52, v136
	v_add_f32_e32 v136, v53, v136
	v_cvt_pk_bf16_f32 v144, v48, v49
	v_cvt_pk_bf16_f32 v145, v50, v51
	s_waitcnt lgkmcnt(13)
	v_mfma_f32_32x32x16_bf16 v[96:111], v[124:127], v[128:131], v[96:111]
	ds_read_b64_tr_b16 v[48:49], v220 offset:47104
	ds_read_b64_tr_b16 v[50:51], v220 offset:47616
	v_add_f32_e32 v124, v54, v136
	v_add_f32_e32 v124, v55, v124
	v_add_f32_e32 v124, v56, v124
	v_add_f32_e32 v124, v57, v124
	v_cvt_pk_bf16_f32 v146, v52, v53
	v_cvt_pk_bf16_f32 v147, v54, v55
	s_waitcnt lgkmcnt(14)
	v_mfma_f32_32x32x16_bf16 v[80:95], v[120:123], v[128:131], v[80:95]
	ds_read_b64_tr_b16 v[52:53], v220 offset:44032
	ds_read_b64_tr_b16 v[54:55], v220 offset:44544
	v_add_f32_e32 v120, v58, v124
	v_add_f32_e32 v120, v59, v120
	v_add_f32_e32 v120, v60, v120
	v_add_f32_e32 v120, v61, v120
	v_cvt_pk_bf16_f32 v136, v56, v57
	v_cvt_pk_bf16_f32 v137, v58, v59
	s_waitcnt lgkmcnt(14)
	v_mfma_f32_32x32x16_bf16 v[96:111], v[116:119], v[148:151], v[96:111]
	ds_read_b64_tr_b16 v[56:57], v220 offset:48128
	ds_read_b64_tr_b16 v[58:59], v220 offset:48640
	v_add_f32_e32 v116, v62, v120
	v_add_f32_e32 v116, v63, v116
	v_add_f32_e32 v116, 0, v116
	v_cvt_pk_bf16_f32 v138, v60, v61
	v_cvt_pk_bf16_f32 v139, v62, v63
	v_mfma_f32_32x32x16_bf16 v[80:95], v[112:115], v[148:151], v[80:95]
	s_cmp_lg_u32 0, -1
	s_cselect_b32 s5, 0, 0
	v_lshl_add_u64 v[60:61], v[174:175], 0, s[44:45]
	s_mov_b32 s4, m0
	s_mov_b32 m0, s76
	s_nop 0
	global_load_lds_dwordx4 v[60:61], off
	s_mov_b32 m0, s4
	s_add_i32 s5, s5, s59
	v_lshl_add_u64 v[60:61], v[172:173], 0, s[46:47]
	s_add_i32 s4, s5, 0x8000
	s_mov_b32 s16, m0
	s_mov_b32 m0, s4
	s_nop 0
	global_load_lds_dwordx4 v[60:61], off
	s_mov_b32 m0, s16
	v_add_f32_e32 v181, v181, v116
	s_waitcnt lgkmcnt(14)
	v_mfma_f32_32x32x16_bf16 v[0:15], v[156:159], v[176:179], v[0:15]
	v_exp_f32_e32 v96, v96
	v_exp_f32_e32 v97, v97
	v_exp_f32_e32 v98, v98
	v_exp_f32_e32 v99, v99
	s_waitcnt lgkmcnt(12)
	v_mfma_f32_32x32x16_bf16 v[16:31], v[156:159], v[64:67], v[16:31]
	v_exp_f32_e32 v100, v100
	v_exp_f32_e32 v101, v101
	v_exp_f32_e32 v102, v102
	v_exp_f32_e32 v103, v103
	ds_read_b128 v[60:63], v199 offset:8192
	ds_read_b128 v[64:67], v199 offset:8704
	s_waitcnt lgkmcnt(12)
	v_mfma_f32_32x32x16_bf16 v[0:15], v[152:155], v[68:71], v[0:15]
	v_exp_f32_e32 v104, v104
	v_exp_f32_e32 v105, v105
	v_exp_f32_e32 v106, v106
	v_exp_f32_e32 v107, v107
	ds_read_b128 v[68:71], v199 offset:10240
	ds_read_b128 v[160:163], v199 offset:10752
	s_waitcnt lgkmcnt(12)
	v_mfma_f32_32x32x16_bf16 v[16:31], v[152:155], v[72:75], v[16:31]
	v_exp_f32_e32 v108, v108
	v_exp_f32_e32 v109, v109
	v_exp_f32_e32 v110, v110
	v_exp_f32_e32 v111, v111
	ds_read_b128 v[72:75], v199 offset:12288
	ds_read_b128 v[164:167], v199 offset:12800
	s_waitcnt lgkmcnt(12)
	v_mfma_f32_32x32x16_bf16 v[0:15], v[144:147], v[76:79], v[0:15]
	v_exp_f32_e32 v80, v80
	v_exp_f32_e32 v81, v81
	v_exp_f32_e32 v82, v82
	v_exp_f32_e32 v83, v83
	ds_read_b128 v[76:79], v199 offset:14336
	ds_read_b128 v[168:171], v199 offset:14848
	s_waitcnt lgkmcnt(12)
	v_mfma_f32_32x32x16_bf16 v[16:31], v[144:147], v[48:51], v[16:31]
	v_exp_f32_e32 v84, v84
	v_exp_f32_e32 v85, v85
	v_exp_f32_e32 v86, v86
	v_exp_f32_e32 v87, v87
	s_waitcnt lgkmcnt(10)
	v_mfma_f32_32x32x16_bf16 v[0:15], v[136:139], v[52:55], v[0:15]
	v_exp_f32_e32 v88, v88
	v_exp_f32_e32 v89, v89
	v_exp_f32_e32 v90, v90
	v_exp_f32_e32 v91, v91
	s_waitcnt lgkmcnt(8)
	v_mfma_f32_32x32x16_bf16 v[16:31], v[136:139], v[56:59], v[16:31]
	v_exp_f32_e32 v92, v92
	v_exp_f32_e32 v93, v93
	v_exp_f32_e32 v94, v94
	v_exp_f32_e32 v95, v95
	s_waitcnt vmcnt(2) lgkmcnt(0)
	s_barrier
	ds_read_b64_tr_b16 v[176:177], v220 offset:24576
	ds_read_b64_tr_b16 v[178:179], v220 offset:25088
	v_add_f32_e32 v48, v96, v97
	v_add_f32_e32 v48, v98, v48
	v_add_f32_e32 v48, v99, v48
	v_add_f32_e32 v48, v100, v48
	v_add_f32_e32 v48, v101, v48
	v_cvt_pk_bf16_f32 v156, v96, v97
	v_cvt_pk_bf16_f32 v157, v98, v99
	s_waitcnt lgkmcnt(9)
	v_mfma_f32_32x32x16_bf16 v[112:127], v[60:63], v[140:143], v[32:47]
	ds_read_b64_tr_b16 v[96:97], v220 offset:28672
	ds_read_b64_tr_b16 v[98:99], v220 offset:29184
	v_add_f32_e32 v48, v102, v48
	v_add_f32_e32 v48, v103, v48
	v_add_f32_e32 v48, v104, v48
	v_add_f32_e32 v136, v105, v48
	s_waitcnt lgkmcnt(10)
	v_mfma_f32_32x32x16_bf16 v[48:63], v[64:67], v[140:143], v[32:47]
	v_cvt_pk_bf16_f32 v158, v100, v101
	v_cvt_pk_bf16_f32 v159, v102, v103
	ds_read_b64_tr_b16 v[64:65], v220 offset:25600
	ds_read_b64_tr_b16 v[66:67], v220 offset:26112
	v_add_f32_e32 v100, v106, v136
	v_add_f32_e32 v100, v107, v100
	v_add_f32_e32 v100, v108, v100
	v_add_f32_e32 v100, v109, v100
	v_cvt_pk_bf16_f32 v152, v104, v105
	v_cvt_pk_bf16_f32 v153, v106, v107
	s_waitcnt lgkmcnt(11)
	v_mfma_f32_32x32x16_bf16 v[112:127], v[68:71], v[132:135], v[112:127]
	ds_read_b64_tr_b16 v[68:69], v220 offset:29696
	ds_read_b64_tr_b16 v[70:71], v220 offset:30208
	s_waitcnt lgkmcnt(12)
	v_mfma_f32_32x32x16_bf16 v[48:63], v[160:163], v[132:135], v[48:63]
	v_add_f32_e32 v100, v110, v100
	v_add_f32_e32 v100, v111, v100
	v_add_f32_e32 v100, v80, v100
	v_add_f32_e32 v104, v81, v100
	v_cvt_pk_bf16_f32 v154, v108, v109
	v_cvt_pk_bf16_f32 v155, v110, v111
	ds_read_b64_tr_b16 v[100:101], v220 offset:26624
	ds_read_b64_tr_b16 v[102:103], v220 offset:27136
	v_add_f32_e32 v104, v82, v104
	v_add_f32_e32 v104, v83, v104
	v_add_f32_e32 v104, v84, v104
	v_add_f32_e32 v104, v85, v104
	v_cvt_pk_bf16_f32 v144, v80, v81
	v_cvt_pk_bf16_f32 v145, v82, v83
	s_waitcnt lgkmcnt(13)
	v_mfma_f32_32x32x16_bf16 v[112:127], v[72:75], v[128:131], v[112:127]
	ds_read_b64_tr_b16 v[72:73], v220 offset:30720
	ds_read_b64_tr_b16 v[74:75], v220 offset:31232
	s_waitcnt lgkmcnt(14)
	v_mfma_f32_32x32x16_bf16 v[48:63], v[164:167], v[128:131], v[48:63]
	v_add_f32_e32 v80, v86, v104
	v_add_f32_e32 v80, v87, v80
	v_add_f32_e32 v80, v88, v80
	v_add_f32_e32 v104, v89, v80
	v_cvt_pk_bf16_f32 v146, v84, v85
	v_cvt_pk_bf16_f32 v147, v86, v87
	ds_read_b64_tr_b16 v[80:81], v220 offset:27648
	ds_read_b64_tr_b16 v[82:83], v220 offset:28160
	v_add_f32_e32 v84, v90, v104
	v_add_f32_e32 v84, v91, v84
	v_add_f32_e32 v84, v92, v84
	v_add_f32_e32 v84, v93, v84
	v_cvt_pk_bf16_f32 v136, v88, v89
	v_cvt_pk_bf16_f32 v137, v90, v91
	s_waitcnt lgkmcnt(14)
	v_mfma_f32_32x32x16_bf16 v[112:127], v[76:79], v[148:151], v[112:127]
	ds_read_b64_tr_b16 v[76:77], v220 offset:31744
	ds_read_b64_tr_b16 v[78:79], v220 offset:32256
	v_mfma_f32_32x32x16_bf16 v[48:63], v[168:171], v[148:151], v[48:63]
	v_add_f32_e32 v84, v94, v84
	v_add_f32_e32 v84, v95, v84
	v_add_f32_e32 v84, 0, v84
	v_cvt_pk_bf16_f32 v138, v92, v93
	v_cvt_pk_bf16_f32 v139, v94, v95
	s_nop 0
	v_add_f32_e32 v181, v181, v84
	v_lshl_add_u64 v[84:85], v[174:175], 0, s[48:49]
	s_add_i32 s16, s5, 0x2000
	s_mov_b32 s18, m0
	s_mov_b32 m0, s16
	s_nop 0
	global_load_lds_dwordx4 v[84:85], off
	s_mov_b32 m0, s18
	v_lshl_add_u64 v[84:85], v[172:173], 0, s[50:51]
	s_add_i32 s5, s5, 0xa000
	s_mov_b32 s16, m0
	s_mov_b32 m0, s5
	s_nop 0
	global_load_lds_dwordx4 v[84:85], off
	s_mov_b32 m0, s16
	s_waitcnt lgkmcnt(14)
	v_mfma_f32_32x32x16_bf16 v[0:15], v[156:159], v[176:179], v[0:15]
	v_exp_f32_e32 v112, v112
	v_exp_f32_e32 v113, v113
	v_exp_f32_e32 v114, v114
	v_exp_f32_e32 v115, v115
	s_waitcnt lgkmcnt(12)
	v_mfma_f32_32x32x16_bf16 v[16:31], v[156:159], v[96:99], v[16:31]
	v_exp_f32_e32 v116, v116
	v_exp_f32_e32 v117, v117
	v_exp_f32_e32 v118, v118
	v_exp_f32_e32 v119, v119
	ds_read_b128 v[84:87], v199 offset:16384
	ds_read_b128 v[88:91], v199 offset:16896
	s_waitcnt lgkmcnt(12)
	v_mfma_f32_32x32x16_bf16 v[0:15], v[152:155], v[64:67], v[0:15]
	v_exp_f32_e32 v120, v120
	v_exp_f32_e32 v121, v121
	v_exp_f32_e32 v122, v122
	v_exp_f32_e32 v123, v123
	ds_read_b128 v[92:95], v199 offset:18432
	ds_read_b128 v[160:163], v199 offset:18944
	s_waitcnt lgkmcnt(12)
	v_mfma_f32_32x32x16_bf16 v[16:31], v[152:155], v[68:71], v[16:31]
	v_exp_f32_e32 v124, v124
	v_exp_f32_e32 v125, v125
	v_exp_f32_e32 v126, v126
	v_exp_f32_e32 v127, v127
	ds_read_b128 v[164:167], v199 offset:20480
	ds_read_b128 v[168:171], v199 offset:20992
	s_waitcnt lgkmcnt(12)
	v_mfma_f32_32x32x16_bf16 v[0:15], v[144:147], v[100:103], v[0:15]
	v_exp_f32_e32 v48, v48
	v_exp_f32_e32 v49, v49
	v_exp_f32_e32 v50, v50
	v_exp_f32_e32 v51, v51
	ds_read_b128 v[174:177], v199 offset:22528
	ds_read_b128 v[182:185], v199 offset:23040
	s_waitcnt lgkmcnt(12)
	v_mfma_f32_32x32x16_bf16 v[16:31], v[144:147], v[72:75], v[16:31]
	v_exp_f32_e32 v52, v52
	v_exp_f32_e32 v53, v53
	v_exp_f32_e32 v54, v54
	v_exp_f32_e32 v55, v55
	s_waitcnt lgkmcnt(10)
	v_mfma_f32_32x32x16_bf16 v[0:15], v[136:139], v[80:83], v[0:15]
	v_exp_f32_e32 v56, v56
	v_exp_f32_e32 v57, v57
	v_exp_f32_e32 v58, v58
	v_exp_f32_e32 v59, v59
	s_waitcnt lgkmcnt(8)
	v_mfma_f32_32x32x16_bf16 v[16:31], v[136:139], v[76:79], v[16:31]
	v_exp_f32_e32 v60, v60
	v_exp_f32_e32 v61, v61
	v_exp_f32_e32 v62, v62
	v_exp_f32_e32 v63, v63
	s_waitcnt vmcnt(2) lgkmcnt(0)
	s_barrier
	ds_read_b64_tr_b16 v[80:81], v220 offset:32768
	ds_read_b64_tr_b16 v[82:83], v220 offset:33280
	v_add_f32_e32 v64, v112, v113
	v_add_f32_e32 v64, v114, v64
	v_add_f32_e32 v64, v115, v64
	v_add_f32_e32 v64, v116, v64
	v_add_f32_e32 v64, v117, v64
	v_cvt_pk_bf16_f32 v156, v112, v113
	v_cvt_pk_bf16_f32 v157, v114, v115
	s_waitcnt lgkmcnt(9)
	v_mfma_f32_32x32x16_bf16 v[96:111], v[84:87], v[140:143], v[32:47]
	ds_read_b64_tr_b16 v[84:85], v220 offset:36864
	ds_read_b64_tr_b16 v[86:87], v220 offset:37376
	v_add_f32_e32 v64, v118, v64
	v_add_f32_e32 v64, v119, v64
	v_add_f32_e32 v64, v120, v64
	v_add_f32_e32 v112, v121, v64
	v_cvt_pk_bf16_f32 v158, v116, v117
	v_cvt_pk_bf16_f32 v159, v118, v119
	s_waitcnt lgkmcnt(10)
	v_mfma_f32_32x32x16_bf16 v[64:79], v[88:91], v[140:143], v[32:47]
	ds_read_b64_tr_b16 v[88:89], v220 offset:33792
	ds_read_b64_tr_b16 v[90:91], v220 offset:34304
	v_add_f32_e32 v112, v122, v112
	v_add_f32_e32 v112, v123, v112
	v_add_f32_e32 v112, v124, v112
	v_add_f32_e32 v112, v125, v112
	v_cvt_pk_bf16_f32 v152, v120, v121
	v_cvt_pk_bf16_f32 v153, v122, v123
	s_waitcnt lgkmcnt(11)
	v_mfma_f32_32x32x16_bf16 v[96:111], v[92:95], v[132:135], v[96:111]
	ds_read_b64_tr_b16 v[92:93], v220 offset:37888
	ds_read_b64_tr_b16 v[94:95], v220 offset:38400
	v_add_f32_e32 v112, v126, v112
	v_add_f32_e32 v112, v127, v112
	v_add_f32_e32 v112, v48, v112
	v_add_f32_e32 v116, v49, v112
	v_cvt_pk_bf16_f32 v154, v124, v125
	v_cvt_pk_bf16_f32 v155, v126, v127
	s_waitcnt lgkmcnt(12)
	v_mfma_f32_32x32x16_bf16 v[64:79], v[160:163], v[132:135], v[64:79]
	ds_read_b64_tr_b16 v[112:113], v220 offset:34816
	ds_read_b64_tr_b16 v[114:115], v220 offset:35328
	v_add_f32_e32 v116, v50, v116
	v_add_f32_e32 v116, v51, v116
	v_add_f32_e32 v116, v52, v116
	v_add_f32_e32 v116, v53, v116
	v_cvt_pk_bf16_f32 v144, v48, v49
	v_cvt_pk_bf16_f32 v145, v50, v51
	s_waitcnt lgkmcnt(13)
	v_mfma_f32_32x32x16_bf16 v[96:111], v[164:167], v[128:131], v[96:111]
	ds_read_b64_tr_b16 v[48:49], v220 offset:38912
	ds_read_b64_tr_b16 v[50:51], v220 offset:39424
	v_add_f32_e32 v116, v54, v116
	v_add_f32_e32 v116, v55, v116
	v_add_f32_e32 v116, v56, v116
	v_add_f32_e32 v116, v57, v116
	v_cvt_pk_bf16_f32 v146, v52, v53
	v_cvt_pk_bf16_f32 v147, v54, v55
	s_waitcnt lgkmcnt(14)
	v_mfma_f32_32x32x16_bf16 v[64:79], v[168:171], v[128:131], v[64:79]
	ds_read_b64_tr_b16 v[52:53], v220 offset:35840
	ds_read_b64_tr_b16 v[54:55], v220 offset:36352
	v_add_f32_e32 v116, v58, v116
	v_add_f32_e32 v116, v59, v116
	v_add_f32_e32 v116, v60, v116
	v_add_f32_e32 v116, v61, v116
	v_cvt_pk_bf16_f32 v136, v56, v57
	v_cvt_pk_bf16_f32 v137, v58, v59
	s_waitcnt lgkmcnt(14)
	v_mfma_f32_32x32x16_bf16 v[96:111], v[174:177], v[148:151], v[96:111]
	ds_read_b64_tr_b16 v[56:57], v220 offset:39936
	ds_read_b64_tr_b16 v[58:59], v220 offset:40448
	v_add_f32_e32 v116, v62, v116
	v_add_f32_e32 v116, v63, v116
	v_add_f32_e32 v116, 0, v116
	v_cvt_pk_bf16_f32 v138, v60, v61
	v_cvt_pk_bf16_f32 v139, v62, v63
	v_mfma_f32_32x32x16_bf16 v[64:79], v[182:185], v[148:151], v[64:79]
	v_lshl_add_u64 v[60:61], v[172:173], 0, s[44:45]
	s_mov_b32 s5, m0
	s_mov_b32 m0, s57
	s_nop 0
	global_load_lds_dwordx4 v[60:61], off
	s_mov_b32 m0, s5
	v_add_f32_e32 v178, v181, v116
	s_waitcnt lgkmcnt(14)
	v_mfma_f32_32x32x16_bf16 v[0:15], v[156:159], v[80:83], v[0:15]
	v_exp_f32_e32 v96, v96
	v_exp_f32_e32 v97, v97
	v_exp_f32_e32 v98, v98
	v_exp_f32_e32 v99, v99
	s_waitcnt lgkmcnt(12)
	v_mfma_f32_32x32x16_bf16 v[16:31], v[156:159], v[84:87], v[16:31]
	v_exp_f32_e32 v100, v100
	v_exp_f32_e32 v101, v101
	v_exp_f32_e32 v102, v102
	v_exp_f32_e32 v103, v103
	ds_read_b128 v[60:63], v199
	ds_read_b128 v[116:119], v199 offset:512
	s_waitcnt lgkmcnt(12)
	v_mfma_f32_32x32x16_bf16 v[0:15], v[152:155], v[88:91], v[0:15]
	v_exp_f32_e32 v104, v104
	v_exp_f32_e32 v105, v105
	v_exp_f32_e32 v106, v106
	v_exp_f32_e32 v107, v107
	ds_read_b128 v[120:123], v199 offset:2048
	ds_read_b128 v[124:127], v199 offset:2560
	s_waitcnt lgkmcnt(12)
	v_mfma_f32_32x32x16_bf16 v[16:31], v[152:155], v[92:95], v[16:31]
	v_exp_f32_e32 v108, v108
	v_exp_f32_e32 v109, v109
	v_exp_f32_e32 v110, v110
	v_exp_f32_e32 v111, v111
	ds_read_b128 v[160:163], v199 offset:4096
	ds_read_b128 v[164:167], v199 offset:4608
	s_waitcnt lgkmcnt(12)
	v_mfma_f32_32x32x16_bf16 v[0:15], v[144:147], v[112:115], v[0:15]
	v_exp_f32_e32 v64, v64
	v_exp_f32_e32 v65, v65
	v_exp_f32_e32 v66, v66
	v_exp_f32_e32 v67, v67
	ds_read_b128 v[112:115], v199 offset:6144
	ds_read_b128 v[168:171], v199 offset:6656
	s_waitcnt lgkmcnt(12)
	v_mfma_f32_32x32x16_bf16 v[16:31], v[144:147], v[48:51], v[16:31]
	v_exp_f32_e32 v68, v68
	v_exp_f32_e32 v69, v69
	v_exp_f32_e32 v70, v70
	v_exp_f32_e32 v71, v71
	s_waitcnt lgkmcnt(10)
	v_mfma_f32_32x32x16_bf16 v[0:15], v[136:139], v[52:55], v[0:15]
	v_exp_f32_e32 v72, v72
	v_exp_f32_e32 v73, v73
	v_exp_f32_e32 v74, v74
	v_exp_f32_e32 v75, v75
	s_waitcnt lgkmcnt(8)
	v_mfma_f32_32x32x16_bf16 v[16:31], v[136:139], v[56:59], v[16:31]
	v_exp_f32_e32 v76, v76
	v_exp_f32_e32 v77, v77
	v_exp_f32_e32 v78, v78
	v_exp_f32_e32 v79, v79
	s_waitcnt vmcnt(1) lgkmcnt(0)
	s_barrier
	ds_read_b64_tr_b16 v[174:175], v220 offset:40960
	ds_read_b64_tr_b16 v[176:177], v220 offset:41472
	v_add_f32_e32 v48, v96, v97
	v_add_f32_e32 v48, v98, v48
	v_add_f32_e32 v48, v99, v48
	v_add_f32_e32 v48, v100, v48
	v_add_f32_e32 v48, v101, v48
	v_cvt_pk_bf16_f32 v156, v96, v97
	v_cvt_pk_bf16_f32 v157, v98, v99
	s_waitcnt lgkmcnt(9)
	v_mfma_f32_32x32x16_bf16 v[80:95], v[60:63], v[140:143], v[32:47]
	ds_read_b64_tr_b16 v[182:183], v220 offset:45056
	ds_read_b64_tr_b16 v[184:185], v220 offset:45568
	v_add_f32_e32 v48, v102, v48
	v_add_f32_e32 v48, v103, v48
	v_add_f32_e32 v48, v104, v48
	v_add_f32_e32 v96, v105, v48
	s_waitcnt lgkmcnt(10)
	v_mfma_f32_32x32x16_bf16 v[48:63], v[116:119], v[140:143], v[32:47]
	v_cvt_pk_bf16_f32 v158, v100, v101
	v_cvt_pk_bf16_f32 v159, v102, v103
	ds_read_b64_tr_b16 v[98:99], v220 offset:41984
	ds_read_b64_tr_b16 v[100:101], v220 offset:42496
	v_add_f32_e32 v96, v106, v96
	v_add_f32_e32 v96, v107, v96
	v_add_f32_e32 v96, v108, v96
	v_add_f32_e32 v96, v109, v96
	v_cvt_pk_bf16_f32 v152, v104, v105
	v_cvt_pk_bf16_f32 v153, v106, v107
	s_waitcnt lgkmcnt(11)
	v_mfma_f32_32x32x16_bf16 v[80:95], v[120:123], v[132:135], v[80:95]
	ds_read_b64_tr_b16 v[102:103], v220 offset:46080
	ds_read_b64_tr_b16 v[104:105], v220 offset:46592
	s_waitcnt lgkmcnt(12)
	v_mfma_f32_32x32x16_bf16 v[48:63], v[124:127], v[132:135], v[48:63]
	v_add_f32_e32 v96, v110, v96
	v_add_f32_e32 v96, v111, v96
	v_add_f32_e32 v96, v64, v96
	v_add_f32_e32 v96, v65, v96
	v_cvt_pk_bf16_f32 v154, v108, v109
	v_cvt_pk_bf16_f32 v155, v110, v111
	ds_read_b64_tr_b16 v[106:107], v220 offset:43008
	ds_read_b64_tr_b16 v[108:109], v220 offset:43520
	v_add_f32_e32 v96, v66, v96
	v_add_f32_e32 v96, v67, v96
	v_add_f32_e32 v96, v68, v96
	v_add_f32_e32 v96, v69, v96
	v_cvt_pk_bf16_f32 v144, v64, v65
	v_cvt_pk_bf16_f32 v145, v66, v67
	s_waitcnt lgkmcnt(13)
	v_mfma_f32_32x32x16_bf16 v[80:95], v[160:163], v[128:131], v[80:95]
	ds_read_b64_tr_b16 v[64:65], v220 offset:47104
	ds_read_b64_tr_b16 v[66:67], v220 offset:47616
	s_waitcnt lgkmcnt(14)
	v_mfma_f32_32x32x16_bf16 v[48:63], v[164:167], v[128:131], v[48:63]
	v_add_f32_e32 v96, v70, v96
	v_add_f32_e32 v96, v71, v96
	v_add_f32_e32 v96, v72, v96
	v_add_f32_e32 v96, v73, v96
	v_cvt_pk_bf16_f32 v146, v68, v69
	v_cvt_pk_bf16_f32 v147, v70, v71
	ds_read_b64_tr_b16 v[68:69], v220 offset:44032
	ds_read_b64_tr_b16 v[70:71], v220 offset:44544
	v_add_f32_e32 v96, v74, v96
	v_add_f32_e32 v96, v75, v96
	v_add_f32_e32 v96, v76, v96
	v_add_f32_e32 v96, v77, v96
	v_cvt_pk_bf16_f32 v136, v72, v73
	v_cvt_pk_bf16_f32 v137, v74, v75
	s_waitcnt lgkmcnt(14)
	v_mfma_f32_32x32x16_bf16 v[80:95], v[112:115], v[148:151], v[80:95]
	ds_read_b64_tr_b16 v[72:73], v220 offset:48128
	ds_read_b64_tr_b16 v[74:75], v220 offset:48640
	v_mfma_f32_32x32x16_bf16 v[48:63], v[168:171], v[148:151], v[48:63]
	v_add_f32_e32 v96, v78, v96
	v_add_f32_e32 v96, v79, v96
	v_add_f32_e32 v96, 0, v96
	v_cvt_pk_bf16_f32 v138, v76, v77
	v_cvt_pk_bf16_f32 v139, v78, v79
	v_lshl_add_u64 v[76:77], v[172:173], 0, s[48:49]
	s_mov_b32 s5, m0
	s_mov_b32 m0, s4
	s_nop 0
	global_load_lds_dwordx4 v[76:77], off
	s_mov_b32 m0, s5
	v_add_f32_e32 v96, v178, v96
	s_waitcnt lgkmcnt(14)
	v_mfma_f32_32x32x16_bf16 v[0:15], v[156:159], v[174:177], v[0:15]
	v_exp_f32_e32 v80, v80
	v_exp_f32_e32 v81, v81
	v_exp_f32_e32 v82, v82
	v_exp_f32_e32 v83, v83
	s_waitcnt lgkmcnt(12)
	v_mfma_f32_32x32x16_bf16 v[16:31], v[156:159], v[182:185], v[16:31]
	v_exp_f32_e32 v84, v84
	v_exp_f32_e32 v85, v85
	v_exp_f32_e32 v86, v86
	v_exp_f32_e32 v87, v87
	ds_read_b128 v[110:113], v199 offset:8192
	ds_read_b128 v[114:117], v199 offset:8704
	s_waitcnt lgkmcnt(12)
	v_mfma_f32_32x32x16_bf16 v[0:15], v[152:155], v[98:101], v[0:15]
	v_exp_f32_e32 v88, v88
	v_exp_f32_e32 v89, v89
	v_exp_f32_e32 v90, v90
	v_exp_f32_e32 v91, v91
	ds_read_b128 v[98:101], v199 offset:10240
	ds_read_b128 v[118:121], v199 offset:10752
	s_waitcnt lgkmcnt(12)
	v_mfma_f32_32x32x16_bf16 v[16:31], v[152:155], v[102:105], v[16:31]
	v_exp_f32_e32 v92, v92
	v_exp_f32_e32 v93, v93
	v_exp_f32_e32 v94, v94
	v_exp_f32_e32 v95, v95
	ds_read_b128 v[102:105], v199 offset:12288
	ds_read_b128 v[122:125], v199 offset:12800
	s_waitcnt lgkmcnt(12)
	v_mfma_f32_32x32x16_bf16 v[0:15], v[144:147], v[106:109], v[0:15]
	v_exp_f32_e32 v48, v48
	v_exp_f32_e32 v49, v49
	v_exp_f32_e32 v50, v50
	v_exp_f32_e32 v51, v51
	ds_read_b128 v[106:109], v199 offset:14336
	ds_read_b128 v[160:163], v199 offset:14848
	s_waitcnt lgkmcnt(12)
	v_mfma_f32_32x32x16_bf16 v[16:31], v[144:147], v[64:67], v[16:31]
	v_exp_f32_e32 v52, v52
	v_exp_f32_e32 v53, v53
	v_exp_f32_e32 v54, v54
	v_exp_f32_e32 v55, v55
	s_waitcnt lgkmcnt(10)
	v_mfma_f32_32x32x16_bf16 v[0:15], v[136:139], v[68:71], v[0:15]
	v_exp_f32_e32 v56, v56
	v_exp_f32_e32 v57, v57
	v_exp_f32_e32 v58, v58
	v_exp_f32_e32 v59, v59
	s_waitcnt lgkmcnt(8)
	v_mfma_f32_32x32x16_bf16 v[16:31], v[136:139], v[72:75], v[16:31]
	v_exp_f32_e32 v60, v60
	v_exp_f32_e32 v61, v61
	v_exp_f32_e32 v62, v62
	v_exp_f32_e32 v63, v63
	s_waitcnt vmcnt(0) lgkmcnt(0)
	s_barrier
	ds_read_b64_tr_b16 v[164:165], v220 offset:24576
	ds_read_b64_tr_b16 v[166:167], v220 offset:25088
	v_add_f32_e32 v64, v80, v81
	v_add_f32_e32 v64, v82, v64
	v_add_f32_e32 v64, v83, v64
	v_add_f32_e32 v64, v84, v64
	v_add_f32_e32 v97, v85, v64
	v_cvt_pk_bf16_f32 v156, v80, v81
	v_cvt_pk_bf16_f32 v157, v82, v83
	s_waitcnt lgkmcnt(9)
	v_mfma_f32_32x32x16_bf16 v[64:79], v[110:113], v[140:143], v[32:47]
	ds_read_b64_tr_b16 v[80:81], v220 offset:28672
	ds_read_b64_tr_b16 v[82:83], v220 offset:29184
	s_waitcnt lgkmcnt(10)
	v_mfma_f32_32x32x16_bf16 v[32:47], v[114:117], v[140:143], v[32:47]
	v_add_f32_e32 v97, v86, v97
	v_add_f32_e32 v97, v87, v97
	v_add_f32_e32 v97, v88, v97
	v_add_f32_e32 v97, v89, v97
	v_cvt_pk_bf16_f32 v158, v84, v85
	v_cvt_pk_bf16_f32 v159, v86, v87
	ds_read_b64_tr_b16 v[84:85], v220 offset:25600
	ds_read_b64_tr_b16 v[86:87], v220 offset:26112
	v_add_f32_e32 v97, v90, v97
	v_add_f32_e32 v97, v91, v97
	v_add_f32_e32 v97, v92, v97
	v_add_f32_e32 v97, v93, v97
	v_cvt_pk_bf16_f32 v152, v88, v89
	v_cvt_pk_bf16_f32 v153, v90, v91
	s_waitcnt lgkmcnt(11)
	v_mfma_f32_32x32x16_bf16 v[64:79], v[98:101], v[132:135], v[64:79]
	ds_read_b64_tr_b16 v[88:89], v220 offset:29696
	ds_read_b64_tr_b16 v[90:91], v220 offset:30208
	s_waitcnt lgkmcnt(12)
	v_mfma_f32_32x32x16_bf16 v[32:47], v[118:121], v[132:135], v[32:47]
	v_add_f32_e32 v97, v94, v97
	v_add_f32_e32 v97, v95, v97
	v_add_f32_e32 v97, v48, v97
	v_add_f32_e32 v97, v49, v97
	v_cvt_pk_bf16_f32 v154, v92, v93
	v_cvt_pk_bf16_f32 v155, v94, v95
	ds_read_b64_tr_b16 v[92:93], v220 offset:26624
	ds_read_b64_tr_b16 v[94:95], v220 offset:27136
	v_add_f32_e32 v97, v50, v97
	v_add_f32_e32 v97, v51, v97
	v_add_f32_e32 v97, v52, v97
	v_add_f32_e32 v97, v53, v97
	v_cvt_pk_bf16_f32 v144, v48, v49
	v_cvt_pk_bf16_f32 v145, v50, v51
	s_waitcnt lgkmcnt(13)
	v_mfma_f32_32x32x16_bf16 v[64:79], v[102:105], v[128:131], v[64:79]
	ds_read_b64_tr_b16 v[48:49], v220 offset:30720
	ds_read_b64_tr_b16 v[50:51], v220 offset:31232
	s_waitcnt lgkmcnt(14)
	v_mfma_f32_32x32x16_bf16 v[32:47], v[122:125], v[128:131], v[32:47]
	v_add_f32_e32 v97, v54, v97
	v_add_f32_e32 v97, v55, v97
	v_add_f32_e32 v97, v56, v97
	v_add_f32_e32 v97, v57, v97
	v_cvt_pk_bf16_f32 v146, v52, v53
	v_cvt_pk_bf16_f32 v147, v54, v55
	ds_read_b64_tr_b16 v[52:53], v220 offset:27648
	ds_read_b64_tr_b16 v[54:55], v220 offset:28160
	v_add_f32_e32 v97, v58, v97
	v_add_f32_e32 v97, v59, v97
	v_add_f32_e32 v97, v60, v97
	v_add_f32_e32 v97, v61, v97
	v_cvt_pk_bf16_f32 v136, v56, v57
	v_cvt_pk_bf16_f32 v137, v58, v59
	s_waitcnt lgkmcnt(14)
	v_mfma_f32_32x32x16_bf16 v[64:79], v[106:109], v[148:151], v[64:79]
	ds_read_b64_tr_b16 v[56:57], v220 offset:31744
	ds_read_b64_tr_b16 v[58:59], v220 offset:32256
	v_mfma_f32_32x32x16_bf16 v[32:47], v[160:163], v[148:151], v[32:47]
	v_add_f32_e32 v97, v62, v97
	v_add_f32_e32 v97, v63, v97
	v_add_f32_e32 v97, 0, v97
	v_cvt_pk_bf16_f32 v138, v60, v61
	v_cvt_pk_bf16_f32 v139, v62, v63
	s_waitcnt lgkmcnt(14)
	v_mfma_f32_32x32x16_bf16 v[0:15], v[156:159], v[164:167], v[0:15]
	s_nop 1
	v_exp_f32_e32 v64, v64
	v_exp_f32_e32 v65, v65
	v_exp_f32_e32 v66, v66
	v_exp_f32_e32 v67, v67
	s_waitcnt lgkmcnt(12)
	v_mfma_f32_32x32x16_bf16 v[16:31], v[156:159], v[80:83], v[16:31]
	v_exp_f32_e32 v68, v68
	v_exp_f32_e32 v69, v69
	v_exp_f32_e32 v70, v70
	v_exp_f32_e32 v71, v71
	s_waitcnt lgkmcnt(10)
	v_mfma_f32_32x32x16_bf16 v[0:15], v[152:155], v[84:87], v[0:15]
	v_exp_f32_e32 v72, v72
	v_exp_f32_e32 v73, v73
	v_exp_f32_e32 v74, v74
	v_exp_f32_e32 v75, v75
	s_waitcnt lgkmcnt(8)
	v_mfma_f32_32x32x16_bf16 v[16:31], v[152:155], v[88:91], v[16:31]
	v_exp_f32_e32 v76, v76
	v_exp_f32_e32 v77, v77
	v_exp_f32_e32 v78, v78
	v_exp_f32_e32 v79, v79
	s_waitcnt lgkmcnt(6)
	v_mfma_f32_32x32x16_bf16 v[0:15], v[144:147], v[92:95], v[0:15]
	v_exp_f32_e32 v32, v32
	v_exp_f32_e32 v33, v33
	v_exp_f32_e32 v34, v34
	v_exp_f32_e32 v35, v35
	s_waitcnt lgkmcnt(4)
	v_mfma_f32_32x32x16_bf16 v[16:31], v[144:147], v[48:51], v[16:31]
	v_exp_f32_e32 v36, v36
	v_exp_f32_e32 v37, v37
	v_exp_f32_e32 v38, v38
	v_exp_f32_e32 v39, v39
	s_waitcnt lgkmcnt(2)
	v_mfma_f32_32x32x16_bf16 v[0:15], v[136:139], v[52:55], v[0:15]
	v_exp_f32_e32 v40, v40
	v_exp_f32_e32 v41, v41
	v_exp_f32_e32 v42, v42
	v_exp_f32_e32 v43, v43
	s_waitcnt lgkmcnt(0)
	v_mfma_f32_32x32x16_bf16 v[16:31], v[136:139], v[56:59], v[16:31]
	v_exp_f32_e32 v44, v44
	v_exp_f32_e32 v45, v45
	v_exp_f32_e32 v46, v46
	v_exp_f32_e32 v47, v47
	v_add_f32_e32 v48, v64, v65
	v_add_f32_e32 v48, v66, v48
	v_add_f32_e32 v48, v67, v48
	v_add_f32_e32 v48, v68, v48
	v_add_f32_e32 v48, v69, v48
	v_add_f32_e32 v48, v70, v48
	v_add_f32_e32 v48, v71, v48
	v_add_f32_e32 v48, v72, v48
	v_add_f32_e32 v48, v73, v48
	v_add_f32_e32 v48, v74, v48
	v_add_f32_e32 v48, v75, v48
	v_add_f32_e32 v48, v76, v48
	v_add_f32_e32 v48, v77, v48
	v_add_f32_e32 v48, v78, v48
	v_add_f32_e32 v48, v79, v48
	v_add_f32_e32 v48, v32, v48
	v_add_f32_e32 v48, v33, v48
	v_add_f32_e32 v48, v34, v48
	v_add_f32_e32 v48, v35, v48
	v_add_f32_e32 v48, v36, v48
	v_add_f32_e32 v48, v37, v48
	v_add_f32_e32 v48, v38, v48
	v_add_f32_e32 v48, v39, v48
	v_add_f32_e32 v48, v40, v48
	v_add_f32_e32 v48, v41, v48
	v_add_f32_e32 v48, v42, v48
	v_add_f32_e32 v48, v43, v48
	v_add_f32_e32 v48, v44, v48
	v_add_f32_e32 v48, v45, v48
	v_add_f32_e32 v48, v46, v48
	v_add_f32_e32 v48, v47, v48
	v_add_f32_e32 v49, v96, v97
	v_add_f32_e32 v48, v49, v48
	v_cvt_pk_bf16_f32 v32, v32, v33
	v_cvt_pk_bf16_f32 v50, v64, v65
	v_cvt_pk_bf16_f32 v51, v66, v67
	v_cvt_pk_bf16_f32 v52, v68, v69
	v_cvt_pk_bf16_f32 v53, v70, v71
	v_cvt_pk_bf16_f32 v54, v72, v73
	v_cvt_pk_bf16_f32 v55, v74, v75
	v_cvt_pk_bf16_f32 v56, v76, v77
	v_cvt_pk_bf16_f32 v57, v78, v79
	v_cvt_pk_bf16_f32 v33, v34, v35
	v_cvt_pk_bf16_f32 v34, v36, v37
	v_cvt_pk_bf16_f32 v35, v38, v39
	v_cvt_pk_bf16_f32 v36, v40, v41
	v_cvt_pk_bf16_f32 v37, v42, v43
	v_cvt_pk_bf16_f32 v38, v44, v45
	v_cvt_pk_bf16_f32 v39, v46, v47
	ds_read_b64_tr_b16 v[40:41],v222 offset:0
	ds_read_b64_tr_b16 v[42:43],v222 offset:512
	ds_read_b64_tr_b16 v[44:45],v222 offset:1024
	ds_read_b64_tr_b16 v[46:47],v222 offset:1536
	ds_read_b64_tr_b16 v[58:59],v222 offset:2048
	ds_read_b64_tr_b16 v[60:61],v222 offset:2560
	ds_read_b64_tr_b16 v[62:63],v222 offset:3072
	ds_read_b64_tr_b16 v[64:65],v222 offset:3584
	s_waitcnt lgkmcnt(0)
	s_nop 0
	v_mfma_f32_32x32x16_bf16 v[0:15], v[50:53], v[40:43], v[0:15]
	ds_read_b64_tr_b16 v[40:41],v222 offset:4096
	ds_read_b64_tr_b16 v[42:43],v222 offset:4608
	v_mfma_f32_32x32x16_bf16 v[0:15], v[54:57], v[44:47], v[0:15]
	ds_read_b64_tr_b16 v[44:45],v222 offset:5120
	ds_read_b64_tr_b16 v[46:47],v222 offset:5632
	v_mfma_f32_32x32x16_bf16 v[0:15], v[32:35], v[58:61], v[0:15]
	ds_read_b64_tr_b16 v[58:59],v222 offset:6144
	ds_read_b64_tr_b16 v[60:61],v222 offset:6656
	ds_read_b64_tr_b16 v[66:67],v222 offset:7168
	ds_read_b64_tr_b16 v[68:69],v222 offset:7680
	s_waitcnt lgkmcnt(0)
	v_mfma_f32_32x32x16_bf16 v[0:15], v[36:39], v[62:65], v[0:15]
	v_mfma_f32_32x32x16_bf16 v[16:31], v[50:53], v[40:43], v[16:31]
	v_mfma_f32_32x32x16_bf16 v[16:31], v[54:57], v[44:47], v[16:31]
	v_mfma_f32_32x32x16_bf16 v[16:31], v[32:35], v[58:61], v[16:31]
	v_mov_b32_e32 v32, v48
	s_nop 1
	v_permlane32_swap_b32_e32 v48, v32
	v_mfma_f32_32x32x16_bf16 v[16:31], v[36:39], v[66:69], v[16:31]
	s_and_saveexec_b64 s[4:5], s[0:1]
	v_lshl_add_u32 v33, v195, 2, s10
	v_add_f32_e32 v32, v48, v32
	ds_write_b32 v33, v32 offset:49280
	s_or_b64 exec, exec, s[4:5]
	s_waitcnt lgkmcnt(0)
	v_add_u32_e32 v40, s10, v221
	ds_read_b128 v[32:35], v40 offset:49280
	ds_read_b128 v[36:39], v40 offset:49312
	s_lshl_b64 s[4:5], s[64:65], 11
	s_add_u32 s4, s34, s4
	s_addc_u32 s5, s35, s5
	s_waitcnt lgkmcnt(1)
	v_rcp_f32_e32 v41, v32
	s_lshl_b32 s10, s67, 12
	v_rcp_f32_e32 v42, v33
	v_rcp_f32_e32 v43, v34
	v_rcp_f32_e32 v44, v35
	s_waitcnt lgkmcnt(0)
	v_rcp_f32_e32 v45, v36
	ds_read_b128 v[32:35], v40 offset:49344
	v_rcp_f32_e32 v46, v37
	v_rcp_f32_e32 v47, v38
	v_rcp_f32_e32 v48, v39
	ds_read_b128 v[36:39], v40 offset:49376
	s_add_i32 s10, s10, 0
	v_lshlrev_b32_e32 v40, 1, v195
	v_mul_f32_e32 v0, v0, v41
	v_add3_u32 v40, s10, v223, v40
	v_cvt_pk_bf16_f32 v0, v0, s0
	ds_write_b16 v40, v0 offset:51200
	v_mul_f32_e32 v0, v16, v41
	v_cvt_pk_bf16_f32 v0, v0, s0
	ds_write_b16 v40, v0 offset:51264
	v_mul_f32_e32 v0, v1, v42
	v_cvt_pk_bf16_f32 v0, v0, s0
	ds_write_b16 v40, v0 offset:51328
	v_mul_f32_e32 v0, v17, v42
	v_cvt_pk_bf16_f32 v0, v0, s0
	ds_write_b16 v40, v0 offset:51392
	v_mul_f32_e32 v0, v2, v43
	v_cvt_pk_bf16_f32 v0, v0, s0
	ds_write_b16 v40, v0 offset:51456
	v_mul_f32_e32 v0, v18, v43
	v_cvt_pk_bf16_f32 v0, v0, s0
	ds_write_b16 v40, v0 offset:51520
	v_mul_f32_e32 v0, v3, v44
	v_cvt_pk_bf16_f32 v0, v0, s0
	ds_write_b16 v40, v0 offset:51584
	v_mul_f32_e32 v0, v19, v44
	v_cvt_pk_bf16_f32 v0, v0, s0
	ds_write_b16 v40, v0 offset:51648
	v_mul_f32_e32 v0, v4, v45
	v_cvt_pk_bf16_f32 v0, v0, s0
	ds_write_b16 v40, v0 offset:52224
	v_mul_f32_e32 v0, v20, v45
	v_cvt_pk_bf16_f32 v0, v0, s0
	ds_write_b16 v40, v0 offset:52288
	v_mul_f32_e32 v0, v5, v46
	v_cvt_pk_bf16_f32 v0, v0, s0
	ds_write_b16 v40, v0 offset:52352
	v_mul_f32_e32 v0, v21, v46
	v_cvt_pk_bf16_f32 v0, v0, s0
	ds_write_b16 v40, v0 offset:52416
	v_mul_f32_e32 v0, v6, v47
	v_cvt_pk_bf16_f32 v0, v0, s0
	ds_write_b16 v40, v0 offset:52480
	v_mul_f32_e32 v0, v22, v47
	v_cvt_pk_bf16_f32 v0, v0, s0
	s_waitcnt lgkmcnt(14)
	v_rcp_f32_e32 v32, v32
	ds_write_b16 v40, v0 offset:52544
	v_mul_f32_e32 v0, v7, v48
	v_cvt_pk_bf16_f32 v0, v0, s0
	ds_write_b16 v40, v0 offset:52608
	v_mul_f32_e32 v0, v23, v48
	v_cvt_pk_bf16_f32 v0, v0, s0
	v_rcp_f32_e32 v33, v33
	ds_write_b16 v40, v0 offset:52672
	v_mul_f32_e32 v0, v8, v32
	v_cvt_pk_bf16_f32 v0, v0, s0
	ds_write_b16 v40, v0 offset:53248
	v_mul_f32_e32 v0, v24, v32
	v_cvt_pk_bf16_f32 v0, v0, s0
	v_rcp_f32_e32 v34, v34
	ds_write_b16 v40, v0 offset:53312
	v_mul_f32_e32 v0, v9, v33
	v_cvt_pk_bf16_f32 v0, v0, s0
	ds_write_b16 v40, v0 offset:53376
	v_mul_f32_e32 v0, v25, v33
	v_cvt_pk_bf16_f32 v0, v0, s0
	v_rcp_f32_e32 v35, v35
	ds_write_b16 v40, v0 offset:53440
	v_mul_f32_e32 v0, v10, v34
	v_cvt_pk_bf16_f32 v0, v0, s0
	ds_write_b16 v40, v0 offset:53504
	v_mul_f32_e32 v0, v26, v34
	v_cvt_pk_bf16_f32 v0, v0, s0
	s_waitcnt lgkmcnt(14)
	v_rcp_f32_e32 v36, v36
	ds_write_b16 v40, v0 offset:53568
	v_mul_f32_e32 v0, v11, v35
	v_cvt_pk_bf16_f32 v0, v0, s0
	ds_write_b16 v40, v0 offset:53632
	v_mul_f32_e32 v0, v27, v35
	v_cvt_pk_bf16_f32 v0, v0, s0
	v_rcp_f32_e32 v37, v37
	ds_write_b16 v40, v0 offset:53696
	v_mul_f32_e32 v0, v12, v36
	v_cvt_pk_bf16_f32 v0, v0, s0
	ds_write_b16 v40, v0 offset:54272
	v_mul_f32_e32 v0, v28, v36
	v_cvt_pk_bf16_f32 v0, v0, s0
	v_rcp_f32_e32 v38, v38
	ds_write_b16 v40, v0 offset:54336
	v_mul_f32_e32 v0, v13, v37
	v_cvt_pk_bf16_f32 v0, v0, s0
	ds_write_b16 v40, v0 offset:54400
	v_mul_f32_e32 v0, v29, v37
	v_cvt_pk_bf16_f32 v0, v0, s0
	v_rcp_f32_e32 v39, v39
	ds_write_b16 v40, v0 offset:54464
	v_mul_f32_e32 v0, v14, v38
	v_cvt_pk_bf16_f32 v0, v0, s0
	ds_write_b16 v40, v0 offset:54528
	v_mul_f32_e32 v0, v30, v38
	v_cvt_pk_bf16_f32 v0, v0, s0
	ds_write_b16 v40, v0 offset:54592
	v_mul_f32_e32 v0, v15, v39
	v_cvt_pk_bf16_f32 v0, v0, s0
	ds_write_b16 v40, v0 offset:54656
	v_mul_f32_e32 v0, v31, v39
	v_cvt_pk_bf16_f32 v0, v0, s0
	v_lshlrev_b32_e32 v190, 1, v198
	ds_write_b16 v40, v0 offset:54720
	v_add_u32_e32 v5, s10, v190
	s_waitcnt lgkmcnt(0)
	v_add_u32_e32 v4, v5, v224
	ds_read_b128 v[10:13], v4 offset:51200
	v_xor_b32_e32 v2, 1, v236
	v_cmp_lt_i32_e32 vcc, v2, v180
	v_xor_b32_e32 v3, 2, v236
	s_add_u32 s4, s4, s66
	s_waitcnt lgkmcnt(0)
	v_and_b32_e32 v7, 0xffff0000, v10
	v_lshlrev_b32_e32 v6, 16, v10
	v_mul_f32_e32 v7, v7, v7
	v_and_b32_e32 v8, 0xffff0000, v11
	v_fmac_f32_e32 v7, v6, v6
	v_lshlrev_b32_e32 v6, 16, v11
	v_mul_f32_e32 v8, v8, v8
	v_fmac_f32_e32 v8, v6, v6
	v_add_f32_e32 v6, v7, v8
	v_and_b32_e32 v8, 0xffff0000, v12
	v_lshlrev_b32_e32 v7, 16, v12
	v_mul_f32_e32 v8, v8, v8
	v_fmac_f32_e32 v8, v7, v7
	v_add_f32_e32 v6, v8, v6
	v_and_b32_e32 v8, 0xffff0000, v13
	v_lshlrev_b32_e32 v7, 16, v13
	v_mul_f32_e32 v8, v8, v8
	v_cndmask_b32_e32 v2, v236, v2, vcc
	v_fmac_f32_e32 v8, v7, v7
	v_lshlrev_b32_e32 v2, 2, v2
	v_add_f32_e32 v6, v8, v6
	s_nop 1
	v_mov_b32_dpp v7, v6 quad_perm:[1,0,3,2] row_mask:0xf bank_mask:0xf
	v_cmp_lt_i32_e32 vcc, v3, v180
	v_xor_b32_e32 v4, 4, v236
	s_addc_u32 s5, s5, 0
	v_cndmask_b32_e32 v3, v236, v3, vcc
	v_lshlrev_b32_e32 v3, 2, v3
	s_waitcnt lgkmcnt(0)
	v_add_f32_e32 v6, v6, v7
	s_nop 1
	v_mov_b32_dpp v7, v6 quad_perm:[2,3,0,1] row_mask:0xf bank_mask:0xf
	v_cmp_lt_i32_e32 vcc, v4, v180
	v_lshl_add_u64 v[0:1], s[4:5], 0, v[190:191]
	s_lshl_b64 s[4:5], s[52:53], 2
	v_cndmask_b32_e32 v4, v236, v4, vcc
	v_lshlrev_b32_e32 v4, 2, v4
	s_add_u32 s4, s6, s4
	s_waitcnt lgkmcnt(0)
	v_add_f32_e32 v7, v6, v7
	s_addc_u32 s5, s7, s5
	s_lshl_b32 s10, s87, 2
	s_nop 1
	v_mov_b32_dpp v8, v7 row_half_mirror row_mask:0xf bank_mask:0xf
	s_add_u32 s10, s4, s10
	s_addc_u32 s16, s5, 0
	s_lshl_b64 s[4:5], s[60:61], 2
	s_add_u32 s4, s10, s4
	s_addc_u32 s5, s16, s5
	v_lshl_add_u64 v[14:15], v[0:1], 0, v[200:201]
	v_lshlrev_b32_e32 v6, 2, v196
	global_store_dwordx4 v[14:15], v[10:13], off
	s_and_saveexec_b64 s[52:53], s[2:3]
	s_cbranch_execz .LBB0_452
	s_waitcnt lgkmcnt(0)
	v_add_f32_e32 v7, v7, v8
	global_atomic_add_f32 v6, v7, s[4:5]
.LBB0_452:
	s_or_b64 exec, exec, s[52:53]
	v_add_u32_e32 v7, v5, v225
	ds_read_b128 v[10:13], v7 offset:51200
	s_waitcnt lgkmcnt(0)
	v_and_b32_e32 v8, 0xffff0000, v10
	v_and_b32_e32 v14, 0xffff0000, v11
	v_lshlrev_b32_e32 v7, 16, v10
	v_lshlrev_b32_e32 v9, 16, v11
	v_mul_f32_e32 v8, v8, v8
	v_mul_f32_e32 v14, v14, v14
	v_fmac_f32_e32 v8, v7, v7
	v_fmac_f32_e32 v14, v9, v9
	v_and_b32_e32 v9, 0xffff0000, v12
	v_add_f32_e32 v7, v8, v14
	v_lshlrev_b32_e32 v8, 16, v12
	v_mul_f32_e32 v9, v9, v9
	v_fmac_f32_e32 v9, v8, v8
	v_add_f32_e32 v7, v9, v7
	v_and_b32_e32 v9, 0xffff0000, v13
	v_lshlrev_b32_e32 v8, 16, v13
	v_mul_f32_e32 v9, v9, v9
	v_fmac_f32_e32 v9, v8, v8
	v_add_f32_e32 v7, v9, v7
	s_nop 1
	v_mov_b32_dpp v8, v7 quad_perm:[1,0,3,2] row_mask:0xf bank_mask:0xf
	v_lshl_add_u64 v[14:15], v[0:1], 0, v[202:203]
	global_store_dwordx4 v[14:15], v[10:13], off
	s_waitcnt lgkmcnt(0)
	v_add_f32_e32 v7, v7, v8
	s_nop 1
	v_mov_b32_dpp v8, v7 quad_perm:[2,3,0,1] row_mask:0xf bank_mask:0xf
	s_waitcnt lgkmcnt(0)
	v_add_f32_e32 v7, v7, v8
	s_nop 1
	v_mov_b32_dpp v8, v7 row_half_mirror row_mask:0xf bank_mask:0xf
	s_and_saveexec_b64 s[52:53], s[2:3]
	s_cbranch_execz .LBB0_454
	s_waitcnt lgkmcnt(0)
	v_add_f32_e32 v7, v7, v8
	global_atomic_add_f32 v6, v7, s[4:5] offset:32
.LBB0_454:
	s_or_b64 exec, exec, s[52:53]
	v_add_u32_e32 v7, v5, v226
	ds_read_b128 v[10:13], v7 offset:51200
	s_waitcnt lgkmcnt(0)
	v_and_b32_e32 v8, 0xffff0000, v10
	v_and_b32_e32 v14, 0xffff0000, v11
	v_lshlrev_b32_e32 v7, 16, v10
	v_lshlrev_b32_e32 v9, 16, v11
	v_mul_f32_e32 v8, v8, v8
	v_mul_f32_e32 v14, v14, v14
	v_fmac_f32_e32 v8, v7, v7
	v_fmac_f32_e32 v14, v9, v9
	v_and_b32_e32 v9, 0xffff0000, v12
	v_add_f32_e32 v7, v8, v14
	v_lshlrev_b32_e32 v8, 16, v12
	v_mul_f32_e32 v9, v9, v9
	v_fmac_f32_e32 v9, v8, v8
	v_add_f32_e32 v7, v9, v7
	v_and_b32_e32 v9, 0xffff0000, v13
	v_lshlrev_b32_e32 v8, 16, v13
	v_mul_f32_e32 v9, v9, v9
	v_fmac_f32_e32 v9, v8, v8
	v_add_f32_e32 v7, v9, v7
	s_nop 1
	v_mov_b32_dpp v8, v7 quad_perm:[1,0,3,2] row_mask:0xf bank_mask:0xf
	v_lshl_add_u64 v[14:15], v[0:1], 0, v[204:205]
	global_store_dwordx4 v[14:15], v[10:13], off
	s_waitcnt lgkmcnt(0)
	v_add_f32_e32 v7, v7, v8
	s_nop 1
	v_mov_b32_dpp v8, v7 quad_perm:[2,3,0,1] row_mask:0xf bank_mask:0xf
	s_waitcnt lgkmcnt(0)
	v_add_f32_e32 v7, v7, v8
	s_nop 1
	v_mov_b32_dpp v8, v7 row_half_mirror row_mask:0xf bank_mask:0xf
	s_and_saveexec_b64 s[52:53], s[2:3]
	s_cbranch_execz .LBB0_456
	s_waitcnt lgkmcnt(0)
	v_add_f32_e32 v7, v7, v8
	global_atomic_add_f32 v6, v7, s[4:5] offset:64
.LBB0_456:
	s_or_b64 exec, exec, s[52:53]
	v_add_u32_e32 v5, v5, v227
	s_waitcnt lgkmcnt(0)
	ds_read_b128 v[8:11], v5 offset:51200
	v_lshl_add_u64 v[0:1], v[0:1], 0, v[206:207]
	s_waitcnt lgkmcnt(0)
	v_and_b32_e32 v7, 0xffff0000, v8
	v_and_b32_e32 v13, 0xffff0000, v9
	v_lshlrev_b32_e32 v5, 16, v8
	v_lshlrev_b32_e32 v12, 16, v9
	v_mul_f32_e32 v7, v7, v7
	v_mul_f32_e32 v13, v13, v13
	v_fmac_f32_e32 v7, v5, v5
	v_fmac_f32_e32 v13, v12, v12
	v_and_b32_e32 v12, 0xffff0000, v10
	v_add_f32_e32 v5, v7, v13
	v_lshlrev_b32_e32 v7, 16, v10
	v_mul_f32_e32 v12, v12, v12
	v_fmac_f32_e32 v12, v7, v7
	v_add_f32_e32 v5, v12, v5
	v_and_b32_e32 v12, 0xffff0000, v11
	v_lshlrev_b32_e32 v7, 16, v11
	v_mul_f32_e32 v12, v12, v12
	v_fmac_f32_e32 v12, v7, v7
	v_add_f32_e32 v5, v12, v5
	s_nop 1
	v_mov_b32_dpp v2, v5 quad_perm:[1,0,3,2] row_mask:0xf bank_mask:0xf
	global_store_dwordx4 v[0:1], v[8:11], off
	s_waitcnt lgkmcnt(0)
	v_add_f32_e32 v2, v5, v2
	s_nop 1
	v_mov_b32_dpp v3, v2 quad_perm:[2,3,0,1] row_mask:0xf bank_mask:0xf
	s_waitcnt lgkmcnt(0)
	v_add_f32_e32 v2, v2, v3
	s_nop 1
	v_mov_b32_dpp v3, v2 row_half_mirror row_mask:0xf bank_mask:0xf
	s_and_saveexec_b64 s[52:53], s[2:3]
	s_cbranch_execz .LBB0_399
	s_waitcnt lgkmcnt(0)
	v_add_f32_e32 v0, v2, v3
	global_atomic_add_f32 v6, v0, s[4:5] offset:96
	s_branch .LBB0_399

.Lcomb:
	s_mov_b64 exec, -1
	v_lshlrev_b32_e32 v132, 5, v240
	v_lshlrev_b32_e32 v128, 4, v240
	global_load_dwordx4 v[120:123], v132, s[62:63]
	global_load_dwordx4 v[124:127], v132, s[62:63] offset:16
	s_lshl_b32 s98, s74, 10
	v_add_u32_e32 v133, s98, v128
	s_mul_i32 s98, s74, 0xe00
	s_addk_i32 s98, 0xa00
	v_add_u32_e32 v134, s98, v128
	s_lshl_b32 s98, s74, 11
	s_addk_i32 s98, 0x400
	v_add_u32_e32 v135, s98, v128
	v_mov_b32_e32 v140, 0xbdd2d3e8
	v_mov_b32_e32 v142, 0xc0135761
	v_mov_b32_e32 v131, 0x358637bd
	global_load_dwordx4 v[0:3], v133, s[22:23] nt
	global_load_dwordx4 v[4:7], v133, s[20:21] nt
	global_load_dwordx4 v[8:11], v134, s[38:39] nt
	v_add_u32_e32 v136, 0x200000, v133
	v_add_u32_e32 v137, 0x700000, v134
	global_load_dwordx4 v[12:15], v136, s[22:23] nt
	global_load_dwordx4 v[16:19], v136, s[20:21] nt
	global_load_dwordx4 v[20:23], v137, s[38:39] nt
	v_add_u32_e32 v136, 0x400000, v133
	v_add_u32_e32 v137, 0xe00000, v134
	global_load_dwordx4 v[24:27], v136, s[22:23] nt
	global_load_dwordx4 v[28:31], v136, s[20:21] nt
	global_load_dwordx4 v[32:35], v137, s[38:39] nt
	v_add_u32_e32 v136, 0x600000, v133
	v_add_u32_e32 v137, 0x1500000, v134
	global_load_dwordx4 v[36:39], v136, s[22:23] nt
	global_load_dwordx4 v[40:43], v136, s[20:21] nt
	global_load_dwordx4 v[44:47], v137, s[38:39] nt
	v_add_u32_e32 v136, 0x800000, v133
	v_add_u32_e32 v137, 0x1c00000, v134
	global_load_dwordx4 v[48:51], v136, s[22:23] nt
	global_load_dwordx4 v[52:55], v136, s[20:21] nt
	global_load_dwordx4 v[56:59], v137, s[38:39] nt
	v_add_u32_e32 v136, 0xa00000, v133
	v_add_u32_e32 v137, 0x2300000, v134
	global_load_dwordx4 v[60:63], v136, s[22:23] nt
	global_load_dwordx4 v[64:67], v136, s[20:21] nt
	global_load_dwordx4 v[68:71], v137, s[38:39] nt
	v_add_u32_e32 v136, 0xc00000, v133
	v_add_u32_e32 v137, 0x2a00000, v134
	global_load_dwordx4 v[72:75], v136, s[22:23] nt
	global_load_dwordx4 v[76:79], v136, s[20:21] nt
	global_load_dwordx4 v[80:83], v137, s[38:39] nt
	v_add_u32_e32 v136, 0xe00000, v133
	v_add_u32_e32 v137, 0x3100000, v134
	global_load_dwordx4 v[84:87], v136, s[22:23] nt
	global_load_dwordx4 v[88:91], v136, s[20:21] nt
	global_load_dwordx4 v[92:95], v137, s[38:39] nt
	s_waitcnt vmcnt(21)
	v_lshlrev_b32_e32 v146, 16, v0
	v_and_b32_e32 v147, 0xffff0000, v0
	v_lshlrev_b32_e32 v148, 16, v1
	v_and_b32_e32 v149, 0xffff0000, v1
	v_lshlrev_b32_e32 v150, 16, v2
	v_and_b32_e32 v151, 0xffff0000, v2
	v_lshlrev_b32_e32 v152, 16, v3
	v_and_b32_e32 v153, 0xffff0000, v3
	v_lshlrev_b32_e32 v154, 16, v4
	v_and_b32_e32 v155, 0xffff0000, v4
	v_lshlrev_b32_e32 v156, 16, v5
	v_and_b32_e32 v157, 0xffff0000, v5
	v_lshlrev_b32_e32 v158, 16, v6
	v_and_b32_e32 v159, 0xffff0000, v6
	v_lshlrev_b32_e32 v160, 16, v7
	v_and_b32_e32 v161, 0xffff0000, v7
	v_lshlrev_b32_e32 v162, 16, v8
	v_and_b32_e32 v163, 0xffff0000, v8
	v_lshlrev_b32_e32 v164, 16, v9
	v_and_b32_e32 v165, 0xffff0000, v9
	v_lshlrev_b32_e32 v166, 16, v10
	v_and_b32_e32 v167, 0xffff0000, v10
	v_lshlrev_b32_e32 v168, 16, v11
	v_and_b32_e32 v169, 0xffff0000, v11
	v_pk_add_f32 v[146:147], v[146:147], v[154:155]
	v_pk_add_f32 v[148:149], v[148:149], v[156:157]
	v_pk_add_f32 v[150:151], v[150:151], v[158:159]
	v_pk_add_f32 v[152:153], v[152:153], v[160:161]
	v_pk_mul_f32 v[170:171], v[162:163], v[162:163]
	v_pk_mul_f32 v[172:173], v[164:165], v[164:165]
	v_pk_mul_f32 v[174:175], v[166:167], v[166:167]
	v_pk_mul_f32 v[176:177], v[168:169], v[168:169]
	v_pk_fma_f32 v[170:171], v[170:171], v[140:141], v[142:143] op_sel_hi:[1,0,0]
	v_pk_fma_f32 v[172:173], v[172:173], v[140:141], v[142:143] op_sel_hi:[1,0,0]
	v_pk_fma_f32 v[174:175], v[174:175], v[140:141], v[142:143] op_sel_hi:[1,0,0]
	v_pk_fma_f32 v[176:177], v[176:177], v[140:141], v[142:143] op_sel_hi:[1,0,0]
	v_pk_mul_f32 v[170:171], v[170:171], v[162:163]
	v_pk_mul_f32 v[172:173], v[172:173], v[164:165]
	v_pk_mul_f32 v[174:175], v[174:175], v[166:167]
	v_pk_mul_f32 v[176:177], v[176:177], v[168:169]
	v_pk_mul_f32 v[154:155], v[146:147], v[162:163]
	v_pk_mul_f32 v[156:157], v[148:149], v[164:165]
	v_pk_mul_f32 v[158:159], v[150:151], v[166:167]
	v_pk_mul_f32 v[160:161], v[152:153], v[168:169]
	v_exp_f32_e32 v170, v170
	v_exp_f32_e32 v171, v171
	v_exp_f32_e32 v172, v172
	v_exp_f32_e32 v173, v173
	v_exp_f32_e32 v174, v174
	v_exp_f32_e32 v175, v175
	v_exp_f32_e32 v176, v176
	v_exp_f32_e32 v177, v177
	v_pk_add_f32 v[170:171], v[170:171], 1.0 op_sel_hi:[1,0]
	v_pk_add_f32 v[172:173], v[172:173], 1.0 op_sel_hi:[1,0]
	v_pk_add_f32 v[174:175], v[174:175], 1.0 op_sel_hi:[1,0]
	v_pk_add_f32 v[176:177], v[176:177], 1.0 op_sel_hi:[1,0]
	v_rcp_f32_e32 v170, v170
	v_rcp_f32_e32 v171, v171
	v_rcp_f32_e32 v172, v172
	v_rcp_f32_e32 v173, v173
	v_rcp_f32_e32 v174, v174
	v_rcp_f32_e32 v175, v175
	v_rcp_f32_e32 v176, v176
	v_rcp_f32_e32 v177, v177
	v_pk_mul_f32 v[96:97], v[154:155], v[170:171]
	v_pk_mul_f32 v[98:99], v[156:157], v[172:173]
	v_pk_mul_f32 v[100:101], v[158:159], v[174:175]
	v_pk_mul_f32 v[102:103], v[160:161], v[176:177]
	v_pk_mul_f32 v[112:113], v[96:97], v[96:97]
	v_pk_mul_f32 v[114:115], v[98:99], v[98:99]
	v_pk_fma_f32 v[112:113], v[100:101], v[100:101], v[112:113]
	v_pk_fma_f32 v[114:115], v[102:103], v[102:103], v[114:115]
	v_pk_add_f32 v[112:113], v[112:113], v[114:115]
	v_add_f32_e32 v112, v112, v113
	s_nop 1
	v_add_f32_dpp v112, v112, v112 quad_perm:[1,0,3,2] row_mask:0xf bank_mask:0xf
	s_nop 1
	v_add_f32_dpp v112, v112, v112 quad_perm:[2,3,0,1] row_mask:0xf bank_mask:0xf
	s_nop 1
	v_add_f32_dpp v112, v112, v112 row_half_mirror row_mask:0xf bank_mask:0xf
	s_nop 1
	v_add_f32_dpp v112, v112, v112 row_mirror row_mask:0xf bank_mask:0xf
	s_nop 1
	v_readlane_b32 s98, v112, 0
	v_readlane_b32 s99, v112, 16
	v_readlane_b32 s100, v112, 32
	v_readlane_b32 vcc_lo, v112, 48
	s_nop 1
	v_mov_b32_e32 v113, s98
	v_add_f32_e32 v113, s99, v113
	v_add_f32_e32 v113, s100, v113
	v_add_f32_e32 v113, vcc_lo, v113
	v_fmamk_f32 v144, v113, 0x3b000000, v131
	v_rsq_f32_e32 v144, v144
	s_nop 0
	v_pk_mul_f32 v[146:147], v[96:97], v[144:145] op_sel_hi:[1,0]
	v_pk_mul_f32 v[148:149], v[98:99], v[144:145] op_sel_hi:[1,0]
	v_pk_mul_f32 v[150:151], v[100:101], v[144:145] op_sel_hi:[1,0]
	v_pk_mul_f32 v[152:153], v[102:103], v[144:145] op_sel_hi:[1,0]
	v_pk_mul_f32 v[146:147], v[146:147], v[120:121]
	v_pk_mul_f32 v[148:149], v[148:149], v[122:123]
	v_pk_mul_f32 v[150:151], v[150:151], v[124:125]
	v_pk_mul_f32 v[152:153], v[152:153], v[126:127]
	v_cvt_pk_bf16_f32 v116, v146, v147
	v_cvt_pk_bf16_f32 v117, v148, v149
	v_cvt_pk_bf16_f32 v118, v150, v151
	v_cvt_pk_bf16_f32 v119, v152, v153
	global_store_dwordx4 v135, v[116:119], s[34:35]
	v_add_u32_e32 v136, 0x1000000, v133
	v_add_u32_e32 v137, 0x3800000, v134
	global_load_dwordx4 v[0:3], v136, s[22:23] nt
	global_load_dwordx4 v[4:7], v136, s[20:21] nt
	global_load_dwordx4 v[8:11], v137, s[38:39] nt
	s_waitcnt vmcnt(22)
	v_lshlrev_b32_e32 v146, 16, v12
	v_and_b32_e32 v147, 0xffff0000, v12
	v_lshlrev_b32_e32 v148, 16, v13
	v_and_b32_e32 v149, 0xffff0000, v13
	v_lshlrev_b32_e32 v150, 16, v14
	v_and_b32_e32 v151, 0xffff0000, v14
	v_lshlrev_b32_e32 v152, 16, v15
	v_and_b32_e32 v153, 0xffff0000, v15
	v_lshlrev_b32_e32 v154, 16, v16
	v_and_b32_e32 v155, 0xffff0000, v16
	v_lshlrev_b32_e32 v156, 16, v17
	v_and_b32_e32 v157, 0xffff0000, v17
	v_lshlrev_b32_e32 v158, 16, v18
	v_and_b32_e32 v159, 0xffff0000, v18
	v_lshlrev_b32_e32 v160, 16, v19
	v_and_b32_e32 v161, 0xffff0000, v19
	v_lshlrev_b32_e32 v162, 16, v20
	v_and_b32_e32 v163, 0xffff0000, v20
	v_lshlrev_b32_e32 v164, 16, v21
	v_and_b32_e32 v165, 0xffff0000, v21
	v_lshlrev_b32_e32 v166, 16, v22
	v_and_b32_e32 v167, 0xffff0000, v22
	v_lshlrev_b32_e32 v168, 16, v23
	v_and_b32_e32 v169, 0xffff0000, v23
	v_pk_add_f32 v[146:147], v[146:147], v[154:155]
	v_pk_add_f32 v[148:149], v[148:149], v[156:157]
	v_pk_add_f32 v[150:151], v[150:151], v[158:159]
	v_pk_add_f32 v[152:153], v[152:153], v[160:161]
	v_pk_mul_f32 v[170:171], v[162:163], v[162:163]
	v_pk_mul_f32 v[172:173], v[164:165], v[164:165]
	v_pk_mul_f32 v[174:175], v[166:167], v[166:167]
	v_pk_mul_f32 v[176:177], v[168:169], v[168:169]
	v_pk_fma_f32 v[170:171], v[170:171], v[140:141], v[142:143] op_sel_hi:[1,0,0]
	v_pk_fma_f32 v[172:173], v[172:173], v[140:141], v[142:143] op_sel_hi:[1,0,0]
	v_pk_fma_f32 v[174:175], v[174:175], v[140:141], v[142:143] op_sel_hi:[1,0,0]
	v_pk_fma_f32 v[176:177], v[176:177], v[140:141], v[142:143] op_sel_hi:[1,0,0]
	v_pk_mul_f32 v[170:171], v[170:171], v[162:163]
	v_pk_mul_f32 v[172:173], v[172:173], v[164:165]
	v_pk_mul_f32 v[174:175], v[174:175], v[166:167]
	v_pk_mul_f32 v[176:177], v[176:177], v[168:169]
	v_pk_mul_f32 v[154:155], v[146:147], v[162:163]
	v_pk_mul_f32 v[156:157], v[148:149], v[164:165]
	v_pk_mul_f32 v[158:159], v[150:151], v[166:167]
	v_pk_mul_f32 v[160:161], v[152:153], v[168:169]
	v_exp_f32_e32 v170, v170
	v_exp_f32_e32 v171, v171
	v_exp_f32_e32 v172, v172
	v_exp_f32_e32 v173, v173
	v_exp_f32_e32 v174, v174
	v_exp_f32_e32 v175, v175
	v_exp_f32_e32 v176, v176
	v_exp_f32_e32 v177, v177
	v_pk_add_f32 v[170:171], v[170:171], 1.0 op_sel_hi:[1,0]
	v_pk_add_f32 v[172:173], v[172:173], 1.0 op_sel_hi:[1,0]
	v_pk_add_f32 v[174:175], v[174:175], 1.0 op_sel_hi:[1,0]
	v_pk_add_f32 v[176:177], v[176:177], 1.0 op_sel_hi:[1,0]
	v_rcp_f32_e32 v170, v170
	v_rcp_f32_e32 v171, v171
	v_rcp_f32_e32 v172, v172
	v_rcp_f32_e32 v173, v173
	v_rcp_f32_e32 v174, v174
	v_rcp_f32_e32 v175, v175
	v_rcp_f32_e32 v176, v176
	v_rcp_f32_e32 v177, v177
	v_pk_mul_f32 v[96:97], v[154:155], v[170:171]
	v_pk_mul_f32 v[98:99], v[156:157], v[172:173]
	v_pk_mul_f32 v[100:101], v[158:159], v[174:175]
	v_pk_mul_f32 v[102:103], v[160:161], v[176:177]
	v_pk_mul_f32 v[112:113], v[96:97], v[96:97]
	v_pk_mul_f32 v[114:115], v[98:99], v[98:99]
	v_pk_fma_f32 v[112:113], v[100:101], v[100:101], v[112:113]
	v_pk_fma_f32 v[114:115], v[102:103], v[102:103], v[114:115]
	v_pk_add_f32 v[112:113], v[112:113], v[114:115]
	v_add_f32_e32 v112, v112, v113
	s_nop 1
	v_add_f32_dpp v112, v112, v112 quad_perm:[1,0,3,2] row_mask:0xf bank_mask:0xf
	s_nop 1
	v_add_f32_dpp v112, v112, v112 quad_perm:[2,3,0,1] row_mask:0xf bank_mask:0xf
	s_nop 1
	v_add_f32_dpp v112, v112, v112 row_half_mirror row_mask:0xf bank_mask:0xf
	s_nop 1
	v_add_f32_dpp v112, v112, v112 row_mirror row_mask:0xf bank_mask:0xf
	s_nop 1
	v_readlane_b32 s98, v112, 0
	v_readlane_b32 s99, v112, 16
	v_readlane_b32 s100, v112, 32
	v_readlane_b32 vcc_lo, v112, 48
	s_nop 1
	v_mov_b32_e32 v113, s98
	v_add_f32_e32 v113, s99, v113
	v_add_f32_e32 v113, s100, v113
	v_add_f32_e32 v113, vcc_lo, v113
	v_fmamk_f32 v144, v113, 0x3b000000, v131
	v_rsq_f32_e32 v144, v144
	s_nop 0
	v_pk_mul_f32 v[146:147], v[96:97], v[144:145] op_sel_hi:[1,0]
	v_pk_mul_f32 v[148:149], v[98:99], v[144:145] op_sel_hi:[1,0]
	v_pk_mul_f32 v[150:151], v[100:101], v[144:145] op_sel_hi:[1,0]
	v_pk_mul_f32 v[152:153], v[102:103], v[144:145] op_sel_hi:[1,0]
	v_pk_mul_f32 v[146:147], v[146:147], v[120:121]
	v_pk_mul_f32 v[148:149], v[148:149], v[122:123]
	v_pk_mul_f32 v[150:151], v[150:151], v[124:125]
	v_pk_mul_f32 v[152:153], v[152:153], v[126:127]
	v_cvt_pk_bf16_f32 v116, v146, v147
	v_cvt_pk_bf16_f32 v117, v148, v149
	v_cvt_pk_bf16_f32 v118, v150, v151
	v_cvt_pk_bf16_f32 v119, v152, v153
	v_add_u32_e32 v138, 0x400000, v135
	global_store_dwordx4 v138, v[116:119], s[34:35]
	v_add_u32_e32 v136, 0x1200000, v133
	v_add_u32_e32 v137, 0x3f00000, v134
	global_load_dwordx4 v[12:15], v136, s[22:23] nt
	global_load_dwordx4 v[16:19], v136, s[20:21] nt
	global_load_dwordx4 v[20:23], v137, s[38:39] nt
	s_waitcnt vmcnt(23)
	v_lshlrev_b32_e32 v146, 16, v24
	v_and_b32_e32 v147, 0xffff0000, v24
	v_lshlrev_b32_e32 v148, 16, v25
	v_and_b32_e32 v149, 0xffff0000, v25
	v_lshlrev_b32_e32 v150, 16, v26
	v_and_b32_e32 v151, 0xffff0000, v26
	v_lshlrev_b32_e32 v152, 16, v27
	v_and_b32_e32 v153, 0xffff0000, v27
	v_lshlrev_b32_e32 v154, 16, v28
	v_and_b32_e32 v155, 0xffff0000, v28
	v_lshlrev_b32_e32 v156, 16, v29
	v_and_b32_e32 v157, 0xffff0000, v29
	v_lshlrev_b32_e32 v158, 16, v30
	v_and_b32_e32 v159, 0xffff0000, v30
	v_lshlrev_b32_e32 v160, 16, v31
	v_and_b32_e32 v161, 0xffff0000, v31
	v_lshlrev_b32_e32 v162, 16, v32
	v_and_b32_e32 v163, 0xffff0000, v32
	v_lshlrev_b32_e32 v164, 16, v33
	v_and_b32_e32 v165, 0xffff0000, v33
	v_lshlrev_b32_e32 v166, 16, v34
	v_and_b32_e32 v167, 0xffff0000, v34
	v_lshlrev_b32_e32 v168, 16, v35
	v_and_b32_e32 v169, 0xffff0000, v35
	v_pk_add_f32 v[146:147], v[146:147], v[154:155]
	v_pk_add_f32 v[148:149], v[148:149], v[156:157]
	v_pk_add_f32 v[150:151], v[150:151], v[158:159]
	v_pk_add_f32 v[152:153], v[152:153], v[160:161]
	v_pk_mul_f32 v[170:171], v[162:163], v[162:163]
	v_pk_mul_f32 v[172:173], v[164:165], v[164:165]
	v_pk_mul_f32 v[174:175], v[166:167], v[166:167]
	v_pk_mul_f32 v[176:177], v[168:169], v[168:169]
	v_pk_fma_f32 v[170:171], v[170:171], v[140:141], v[142:143] op_sel_hi:[1,0,0]
	v_pk_fma_f32 v[172:173], v[172:173], v[140:141], v[142:143] op_sel_hi:[1,0,0]
	v_pk_fma_f32 v[174:175], v[174:175], v[140:141], v[142:143] op_sel_hi:[1,0,0]
	v_pk_fma_f32 v[176:177], v[176:177], v[140:141], v[142:143] op_sel_hi:[1,0,0]
	v_pk_mul_f32 v[170:171], v[170:171], v[162:163]
	v_pk_mul_f32 v[172:173], v[172:173], v[164:165]
	v_pk_mul_f32 v[174:175], v[174:175], v[166:167]
	v_pk_mul_f32 v[176:177], v[176:177], v[168:169]
	v_pk_mul_f32 v[154:155], v[146:147], v[162:163]
	v_pk_mul_f32 v[156:157], v[148:149], v[164:165]
	v_pk_mul_f32 v[158:159], v[150:151], v[166:167]
	v_pk_mul_f32 v[160:161], v[152:153], v[168:169]
	v_exp_f32_e32 v170, v170
	v_exp_f32_e32 v171, v171
	v_exp_f32_e32 v172, v172
	v_exp_f32_e32 v173, v173
	v_exp_f32_e32 v174, v174
	v_exp_f32_e32 v175, v175
	v_exp_f32_e32 v176, v176
	v_exp_f32_e32 v177, v177
	v_pk_add_f32 v[170:171], v[170:171], 1.0 op_sel_hi:[1,0]
	v_pk_add_f32 v[172:173], v[172:173], 1.0 op_sel_hi:[1,0]
	v_pk_add_f32 v[174:175], v[174:175], 1.0 op_sel_hi:[1,0]
	v_pk_add_f32 v[176:177], v[176:177], 1.0 op_sel_hi:[1,0]
	v_rcp_f32_e32 v170, v170
	v_rcp_f32_e32 v171, v171
	v_rcp_f32_e32 v172, v172
	v_rcp_f32_e32 v173, v173
	v_rcp_f32_e32 v174, v174
	v_rcp_f32_e32 v175, v175
	v_rcp_f32_e32 v176, v176
	v_rcp_f32_e32 v177, v177
	v_pk_mul_f32 v[96:97], v[154:155], v[170:171]
	v_pk_mul_f32 v[98:99], v[156:157], v[172:173]
	v_pk_mul_f32 v[100:101], v[158:159], v[174:175]
	v_pk_mul_f32 v[102:103], v[160:161], v[176:177]
	v_pk_mul_f32 v[112:113], v[96:97], v[96:97]
	v_pk_mul_f32 v[114:115], v[98:99], v[98:99]
	v_pk_fma_f32 v[112:113], v[100:101], v[100:101], v[112:113]
	v_pk_fma_f32 v[114:115], v[102:103], v[102:103], v[114:115]
	v_pk_add_f32 v[112:113], v[112:113], v[114:115]
	v_add_f32_e32 v112, v112, v113
	s_nop 1
	v_add_f32_dpp v112, v112, v112 quad_perm:[1,0,3,2] row_mask:0xf bank_mask:0xf
	s_nop 1
	v_add_f32_dpp v112, v112, v112 quad_perm:[2,3,0,1] row_mask:0xf bank_mask:0xf
	s_nop 1
	v_add_f32_dpp v112, v112, v112 row_half_mirror row_mask:0xf bank_mask:0xf
	s_nop 1
	v_add_f32_dpp v112, v112, v112 row_mirror row_mask:0xf bank_mask:0xf
	s_nop 1
	v_readlane_b32 s98, v112, 0
	v_readlane_b32 s99, v112, 16
	v_readlane_b32 s100, v112, 32
	v_readlane_b32 vcc_lo, v112, 48
	s_nop 1
	v_mov_b32_e32 v113, s98
	v_add_f32_e32 v113, s99, v113
	v_add_f32_e32 v113, s100, v113
	v_add_f32_e32 v113, vcc_lo, v113
	v_fmamk_f32 v144, v113, 0x3b000000, v131
	v_rsq_f32_e32 v144, v144
	s_nop 0
	v_pk_mul_f32 v[146:147], v[96:97], v[144:145] op_sel_hi:[1,0]
	v_pk_mul_f32 v[148:149], v[98:99], v[144:145] op_sel_hi:[1,0]
	v_pk_mul_f32 v[150:151], v[100:101], v[144:145] op_sel_hi:[1,0]
	v_pk_mul_f32 v[152:153], v[102:103], v[144:145] op_sel_hi:[1,0]
	v_pk_mul_f32 v[146:147], v[146:147], v[120:121]
	v_pk_mul_f32 v[148:149], v[148:149], v[122:123]
	v_pk_mul_f32 v[150:151], v[150:151], v[124:125]
	v_pk_mul_f32 v[152:153], v[152:153], v[126:127]
	v_cvt_pk_bf16_f32 v116, v146, v147
	v_cvt_pk_bf16_f32 v117, v148, v149
	v_cvt_pk_bf16_f32 v118, v150, v151
	v_cvt_pk_bf16_f32 v119, v152, v153
	v_add_u32_e32 v138, 0x800000, v135
	global_store_dwordx4 v138, v[116:119], s[34:35]
	v_add_u32_e32 v136, 0x1400000, v133
	v_add_u32_e32 v137, 0x4600000, v134
	global_load_dwordx4 v[24:27], v136, s[22:23] nt
	global_load_dwordx4 v[28:31], v136, s[20:21] nt
	global_load_dwordx4 v[32:35], v137, s[38:39] nt
	s_waitcnt vmcnt(24)
	v_lshlrev_b32_e32 v146, 16, v36
	v_and_b32_e32 v147, 0xffff0000, v36
	v_lshlrev_b32_e32 v148, 16, v37
	v_and_b32_e32 v149, 0xffff0000, v37
	v_lshlrev_b32_e32 v150, 16, v38
	v_and_b32_e32 v151, 0xffff0000, v38
	v_lshlrev_b32_e32 v152, 16, v39
	v_and_b32_e32 v153, 0xffff0000, v39
	v_lshlrev_b32_e32 v154, 16, v40
	v_and_b32_e32 v155, 0xffff0000, v40
	v_lshlrev_b32_e32 v156, 16, v41
	v_and_b32_e32 v157, 0xffff0000, v41
	v_lshlrev_b32_e32 v158, 16, v42
	v_and_b32_e32 v159, 0xffff0000, v42
	v_lshlrev_b32_e32 v160, 16, v43
	v_and_b32_e32 v161, 0xffff0000, v43
	v_lshlrev_b32_e32 v162, 16, v44
	v_and_b32_e32 v163, 0xffff0000, v44
	v_lshlrev_b32_e32 v164, 16, v45
	v_and_b32_e32 v165, 0xffff0000, v45
	v_lshlrev_b32_e32 v166, 16, v46
	v_and_b32_e32 v167, 0xffff0000, v46
	v_lshlrev_b32_e32 v168, 16, v47
	v_and_b32_e32 v169, 0xffff0000, v47
	v_pk_add_f32 v[146:147], v[146:147], v[154:155]
	v_pk_add_f32 v[148:149], v[148:149], v[156:157]
	v_pk_add_f32 v[150:151], v[150:151], v[158:159]
	v_pk_add_f32 v[152:153], v[152:153], v[160:161]
	v_pk_mul_f32 v[170:171], v[162:163], v[162:163]
	v_pk_mul_f32 v[172:173], v[164:165], v[164:165]
	v_pk_mul_f32 v[174:175], v[166:167], v[166:167]
	v_pk_mul_f32 v[176:177], v[168:169], v[168:169]
	v_pk_fma_f32 v[170:171], v[170:171], v[140:141], v[142:143] op_sel_hi:[1,0,0]
	v_pk_fma_f32 v[172:173], v[172:173], v[140:141], v[142:143] op_sel_hi:[1,0,0]
	v_pk_fma_f32 v[174:175], v[174:175], v[140:141], v[142:143] op_sel_hi:[1,0,0]
	v_pk_fma_f32 v[176:177], v[176:177], v[140:141], v[142:143] op_sel_hi:[1,0,0]
	v_pk_mul_f32 v[170:171], v[170:171], v[162:163]
	v_pk_mul_f32 v[172:173], v[172:173], v[164:165]
	v_pk_mul_f32 v[174:175], v[174:175], v[166:167]
	v_pk_mul_f32 v[176:177], v[176:177], v[168:169]
	v_pk_mul_f32 v[154:155], v[146:147], v[162:163]
	v_pk_mul_f32 v[156:157], v[148:149], v[164:165]
	v_pk_mul_f32 v[158:159], v[150:151], v[166:167]
	v_pk_mul_f32 v[160:161], v[152:153], v[168:169]
	v_exp_f32_e32 v170, v170
	v_exp_f32_e32 v171, v171
	v_exp_f32_e32 v172, v172
	v_exp_f32_e32 v173, v173
	v_exp_f32_e32 v174, v174
	v_exp_f32_e32 v175, v175
	v_exp_f32_e32 v176, v176
	v_exp_f32_e32 v177, v177
	v_pk_add_f32 v[170:171], v[170:171], 1.0 op_sel_hi:[1,0]
	v_pk_add_f32 v[172:173], v[172:173], 1.0 op_sel_hi:[1,0]
	v_pk_add_f32 v[174:175], v[174:175], 1.0 op_sel_hi:[1,0]
	v_pk_add_f32 v[176:177], v[176:177], 1.0 op_sel_hi:[1,0]
	v_rcp_f32_e32 v170, v170
	v_rcp_f32_e32 v171, v171
	v_rcp_f32_e32 v172, v172
	v_rcp_f32_e32 v173, v173
	v_rcp_f32_e32 v174, v174
	v_rcp_f32_e32 v175, v175
	v_rcp_f32_e32 v176, v176
	v_rcp_f32_e32 v177, v177
	v_pk_mul_f32 v[96:97], v[154:155], v[170:171]
	v_pk_mul_f32 v[98:99], v[156:157], v[172:173]
	v_pk_mul_f32 v[100:101], v[158:159], v[174:175]
	v_pk_mul_f32 v[102:103], v[160:161], v[176:177]
	v_pk_mul_f32 v[112:113], v[96:97], v[96:97]
	v_pk_mul_f32 v[114:115], v[98:99], v[98:99]
	v_pk_fma_f32 v[112:113], v[100:101], v[100:101], v[112:113]
	v_pk_fma_f32 v[114:115], v[102:103], v[102:103], v[114:115]
	v_pk_add_f32 v[112:113], v[112:113], v[114:115]
	v_add_f32_e32 v112, v112, v113
	s_nop 1
	v_add_f32_dpp v112, v112, v112 quad_perm:[1,0,3,2] row_mask:0xf bank_mask:0xf
	s_nop 1
	v_add_f32_dpp v112, v112, v112 quad_perm:[2,3,0,1] row_mask:0xf bank_mask:0xf
	s_nop 1
	v_add_f32_dpp v112, v112, v112 row_half_mirror row_mask:0xf bank_mask:0xf
	s_nop 1
	v_add_f32_dpp v112, v112, v112 row_mirror row_mask:0xf bank_mask:0xf
	s_nop 1
	v_readlane_b32 s98, v112, 0
	v_readlane_b32 s99, v112, 16
	v_readlane_b32 s100, v112, 32
	v_readlane_b32 vcc_lo, v112, 48
	s_nop 1
	v_mov_b32_e32 v113, s98
	v_add_f32_e32 v113, s99, v113
	v_add_f32_e32 v113, s100, v113
	v_add_f32_e32 v113, vcc_lo, v113
	v_fmamk_f32 v144, v113, 0x3b000000, v131
	v_rsq_f32_e32 v144, v144
	s_nop 0
	v_pk_mul_f32 v[146:147], v[96:97], v[144:145] op_sel_hi:[1,0]
	v_pk_mul_f32 v[148:149], v[98:99], v[144:145] op_sel_hi:[1,0]
	v_pk_mul_f32 v[150:151], v[100:101], v[144:145] op_sel_hi:[1,0]
	v_pk_mul_f32 v[152:153], v[102:103], v[144:145] op_sel_hi:[1,0]
	v_pk_mul_f32 v[146:147], v[146:147], v[120:121]
	v_pk_mul_f32 v[148:149], v[148:149], v[122:123]
	v_pk_mul_f32 v[150:151], v[150:151], v[124:125]
	v_pk_mul_f32 v[152:153], v[152:153], v[126:127]
	v_cvt_pk_bf16_f32 v116, v146, v147
	v_cvt_pk_bf16_f32 v117, v148, v149
	v_cvt_pk_bf16_f32 v118, v150, v151
	v_cvt_pk_bf16_f32 v119, v152, v153
	v_add_u32_e32 v138, 0xc00000, v135
	global_store_dwordx4 v138, v[116:119], s[34:35]
	v_add_u32_e32 v136, 0x1600000, v133
	v_add_u32_e32 v137, 0x4d00000, v134
	global_load_dwordx4 v[36:39], v136, s[22:23] nt
	global_load_dwordx4 v[40:43], v136, s[20:21] nt
	global_load_dwordx4 v[44:47], v137, s[38:39] nt
	s_waitcnt vmcnt(25)
	v_lshlrev_b32_e32 v146, 16, v48
	v_and_b32_e32 v147, 0xffff0000, v48
	v_lshlrev_b32_e32 v148, 16, v49
	v_and_b32_e32 v149, 0xffff0000, v49
	v_lshlrev_b32_e32 v150, 16, v50
	v_and_b32_e32 v151, 0xffff0000, v50
	v_lshlrev_b32_e32 v152, 16, v51
	v_and_b32_e32 v153, 0xffff0000, v51
	v_lshlrev_b32_e32 v154, 16, v52
	v_and_b32_e32 v155, 0xffff0000, v52
	v_lshlrev_b32_e32 v156, 16, v53
	v_and_b32_e32 v157, 0xffff0000, v53
	v_lshlrev_b32_e32 v158, 16, v54
	v_and_b32_e32 v159, 0xffff0000, v54
	v_lshlrev_b32_e32 v160, 16, v55
	v_and_b32_e32 v161, 0xffff0000, v55
	v_lshlrev_b32_e32 v162, 16, v56
	v_and_b32_e32 v163, 0xffff0000, v56
	v_lshlrev_b32_e32 v164, 16, v57
	v_and_b32_e32 v165, 0xffff0000, v57
	v_lshlrev_b32_e32 v166, 16, v58
	v_and_b32_e32 v167, 0xffff0000, v58
	v_lshlrev_b32_e32 v168, 16, v59
	v_and_b32_e32 v169, 0xffff0000, v59
	v_pk_add_f32 v[146:147], v[146:147], v[154:155]
	v_pk_add_f32 v[148:149], v[148:149], v[156:157]
	v_pk_add_f32 v[150:151], v[150:151], v[158:159]
	v_pk_add_f32 v[152:153], v[152:153], v[160:161]
	v_pk_mul_f32 v[170:171], v[162:163], v[162:163]
	v_pk_mul_f32 v[172:173], v[164:165], v[164:165]
	v_pk_mul_f32 v[174:175], v[166:167], v[166:167]
	v_pk_mul_f32 v[176:177], v[168:169], v[168:169]
	v_pk_fma_f32 v[170:171], v[170:171], v[140:141], v[142:143] op_sel_hi:[1,0,0]
	v_pk_fma_f32 v[172:173], v[172:173], v[140:141], v[142:143] op_sel_hi:[1,0,0]
	v_pk_fma_f32 v[174:175], v[174:175], v[140:141], v[142:143] op_sel_hi:[1,0,0]
	v_pk_fma_f32 v[176:177], v[176:177], v[140:141], v[142:143] op_sel_hi:[1,0,0]
	v_pk_mul_f32 v[170:171], v[170:171], v[162:163]
	v_pk_mul_f32 v[172:173], v[172:173], v[164:165]
	v_pk_mul_f32 v[174:175], v[174:175], v[166:167]
	v_pk_mul_f32 v[176:177], v[176:177], v[168:169]
	v_pk_mul_f32 v[154:155], v[146:147], v[162:163]
	v_pk_mul_f32 v[156:157], v[148:149], v[164:165]
	v_pk_mul_f32 v[158:159], v[150:151], v[166:167]
	v_pk_mul_f32 v[160:161], v[152:153], v[168:169]
	v_exp_f32_e32 v170, v170
	v_exp_f32_e32 v171, v171
	v_exp_f32_e32 v172, v172
	v_exp_f32_e32 v173, v173
	v_exp_f32_e32 v174, v174
	v_exp_f32_e32 v175, v175
	v_exp_f32_e32 v176, v176
	v_exp_f32_e32 v177, v177
	v_pk_add_f32 v[170:171], v[170:171], 1.0 op_sel_hi:[1,0]
	v_pk_add_f32 v[172:173], v[172:173], 1.0 op_sel_hi:[1,0]
	v_pk_add_f32 v[174:175], v[174:175], 1.0 op_sel_hi:[1,0]
	v_pk_add_f32 v[176:177], v[176:177], 1.0 op_sel_hi:[1,0]
	v_rcp_f32_e32 v170, v170
	v_rcp_f32_e32 v171, v171
	v_rcp_f32_e32 v172, v172
	v_rcp_f32_e32 v173, v173
	v_rcp_f32_e32 v174, v174
	v_rcp_f32_e32 v175, v175
	v_rcp_f32_e32 v176, v176
	v_rcp_f32_e32 v177, v177
	v_pk_mul_f32 v[96:97], v[154:155], v[170:171]
	v_pk_mul_f32 v[98:99], v[156:157], v[172:173]
	v_pk_mul_f32 v[100:101], v[158:159], v[174:175]
	v_pk_mul_f32 v[102:103], v[160:161], v[176:177]
	v_pk_mul_f32 v[112:113], v[96:97], v[96:97]
	v_pk_mul_f32 v[114:115], v[98:99], v[98:99]
	v_pk_fma_f32 v[112:113], v[100:101], v[100:101], v[112:113]
	v_pk_fma_f32 v[114:115], v[102:103], v[102:103], v[114:115]
	v_pk_add_f32 v[112:113], v[112:113], v[114:115]
	v_add_f32_e32 v112, v112, v113
	s_nop 1
	v_add_f32_dpp v112, v112, v112 quad_perm:[1,0,3,2] row_mask:0xf bank_mask:0xf
	s_nop 1
	v_add_f32_dpp v112, v112, v112 quad_perm:[2,3,0,1] row_mask:0xf bank_mask:0xf
	s_nop 1
	v_add_f32_dpp v112, v112, v112 row_half_mirror row_mask:0xf bank_mask:0xf
	s_nop 1
	v_add_f32_dpp v112, v112, v112 row_mirror row_mask:0xf bank_mask:0xf
	s_nop 1
	v_readlane_b32 s98, v112, 0
	v_readlane_b32 s99, v112, 16
	v_readlane_b32 s100, v112, 32
	v_readlane_b32 vcc_lo, v112, 48
	s_nop 1
	v_mov_b32_e32 v113, s98
	v_add_f32_e32 v113, s99, v113
	v_add_f32_e32 v113, s100, v113
	v_add_f32_e32 v113, vcc_lo, v113
	v_fmamk_f32 v144, v113, 0x3b000000, v131
	v_rsq_f32_e32 v144, v144
	s_nop 0
	v_pk_mul_f32 v[146:147], v[96:97], v[144:145] op_sel_hi:[1,0]
	v_pk_mul_f32 v[148:149], v[98:99], v[144:145] op_sel_hi:[1,0]
	v_pk_mul_f32 v[150:151], v[100:101], v[144:145] op_sel_hi:[1,0]
	v_pk_mul_f32 v[152:153], v[102:103], v[144:145] op_sel_hi:[1,0]
	v_pk_mul_f32 v[146:147], v[146:147], v[120:121]
	v_pk_mul_f32 v[148:149], v[148:149], v[122:123]
	v_pk_mul_f32 v[150:151], v[150:151], v[124:125]
	v_pk_mul_f32 v[152:153], v[152:153], v[126:127]
	v_cvt_pk_bf16_f32 v116, v146, v147
	v_cvt_pk_bf16_f32 v117, v148, v149
	v_cvt_pk_bf16_f32 v118, v150, v151
	v_cvt_pk_bf16_f32 v119, v152, v153
	v_add_u32_e32 v138, 0x1000000, v135
	global_store_dwordx4 v138, v[116:119], s[34:35]
	v_add_u32_e32 v136, 0x1800000, v133
	v_add_u32_e32 v137, 0x5400000, v134
	global_load_dwordx4 v[48:51], v136, s[22:23] nt
	global_load_dwordx4 v[52:55], v136, s[20:21] nt
	global_load_dwordx4 v[56:59], v137, s[38:39] nt
	s_waitcnt vmcnt(26)
	v_lshlrev_b32_e32 v146, 16, v60
	v_and_b32_e32 v147, 0xffff0000, v60
	v_lshlrev_b32_e32 v148, 16, v61
	v_and_b32_e32 v149, 0xffff0000, v61
	v_lshlrev_b32_e32 v150, 16, v62
	v_and_b32_e32 v151, 0xffff0000, v62
	v_lshlrev_b32_e32 v152, 16, v63
	v_and_b32_e32 v153, 0xffff0000, v63
	v_lshlrev_b32_e32 v154, 16, v64
	v_and_b32_e32 v155, 0xffff0000, v64
	v_lshlrev_b32_e32 v156, 16, v65
	v_and_b32_e32 v157, 0xffff0000, v65
	v_lshlrev_b32_e32 v158, 16, v66
	v_and_b32_e32 v159, 0xffff0000, v66
	v_lshlrev_b32_e32 v160, 16, v67
	v_and_b32_e32 v161, 0xffff0000, v67
	v_lshlrev_b32_e32 v162, 16, v68
	v_and_b32_e32 v163, 0xffff0000, v68
	v_lshlrev_b32_e32 v164, 16, v69
	v_and_b32_e32 v165, 0xffff0000, v69
	v_lshlrev_b32_e32 v166, 16, v70
	v_and_b32_e32 v167, 0xffff0000, v70
	v_lshlrev_b32_e32 v168, 16, v71
	v_and_b32_e32 v169, 0xffff0000, v71
	v_pk_add_f32 v[146:147], v[146:147], v[154:155]
	v_pk_add_f32 v[148:149], v[148:149], v[156:157]
	v_pk_add_f32 v[150:151], v[150:151], v[158:159]
	v_pk_add_f32 v[152:153], v[152:153], v[160:161]
	v_pk_mul_f32 v[170:171], v[162:163], v[162:163]
	v_pk_mul_f32 v[172:173], v[164:165], v[164:165]
	v_pk_mul_f32 v[174:175], v[166:167], v[166:167]
	v_pk_mul_f32 v[176:177], v[168:169], v[168:169]
	v_pk_fma_f32 v[170:171], v[170:171], v[140:141], v[142:143] op_sel_hi:[1,0,0]
	v_pk_fma_f32 v[172:173], v[172:173], v[140:141], v[142:143] op_sel_hi:[1,0,0]
	v_pk_fma_f32 v[174:175], v[174:175], v[140:141], v[142:143] op_sel_hi:[1,0,0]
	v_pk_fma_f32 v[176:177], v[176:177], v[140:141], v[142:143] op_sel_hi:[1,0,0]
	v_pk_mul_f32 v[170:171], v[170:171], v[162:163]
	v_pk_mul_f32 v[172:173], v[172:173], v[164:165]
	v_pk_mul_f32 v[174:175], v[174:175], v[166:167]
	v_pk_mul_f32 v[176:177], v[176:177], v[168:169]
	v_pk_mul_f32 v[154:155], v[146:147], v[162:163]
	v_pk_mul_f32 v[156:157], v[148:149], v[164:165]
	v_pk_mul_f32 v[158:159], v[150:151], v[166:167]
	v_pk_mul_f32 v[160:161], v[152:153], v[168:169]
	v_exp_f32_e32 v170, v170
	v_exp_f32_e32 v171, v171
	v_exp_f32_e32 v172, v172
	v_exp_f32_e32 v173, v173
	v_exp_f32_e32 v174, v174
	v_exp_f32_e32 v175, v175
	v_exp_f32_e32 v176, v176
	v_exp_f32_e32 v177, v177
	v_pk_add_f32 v[170:171], v[170:171], 1.0 op_sel_hi:[1,0]
	v_pk_add_f32 v[172:173], v[172:173], 1.0 op_sel_hi:[1,0]
	v_pk_add_f32 v[174:175], v[174:175], 1.0 op_sel_hi:[1,0]
	v_pk_add_f32 v[176:177], v[176:177], 1.0 op_sel_hi:[1,0]
	v_rcp_f32_e32 v170, v170
	v_rcp_f32_e32 v171, v171
	v_rcp_f32_e32 v172, v172
	v_rcp_f32_e32 v173, v173
	v_rcp_f32_e32 v174, v174
	v_rcp_f32_e32 v175, v175
	v_rcp_f32_e32 v176, v176
	v_rcp_f32_e32 v177, v177
	v_pk_mul_f32 v[96:97], v[154:155], v[170:171]
	v_pk_mul_f32 v[98:99], v[156:157], v[172:173]
	v_pk_mul_f32 v[100:101], v[158:159], v[174:175]
	v_pk_mul_f32 v[102:103], v[160:161], v[176:177]
	v_pk_mul_f32 v[112:113], v[96:97], v[96:97]
	v_pk_mul_f32 v[114:115], v[98:99], v[98:99]
	v_pk_fma_f32 v[112:113], v[100:101], v[100:101], v[112:113]
	v_pk_fma_f32 v[114:115], v[102:103], v[102:103], v[114:115]
	v_pk_add_f32 v[112:113], v[112:113], v[114:115]
	v_add_f32_e32 v112, v112, v113
	s_nop 1
	v_add_f32_dpp v112, v112, v112 quad_perm:[1,0,3,2] row_mask:0xf bank_mask:0xf
	s_nop 1
	v_add_f32_dpp v112, v112, v112 quad_perm:[2,3,0,1] row_mask:0xf bank_mask:0xf
	s_nop 1
	v_add_f32_dpp v112, v112, v112 row_half_mirror row_mask:0xf bank_mask:0xf
	s_nop 1
	v_add_f32_dpp v112, v112, v112 row_mirror row_mask:0xf bank_mask:0xf
	s_nop 1
	v_readlane_b32 s98, v112, 0
	v_readlane_b32 s99, v112, 16
	v_readlane_b32 s100, v112, 32
	v_readlane_b32 vcc_lo, v112, 48
	s_nop 1
	v_mov_b32_e32 v113, s98
	v_add_f32_e32 v113, s99, v113
	v_add_f32_e32 v113, s100, v113
	v_add_f32_e32 v113, vcc_lo, v113
	v_fmamk_f32 v144, v113, 0x3b000000, v131
	v_rsq_f32_e32 v144, v144
	s_nop 0
	v_pk_mul_f32 v[146:147], v[96:97], v[144:145] op_sel_hi:[1,0]
	v_pk_mul_f32 v[148:149], v[98:99], v[144:145] op_sel_hi:[1,0]
	v_pk_mul_f32 v[150:151], v[100:101], v[144:145] op_sel_hi:[1,0]
	v_pk_mul_f32 v[152:153], v[102:103], v[144:145] op_sel_hi:[1,0]
	v_pk_mul_f32 v[146:147], v[146:147], v[120:121]
	v_pk_mul_f32 v[148:149], v[148:149], v[122:123]
	v_pk_mul_f32 v[150:151], v[150:151], v[124:125]
	v_pk_mul_f32 v[152:153], v[152:153], v[126:127]
	v_cvt_pk_bf16_f32 v116, v146, v147
	v_cvt_pk_bf16_f32 v117, v148, v149
	v_cvt_pk_bf16_f32 v118, v150, v151
	v_cvt_pk_bf16_f32 v119, v152, v153
	v_add_u32_e32 v138, 0x1400000, v135
	global_store_dwordx4 v138, v[116:119], s[34:35]
	v_add_u32_e32 v136, 0x1a00000, v133
	v_add_u32_e32 v137, 0x5b00000, v134
	global_load_dwordx4 v[60:63], v136, s[22:23] nt
	global_load_dwordx4 v[64:67], v136, s[20:21] nt
	global_load_dwordx4 v[68:71], v137, s[38:39] nt
	s_waitcnt vmcnt(27)
	v_lshlrev_b32_e32 v146, 16, v72
	v_and_b32_e32 v147, 0xffff0000, v72
	v_lshlrev_b32_e32 v148, 16, v73
	v_and_b32_e32 v149, 0xffff0000, v73
	v_lshlrev_b32_e32 v150, 16, v74
	v_and_b32_e32 v151, 0xffff0000, v74
	v_lshlrev_b32_e32 v152, 16, v75
	v_and_b32_e32 v153, 0xffff0000, v75
	v_lshlrev_b32_e32 v154, 16, v76
	v_and_b32_e32 v155, 0xffff0000, v76
	v_lshlrev_b32_e32 v156, 16, v77
	v_and_b32_e32 v157, 0xffff0000, v77
	v_lshlrev_b32_e32 v158, 16, v78
	v_and_b32_e32 v159, 0xffff0000, v78
	v_lshlrev_b32_e32 v160, 16, v79
	v_and_b32_e32 v161, 0xffff0000, v79
	v_lshlrev_b32_e32 v162, 16, v80
	v_and_b32_e32 v163, 0xffff0000, v80
	v_lshlrev_b32_e32 v164, 16, v81
	v_and_b32_e32 v165, 0xffff0000, v81
	v_lshlrev_b32_e32 v166, 16, v82
	v_and_b32_e32 v167, 0xffff0000, v82
	v_lshlrev_b32_e32 v168, 16, v83
	v_and_b32_e32 v169, 0xffff0000, v83
	v_pk_add_f32 v[146:147], v[146:147], v[154:155]
	v_pk_add_f32 v[148:149], v[148:149], v[156:157]
	v_pk_add_f32 v[150:151], v[150:151], v[158:159]
	v_pk_add_f32 v[152:153], v[152:153], v[160:161]
	v_pk_mul_f32 v[170:171], v[162:163], v[162:163]
	v_pk_mul_f32 v[172:173], v[164:165], v[164:165]
	v_pk_mul_f32 v[174:175], v[166:167], v[166:167]
	v_pk_mul_f32 v[176:177], v[168:169], v[168:169]
	v_pk_fma_f32 v[170:171], v[170:171], v[140:141], v[142:143] op_sel_hi:[1,0,0]
	v_pk_fma_f32 v[172:173], v[172:173], v[140:141], v[142:143] op_sel_hi:[1,0,0]
	v_pk_fma_f32 v[174:175], v[174:175], v[140:141], v[142:143] op_sel_hi:[1,0,0]
	v_pk_fma_f32 v[176:177], v[176:177], v[140:141], v[142:143] op_sel_hi:[1,0,0]
	v_pk_mul_f32 v[170:171], v[170:171], v[162:163]
	v_pk_mul_f32 v[172:173], v[172:173], v[164:165]
	v_pk_mul_f32 v[174:175], v[174:175], v[166:167]
	v_pk_mul_f32 v[176:177], v[176:177], v[168:169]
	v_pk_mul_f32 v[154:155], v[146:147], v[162:163]
	v_pk_mul_f32 v[156:157], v[148:149], v[164:165]
	v_pk_mul_f32 v[158:159], v[150:151], v[166:167]
	v_pk_mul_f32 v[160:161], v[152:153], v[168:169]
	v_exp_f32_e32 v170, v170
	v_exp_f32_e32 v171, v171
	v_exp_f32_e32 v172, v172
	v_exp_f32_e32 v173, v173
	v_exp_f32_e32 v174, v174
	v_exp_f32_e32 v175, v175
	v_exp_f32_e32 v176, v176
	v_exp_f32_e32 v177, v177
	v_pk_add_f32 v[170:171], v[170:171], 1.0 op_sel_hi:[1,0]
	v_pk_add_f32 v[172:173], v[172:173], 1.0 op_sel_hi:[1,0]
	v_pk_add_f32 v[174:175], v[174:175], 1.0 op_sel_hi:[1,0]
	v_pk_add_f32 v[176:177], v[176:177], 1.0 op_sel_hi:[1,0]
	v_rcp_f32_e32 v170, v170
	v_rcp_f32_e32 v171, v171
	v_rcp_f32_e32 v172, v172
	v_rcp_f32_e32 v173, v173
	v_rcp_f32_e32 v174, v174
	v_rcp_f32_e32 v175, v175
	v_rcp_f32_e32 v176, v176
	v_rcp_f32_e32 v177, v177
	v_pk_mul_f32 v[96:97], v[154:155], v[170:171]
	v_pk_mul_f32 v[98:99], v[156:157], v[172:173]
	v_pk_mul_f32 v[100:101], v[158:159], v[174:175]
	v_pk_mul_f32 v[102:103], v[160:161], v[176:177]
	v_pk_mul_f32 v[112:113], v[96:97], v[96:97]
	v_pk_mul_f32 v[114:115], v[98:99], v[98:99]
	v_pk_fma_f32 v[112:113], v[100:101], v[100:101], v[112:113]
	v_pk_fma_f32 v[114:115], v[102:103], v[102:103], v[114:115]
	v_pk_add_f32 v[112:113], v[112:113], v[114:115]
	v_add_f32_e32 v112, v112, v113
	s_nop 1
	v_add_f32_dpp v112, v112, v112 quad_perm:[1,0,3,2] row_mask:0xf bank_mask:0xf
	s_nop 1
	v_add_f32_dpp v112, v112, v112 quad_perm:[2,3,0,1] row_mask:0xf bank_mask:0xf
	s_nop 1
	v_add_f32_dpp v112, v112, v112 row_half_mirror row_mask:0xf bank_mask:0xf
	s_nop 1
	v_add_f32_dpp v112, v112, v112 row_mirror row_mask:0xf bank_mask:0xf
	s_nop 1
	v_readlane_b32 s98, v112, 0
	v_readlane_b32 s99, v112, 16
	v_readlane_b32 s100, v112, 32
	v_readlane_b32 vcc_lo, v112, 48
	s_nop 1
	v_mov_b32_e32 v113, s98
	v_add_f32_e32 v113, s99, v113
	v_add_f32_e32 v113, s100, v113
	v_add_f32_e32 v113, vcc_lo, v113
	v_fmamk_f32 v144, v113, 0x3b000000, v131
	v_rsq_f32_e32 v144, v144
	s_nop 0
	v_pk_mul_f32 v[146:147], v[96:97], v[144:145] op_sel_hi:[1,0]
	v_pk_mul_f32 v[148:149], v[98:99], v[144:145] op_sel_hi:[1,0]
	v_pk_mul_f32 v[150:151], v[100:101], v[144:145] op_sel_hi:[1,0]
	v_pk_mul_f32 v[152:153], v[102:103], v[144:145] op_sel_hi:[1,0]
	v_pk_mul_f32 v[146:147], v[146:147], v[120:121]
	v_pk_mul_f32 v[148:149], v[148:149], v[122:123]
	v_pk_mul_f32 v[150:151], v[150:151], v[124:125]
	v_pk_mul_f32 v[152:153], v[152:153], v[126:127]
	v_cvt_pk_bf16_f32 v116, v146, v147
	v_cvt_pk_bf16_f32 v117, v148, v149
	v_cvt_pk_bf16_f32 v118, v150, v151
	v_cvt_pk_bf16_f32 v119, v152, v153
	v_add_u32_e32 v138, 0x1800000, v135
	global_store_dwordx4 v138, v[116:119], s[34:35]
	v_add_u32_e32 v136, 0x1c00000, v133
	v_add_u32_e32 v137, 0x6200000, v134
	global_load_dwordx4 v[72:75], v136, s[22:23] nt
	global_load_dwordx4 v[76:79], v136, s[20:21] nt
	global_load_dwordx4 v[80:83], v137, s[38:39] nt
	s_waitcnt vmcnt(28)
	v_lshlrev_b32_e32 v146, 16, v84
	v_and_b32_e32 v147, 0xffff0000, v84
	v_lshlrev_b32_e32 v148, 16, v85
	v_and_b32_e32 v149, 0xffff0000, v85
	v_lshlrev_b32_e32 v150, 16, v86
	v_and_b32_e32 v151, 0xffff0000, v86
	v_lshlrev_b32_e32 v152, 16, v87
	v_and_b32_e32 v153, 0xffff0000, v87
	v_lshlrev_b32_e32 v154, 16, v88
	v_and_b32_e32 v155, 0xffff0000, v88
	v_lshlrev_b32_e32 v156, 16, v89
	v_and_b32_e32 v157, 0xffff0000, v89
	v_lshlrev_b32_e32 v158, 16, v90
	v_and_b32_e32 v159, 0xffff0000, v90
	v_lshlrev_b32_e32 v160, 16, v91
	v_and_b32_e32 v161, 0xffff0000, v91
	v_lshlrev_b32_e32 v162, 16, v92
	v_and_b32_e32 v163, 0xffff0000, v92
	v_lshlrev_b32_e32 v164, 16, v93
	v_and_b32_e32 v165, 0xffff0000, v93
	v_lshlrev_b32_e32 v166, 16, v94
	v_and_b32_e32 v167, 0xffff0000, v94
	v_lshlrev_b32_e32 v168, 16, v95
	v_and_b32_e32 v169, 0xffff0000, v95
	v_pk_add_f32 v[146:147], v[146:147], v[154:155]
	v_pk_add_f32 v[148:149], v[148:149], v[156:157]
	v_pk_add_f32 v[150:151], v[150:151], v[158:159]
	v_pk_add_f32 v[152:153], v[152:153], v[160:161]
	v_pk_mul_f32 v[170:171], v[162:163], v[162:163]
	v_pk_mul_f32 v[172:173], v[164:165], v[164:165]
	v_pk_mul_f32 v[174:175], v[166:167], v[166:167]
	v_pk_mul_f32 v[176:177], v[168:169], v[168:169]
	v_pk_fma_f32 v[170:171], v[170:171], v[140:141], v[142:143] op_sel_hi:[1,0,0]
	v_pk_fma_f32 v[172:173], v[172:173], v[140:141], v[142:143] op_sel_hi:[1,0,0]
	v_pk_fma_f32 v[174:175], v[174:175], v[140:141], v[142:143] op_sel_hi:[1,0,0]
	v_pk_fma_f32 v[176:177], v[176:177], v[140:141], v[142:143] op_sel_hi:[1,0,0]
	v_pk_mul_f32 v[170:171], v[170:171], v[162:163]
	v_pk_mul_f32 v[172:173], v[172:173], v[164:165]
	v_pk_mul_f32 v[174:175], v[174:175], v[166:167]
	v_pk_mul_f32 v[176:177], v[176:177], v[168:169]
	v_pk_mul_f32 v[154:155], v[146:147], v[162:163]
	v_pk_mul_f32 v[156:157], v[148:149], v[164:165]
	v_pk_mul_f32 v[158:159], v[150:151], v[166:167]
	v_pk_mul_f32 v[160:161], v[152:153], v[168:169]
	v_exp_f32_e32 v170, v170
	v_exp_f32_e32 v171, v171
	v_exp_f32_e32 v172, v172
	v_exp_f32_e32 v173, v173
	v_exp_f32_e32 v174, v174
	v_exp_f32_e32 v175, v175
	v_exp_f32_e32 v176, v176
	v_exp_f32_e32 v177, v177
	v_pk_add_f32 v[170:171], v[170:171], 1.0 op_sel_hi:[1,0]
	v_pk_add_f32 v[172:173], v[172:173], 1.0 op_sel_hi:[1,0]
	v_pk_add_f32 v[174:175], v[174:175], 1.0 op_sel_hi:[1,0]
	v_pk_add_f32 v[176:177], v[176:177], 1.0 op_sel_hi:[1,0]
	v_rcp_f32_e32 v170, v170
	v_rcp_f32_e32 v171, v171
	v_rcp_f32_e32 v172, v172
	v_rcp_f32_e32 v173, v173
	v_rcp_f32_e32 v174, v174
	v_rcp_f32_e32 v175, v175
	v_rcp_f32_e32 v176, v176
	v_rcp_f32_e32 v177, v177
	v_pk_mul_f32 v[96:97], v[154:155], v[170:171]
	v_pk_mul_f32 v[98:99], v[156:157], v[172:173]
	v_pk_mul_f32 v[100:101], v[158:159], v[174:175]
	v_pk_mul_f32 v[102:103], v[160:161], v[176:177]
	v_pk_mul_f32 v[112:113], v[96:97], v[96:97]
	v_pk_mul_f32 v[114:115], v[98:99], v[98:99]
	v_pk_fma_f32 v[112:113], v[100:101], v[100:101], v[112:113]
	v_pk_fma_f32 v[114:115], v[102:103], v[102:103], v[114:115]
	v_pk_add_f32 v[112:113], v[112:113], v[114:115]
	v_add_f32_e32 v112, v112, v113
	s_nop 1
	v_add_f32_dpp v112, v112, v112 quad_perm:[1,0,3,2] row_mask:0xf bank_mask:0xf
	s_nop 1
	v_add_f32_dpp v112, v112, v112 quad_perm:[2,3,0,1] row_mask:0xf bank_mask:0xf
	s_nop 1
	v_add_f32_dpp v112, v112, v112 row_half_mirror row_mask:0xf bank_mask:0xf
	s_nop 1
	v_add_f32_dpp v112, v112, v112 row_mirror row_mask:0xf bank_mask:0xf
	s_nop 1
	v_readlane_b32 s98, v112, 0
	v_readlane_b32 s99, v112, 16
	v_readlane_b32 s100, v112, 32
	v_readlane_b32 vcc_lo, v112, 48
	s_nop 1
	v_mov_b32_e32 v113, s98
	v_add_f32_e32 v113, s99, v113
	v_add_f32_e32 v113, s100, v113
	v_add_f32_e32 v113, vcc_lo, v113
	v_fmamk_f32 v144, v113, 0x3b000000, v131
	v_rsq_f32_e32 v144, v144
	s_nop 0
	v_pk_mul_f32 v[146:147], v[96:97], v[144:145] op_sel_hi:[1,0]
	v_pk_mul_f32 v[148:149], v[98:99], v[144:145] op_sel_hi:[1,0]
	v_pk_mul_f32 v[150:151], v[100:101], v[144:145] op_sel_hi:[1,0]
	v_pk_mul_f32 v[152:153], v[102:103], v[144:145] op_sel_hi:[1,0]
	v_pk_mul_f32 v[146:147], v[146:147], v[120:121]
	v_pk_mul_f32 v[148:149], v[148:149], v[122:123]
	v_pk_mul_f32 v[150:151], v[150:151], v[124:125]
	v_pk_mul_f32 v[152:153], v[152:153], v[126:127]
	v_cvt_pk_bf16_f32 v116, v146, v147
	v_cvt_pk_bf16_f32 v117, v148, v149
	v_cvt_pk_bf16_f32 v118, v150, v151
	v_cvt_pk_bf16_f32 v119, v152, v153
	v_add_u32_e32 v138, 0x1c00000, v135
	global_store_dwordx4 v138, v[116:119], s[34:35]
	v_add_u32_e32 v136, 0x1e00000, v133
	v_add_u32_e32 v137, 0x6900000, v134
	global_load_dwordx4 v[84:87], v136, s[22:23] nt
	global_load_dwordx4 v[88:91], v136, s[20:21] nt
	global_load_dwordx4 v[92:95], v137, s[38:39] nt
	s_waitcnt vmcnt(28)
	v_lshlrev_b32_e32 v146, 16, v0
	v_and_b32_e32 v147, 0xffff0000, v0
	v_lshlrev_b32_e32 v148, 16, v1
	v_and_b32_e32 v149, 0xffff0000, v1
	v_lshlrev_b32_e32 v150, 16, v2
	v_and_b32_e32 v151, 0xffff0000, v2
	v_lshlrev_b32_e32 v152, 16, v3
	v_and_b32_e32 v153, 0xffff0000, v3
	v_lshlrev_b32_e32 v154, 16, v4
	v_and_b32_e32 v155, 0xffff0000, v4
	v_lshlrev_b32_e32 v156, 16, v5
	v_and_b32_e32 v157, 0xffff0000, v5
	v_lshlrev_b32_e32 v158, 16, v6
	v_and_b32_e32 v159, 0xffff0000, v6
	v_lshlrev_b32_e32 v160, 16, v7
	v_and_b32_e32 v161, 0xffff0000, v7
	v_lshlrev_b32_e32 v162, 16, v8
	v_and_b32_e32 v163, 0xffff0000, v8
	v_lshlrev_b32_e32 v164, 16, v9
	v_and_b32_e32 v165, 0xffff0000, v9
	v_lshlrev_b32_e32 v166, 16, v10
	v_and_b32_e32 v167, 0xffff0000, v10
	v_lshlrev_b32_e32 v168, 16, v11
	v_and_b32_e32 v169, 0xffff0000, v11
	v_pk_add_f32 v[146:147], v[146:147], v[154:155]
	v_pk_add_f32 v[148:149], v[148:149], v[156:157]
	v_pk_add_f32 v[150:151], v[150:151], v[158:159]
	v_pk_add_f32 v[152:153], v[152:153], v[160:161]
	v_pk_mul_f32 v[170:171], v[162:163], v[162:163]
	v_pk_mul_f32 v[172:173], v[164:165], v[164:165]
	v_pk_mul_f32 v[174:175], v[166:167], v[166:167]
	v_pk_mul_f32 v[176:177], v[168:169], v[168:169]
	v_pk_fma_f32 v[170:171], v[170:171], v[140:141], v[142:143] op_sel_hi:[1,0,0]
	v_pk_fma_f32 v[172:173], v[172:173], v[140:141], v[142:143] op_sel_hi:[1,0,0]
	v_pk_fma_f32 v[174:175], v[174:175], v[140:141], v[142:143] op_sel_hi:[1,0,0]
	v_pk_fma_f32 v[176:177], v[176:177], v[140:141], v[142:143] op_sel_hi:[1,0,0]
	v_pk_mul_f32 v[170:171], v[170:171], v[162:163]
	v_pk_mul_f32 v[172:173], v[172:173], v[164:165]
	v_pk_mul_f32 v[174:175], v[174:175], v[166:167]
	v_pk_mul_f32 v[176:177], v[176:177], v[168:169]
	v_pk_mul_f32 v[154:155], v[146:147], v[162:163]
	v_pk_mul_f32 v[156:157], v[148:149], v[164:165]
	v_pk_mul_f32 v[158:159], v[150:151], v[166:167]
	v_pk_mul_f32 v[160:161], v[152:153], v[168:169]
	v_exp_f32_e32 v170, v170
	v_exp_f32_e32 v171, v171
	v_exp_f32_e32 v172, v172
	v_exp_f32_e32 v173, v173
	v_exp_f32_e32 v174, v174
	v_exp_f32_e32 v175, v175
	v_exp_f32_e32 v176, v176
	v_exp_f32_e32 v177, v177
	v_pk_add_f32 v[170:171], v[170:171], 1.0 op_sel_hi:[1,0]
	v_pk_add_f32 v[172:173], v[172:173], 1.0 op_sel_hi:[1,0]
	v_pk_add_f32 v[174:175], v[174:175], 1.0 op_sel_hi:[1,0]
	v_pk_add_f32 v[176:177], v[176:177], 1.0 op_sel_hi:[1,0]
	v_rcp_f32_e32 v170, v170
	v_rcp_f32_e32 v171, v171
	v_rcp_f32_e32 v172, v172
	v_rcp_f32_e32 v173, v173
	v_rcp_f32_e32 v174, v174
	v_rcp_f32_e32 v175, v175
	v_rcp_f32_e32 v176, v176
	v_rcp_f32_e32 v177, v177
	v_pk_mul_f32 v[96:97], v[154:155], v[170:171]
	v_pk_mul_f32 v[98:99], v[156:157], v[172:173]
	v_pk_mul_f32 v[100:101], v[158:159], v[174:175]
	v_pk_mul_f32 v[102:103], v[160:161], v[176:177]
	v_pk_mul_f32 v[112:113], v[96:97], v[96:97]
	v_pk_mul_f32 v[114:115], v[98:99], v[98:99]
	v_pk_fma_f32 v[112:113], v[100:101], v[100:101], v[112:113]
	v_pk_fma_f32 v[114:115], v[102:103], v[102:103], v[114:115]
	v_pk_add_f32 v[112:113], v[112:113], v[114:115]
	v_add_f32_e32 v112, v112, v113
	s_nop 1
	v_add_f32_dpp v112, v112, v112 quad_perm:[1,0,3,2] row_mask:0xf bank_mask:0xf
	s_nop 1
	v_add_f32_dpp v112, v112, v112 quad_perm:[2,3,0,1] row_mask:0xf bank_mask:0xf
	s_nop 1
	v_add_f32_dpp v112, v112, v112 row_half_mirror row_mask:0xf bank_mask:0xf
	s_nop 1
	v_add_f32_dpp v112, v112, v112 row_mirror row_mask:0xf bank_mask:0xf
	s_nop 1
	v_readlane_b32 s98, v112, 0
	v_readlane_b32 s99, v112, 16
	v_readlane_b32 s100, v112, 32
	v_readlane_b32 vcc_lo, v112, 48
	s_nop 1
	v_mov_b32_e32 v113, s98
	v_add_f32_e32 v113, s99, v113
	v_add_f32_e32 v113, s100, v113
	v_add_f32_e32 v113, vcc_lo, v113
	v_fmamk_f32 v144, v113, 0x3b000000, v131
	v_rsq_f32_e32 v144, v144
	s_nop 0
	v_pk_mul_f32 v[146:147], v[96:97], v[144:145] op_sel_hi:[1,0]
	v_pk_mul_f32 v[148:149], v[98:99], v[144:145] op_sel_hi:[1,0]
	v_pk_mul_f32 v[150:151], v[100:101], v[144:145] op_sel_hi:[1,0]
	v_pk_mul_f32 v[152:153], v[102:103], v[144:145] op_sel_hi:[1,0]
	v_pk_mul_f32 v[146:147], v[146:147], v[120:121]
	v_pk_mul_f32 v[148:149], v[148:149], v[122:123]
	v_pk_mul_f32 v[150:151], v[150:151], v[124:125]
	v_pk_mul_f32 v[152:153], v[152:153], v[126:127]
	v_cvt_pk_bf16_f32 v116, v146, v147
	v_cvt_pk_bf16_f32 v117, v148, v149
	v_cvt_pk_bf16_f32 v118, v150, v151
	v_cvt_pk_bf16_f32 v119, v152, v153
	v_add_u32_e32 v138, 0x2000000, v135
	global_store_dwordx4 v138, v[116:119], s[34:35]
	s_waitcnt vmcnt(25)
	v_lshlrev_b32_e32 v146, 16, v12
	v_and_b32_e32 v147, 0xffff0000, v12
	v_lshlrev_b32_e32 v148, 16, v13
	v_and_b32_e32 v149, 0xffff0000, v13
	v_lshlrev_b32_e32 v150, 16, v14
	v_and_b32_e32 v151, 0xffff0000, v14
	v_lshlrev_b32_e32 v152, 16, v15
	v_and_b32_e32 v153, 0xffff0000, v15
	v_lshlrev_b32_e32 v154, 16, v16
	v_and_b32_e32 v155, 0xffff0000, v16
	v_lshlrev_b32_e32 v156, 16, v17
	v_and_b32_e32 v157, 0xffff0000, v17
	v_lshlrev_b32_e32 v158, 16, v18
	v_and_b32_e32 v159, 0xffff0000, v18
	v_lshlrev_b32_e32 v160, 16, v19
	v_and_b32_e32 v161, 0xffff0000, v19
	v_lshlrev_b32_e32 v162, 16, v20
	v_and_b32_e32 v163, 0xffff0000, v20
	v_lshlrev_b32_e32 v164, 16, v21
	v_and_b32_e32 v165, 0xffff0000, v21
	v_lshlrev_b32_e32 v166, 16, v22
	v_and_b32_e32 v167, 0xffff0000, v22
	v_lshlrev_b32_e32 v168, 16, v23
	v_and_b32_e32 v169, 0xffff0000, v23
	v_pk_add_f32 v[146:147], v[146:147], v[154:155]
	v_pk_add_f32 v[148:149], v[148:149], v[156:157]
	v_pk_add_f32 v[150:151], v[150:151], v[158:159]
	v_pk_add_f32 v[152:153], v[152:153], v[160:161]
	v_pk_mul_f32 v[170:171], v[162:163], v[162:163]
	v_pk_mul_f32 v[172:173], v[164:165], v[164:165]
	v_pk_mul_f32 v[174:175], v[166:167], v[166:167]
	v_pk_mul_f32 v[176:177], v[168:169], v[168:169]
	v_pk_fma_f32 v[170:171], v[170:171], v[140:141], v[142:143] op_sel_hi:[1,0,0]
	v_pk_fma_f32 v[172:173], v[172:173], v[140:141], v[142:143] op_sel_hi:[1,0,0]
	v_pk_fma_f32 v[174:175], v[174:175], v[140:141], v[142:143] op_sel_hi:[1,0,0]
	v_pk_fma_f32 v[176:177], v[176:177], v[140:141], v[142:143] op_sel_hi:[1,0,0]
	v_pk_mul_f32 v[170:171], v[170:171], v[162:163]
	v_pk_mul_f32 v[172:173], v[172:173], v[164:165]
	v_pk_mul_f32 v[174:175], v[174:175], v[166:167]
	v_pk_mul_f32 v[176:177], v[176:177], v[168:169]
	v_pk_mul_f32 v[154:155], v[146:147], v[162:163]
	v_pk_mul_f32 v[156:157], v[148:149], v[164:165]
	v_pk_mul_f32 v[158:159], v[150:151], v[166:167]
	v_pk_mul_f32 v[160:161], v[152:153], v[168:169]
	v_exp_f32_e32 v170, v170
	v_exp_f32_e32 v171, v171
	v_exp_f32_e32 v172, v172
	v_exp_f32_e32 v173, v173
	v_exp_f32_e32 v174, v174
	v_exp_f32_e32 v175, v175
	v_exp_f32_e32 v176, v176
	v_exp_f32_e32 v177, v177
	v_pk_add_f32 v[170:171], v[170:171], 1.0 op_sel_hi:[1,0]
	v_pk_add_f32 v[172:173], v[172:173], 1.0 op_sel_hi:[1,0]
	v_pk_add_f32 v[174:175], v[174:175], 1.0 op_sel_hi:[1,0]
	v_pk_add_f32 v[176:177], v[176:177], 1.0 op_sel_hi:[1,0]
	v_rcp_f32_e32 v170, v170
	v_rcp_f32_e32 v171, v171
	v_rcp_f32_e32 v172, v172
	v_rcp_f32_e32 v173, v173
	v_rcp_f32_e32 v174, v174
	v_rcp_f32_e32 v175, v175
	v_rcp_f32_e32 v176, v176
	v_rcp_f32_e32 v177, v177
	v_pk_mul_f32 v[96:97], v[154:155], v[170:171]
	v_pk_mul_f32 v[98:99], v[156:157], v[172:173]
	v_pk_mul_f32 v[100:101], v[158:159], v[174:175]
	v_pk_mul_f32 v[102:103], v[160:161], v[176:177]
	v_pk_mul_f32 v[112:113], v[96:97], v[96:97]
	v_pk_mul_f32 v[114:115], v[98:99], v[98:99]
	v_pk_fma_f32 v[112:113], v[100:101], v[100:101], v[112:113]
	v_pk_fma_f32 v[114:115], v[102:103], v[102:103], v[114:115]
	v_pk_add_f32 v[112:113], v[112:113], v[114:115]
	v_add_f32_e32 v112, v112, v113
	s_nop 1
	v_add_f32_dpp v112, v112, v112 quad_perm:[1,0,3,2] row_mask:0xf bank_mask:0xf
	s_nop 1
	v_add_f32_dpp v112, v112, v112 quad_perm:[2,3,0,1] row_mask:0xf bank_mask:0xf
	s_nop 1
	v_add_f32_dpp v112, v112, v112 row_half_mirror row_mask:0xf bank_mask:0xf
	s_nop 1
	v_add_f32_dpp v112, v112, v112 row_mirror row_mask:0xf bank_mask:0xf
	s_nop 1
	v_readlane_b32 s98, v112, 0
	v_readlane_b32 s99, v112, 16
	v_readlane_b32 s100, v112, 32
	v_readlane_b32 vcc_lo, v112, 48
	s_nop 1
	v_mov_b32_e32 v113, s98
	v_add_f32_e32 v113, s99, v113
	v_add_f32_e32 v113, s100, v113
	v_add_f32_e32 v113, vcc_lo, v113
	v_fmamk_f32 v144, v113, 0x3b000000, v131
	v_rsq_f32_e32 v144, v144
	s_nop 0
	v_pk_mul_f32 v[146:147], v[96:97], v[144:145] op_sel_hi:[1,0]
	v_pk_mul_f32 v[148:149], v[98:99], v[144:145] op_sel_hi:[1,0]
	v_pk_mul_f32 v[150:151], v[100:101], v[144:145] op_sel_hi:[1,0]
	v_pk_mul_f32 v[152:153], v[102:103], v[144:145] op_sel_hi:[1,0]
	v_pk_mul_f32 v[146:147], v[146:147], v[120:121]
	v_pk_mul_f32 v[148:149], v[148:149], v[122:123]
	v_pk_mul_f32 v[150:151], v[150:151], v[124:125]
	v_pk_mul_f32 v[152:153], v[152:153], v[126:127]
	v_cvt_pk_bf16_f32 v116, v146, v147
	v_cvt_pk_bf16_f32 v117, v148, v149
	v_cvt_pk_bf16_f32 v118, v150, v151
	v_cvt_pk_bf16_f32 v119, v152, v153
	v_add_u32_e32 v138, 0x2400000, v135
	global_store_dwordx4 v138, v[116:119], s[34:35]
	s_waitcnt vmcnt(22)
	v_lshlrev_b32_e32 v146, 16, v24
	v_and_b32_e32 v147, 0xffff0000, v24
	v_lshlrev_b32_e32 v148, 16, v25
	v_and_b32_e32 v149, 0xffff0000, v25
	v_lshlrev_b32_e32 v150, 16, v26
	v_and_b32_e32 v151, 0xffff0000, v26
	v_lshlrev_b32_e32 v152, 16, v27
	v_and_b32_e32 v153, 0xffff0000, v27
	v_lshlrev_b32_e32 v154, 16, v28
	v_and_b32_e32 v155, 0xffff0000, v28
	v_lshlrev_b32_e32 v156, 16, v29
	v_and_b32_e32 v157, 0xffff0000, v29
	v_lshlrev_b32_e32 v158, 16, v30
	v_and_b32_e32 v159, 0xffff0000, v30
	v_lshlrev_b32_e32 v160, 16, v31
	v_and_b32_e32 v161, 0xffff0000, v31
	v_lshlrev_b32_e32 v162, 16, v32
	v_and_b32_e32 v163, 0xffff0000, v32
	v_lshlrev_b32_e32 v164, 16, v33
	v_and_b32_e32 v165, 0xffff0000, v33
	v_lshlrev_b32_e32 v166, 16, v34
	v_and_b32_e32 v167, 0xffff0000, v34
	v_lshlrev_b32_e32 v168, 16, v35
	v_and_b32_e32 v169, 0xffff0000, v35
	v_pk_add_f32 v[146:147], v[146:147], v[154:155]
	v_pk_add_f32 v[148:149], v[148:149], v[156:157]
	v_pk_add_f32 v[150:151], v[150:151], v[158:159]
	v_pk_add_f32 v[152:153], v[152:153], v[160:161]
	v_pk_mul_f32 v[170:171], v[162:163], v[162:163]
	v_pk_mul_f32 v[172:173], v[164:165], v[164:165]
	v_pk_mul_f32 v[174:175], v[166:167], v[166:167]
	v_pk_mul_f32 v[176:177], v[168:169], v[168:169]
	v_pk_fma_f32 v[170:171], v[170:171], v[140:141], v[142:143] op_sel_hi:[1,0,0]
	v_pk_fma_f32 v[172:173], v[172:173], v[140:141], v[142:143] op_sel_hi:[1,0,0]
	v_pk_fma_f32 v[174:175], v[174:175], v[140:141], v[142:143] op_sel_hi:[1,0,0]
	v_pk_fma_f32 v[176:177], v[176:177], v[140:141], v[142:143] op_sel_hi:[1,0,0]
	v_pk_mul_f32 v[170:171], v[170:171], v[162:163]
	v_pk_mul_f32 v[172:173], v[172:173], v[164:165]
	v_pk_mul_f32 v[174:175], v[174:175], v[166:167]
	v_pk_mul_f32 v[176:177], v[176:177], v[168:169]
	v_pk_mul_f32 v[154:155], v[146:147], v[162:163]
	v_pk_mul_f32 v[156:157], v[148:149], v[164:165]
	v_pk_mul_f32 v[158:159], v[150:151], v[166:167]
	v_pk_mul_f32 v[160:161], v[152:153], v[168:169]
	v_exp_f32_e32 v170, v170
	v_exp_f32_e32 v171, v171
	v_exp_f32_e32 v172, v172
	v_exp_f32_e32 v173, v173
	v_exp_f32_e32 v174, v174
	v_exp_f32_e32 v175, v175
	v_exp_f32_e32 v176, v176
	v_exp_f32_e32 v177, v177
	v_pk_add_f32 v[170:171], v[170:171], 1.0 op_sel_hi:[1,0]
	v_pk_add_f32 v[172:173], v[172:173], 1.0 op_sel_hi:[1,0]
	v_pk_add_f32 v[174:175], v[174:175], 1.0 op_sel_hi:[1,0]
	v_pk_add_f32 v[176:177], v[176:177], 1.0 op_sel_hi:[1,0]
	v_rcp_f32_e32 v170, v170
	v_rcp_f32_e32 v171, v171
	v_rcp_f32_e32 v172, v172
	v_rcp_f32_e32 v173, v173
	v_rcp_f32_e32 v174, v174
	v_rcp_f32_e32 v175, v175
	v_rcp_f32_e32 v176, v176
	v_rcp_f32_e32 v177, v177
	v_pk_mul_f32 v[96:97], v[154:155], v[170:171]
	v_pk_mul_f32 v[98:99], v[156:157], v[172:173]
	v_pk_mul_f32 v[100:101], v[158:159], v[174:175]
	v_pk_mul_f32 v[102:103], v[160:161], v[176:177]
	v_pk_mul_f32 v[112:113], v[96:97], v[96:97]
	v_pk_mul_f32 v[114:115], v[98:99], v[98:99]
	v_pk_fma_f32 v[112:113], v[100:101], v[100:101], v[112:113]
	v_pk_fma_f32 v[114:115], v[102:103], v[102:103], v[114:115]
	v_pk_add_f32 v[112:113], v[112:113], v[114:115]
	v_add_f32_e32 v112, v112, v113
	s_nop 1
	v_add_f32_dpp v112, v112, v112 quad_perm:[1,0,3,2] row_mask:0xf bank_mask:0xf
	s_nop 1
	v_add_f32_dpp v112, v112, v112 quad_perm:[2,3,0,1] row_mask:0xf bank_mask:0xf
	s_nop 1
	v_add_f32_dpp v112, v112, v112 row_half_mirror row_mask:0xf bank_mask:0xf
	s_nop 1
	v_add_f32_dpp v112, v112, v112 row_mirror row_mask:0xf bank_mask:0xf
	s_nop 1
	v_readlane_b32 s98, v112, 0
	v_readlane_b32 s99, v112, 16
	v_readlane_b32 s100, v112, 32
	v_readlane_b32 vcc_lo, v112, 48
	s_nop 1
	v_mov_b32_e32 v113, s98
	v_add_f32_e32 v113, s99, v113
	v_add_f32_e32 v113, s100, v113
	v_add_f32_e32 v113, vcc_lo, v113
	v_fmamk_f32 v144, v113, 0x3b000000, v131
	v_rsq_f32_e32 v144, v144
	s_nop 0
	v_pk_mul_f32 v[146:147], v[96:97], v[144:145] op_sel_hi:[1,0]
	v_pk_mul_f32 v[148:149], v[98:99], v[144:145] op_sel_hi:[1,0]
	v_pk_mul_f32 v[150:151], v[100:101], v[144:145] op_sel_hi:[1,0]
	v_pk_mul_f32 v[152:153], v[102:103], v[144:145] op_sel_hi:[1,0]
	v_pk_mul_f32 v[146:147], v[146:147], v[120:121]
	v_pk_mul_f32 v[148:149], v[148:149], v[122:123]
	v_pk_mul_f32 v[150:151], v[150:151], v[124:125]
	v_pk_mul_f32 v[152:153], v[152:153], v[126:127]
	v_cvt_pk_bf16_f32 v116, v146, v147
	v_cvt_pk_bf16_f32 v117, v148, v149
	v_cvt_pk_bf16_f32 v118, v150, v151
	v_cvt_pk_bf16_f32 v119, v152, v153
	v_add_u32_e32 v138, 0x2800000, v135
	global_store_dwordx4 v138, v[116:119], s[34:35]
	s_waitcnt vmcnt(19)
	v_lshlrev_b32_e32 v146, 16, v36
	v_and_b32_e32 v147, 0xffff0000, v36
	v_lshlrev_b32_e32 v148, 16, v37
	v_and_b32_e32 v149, 0xffff0000, v37
	v_lshlrev_b32_e32 v150, 16, v38
	v_and_b32_e32 v151, 0xffff0000, v38
	v_lshlrev_b32_e32 v152, 16, v39
	v_and_b32_e32 v153, 0xffff0000, v39
	v_lshlrev_b32_e32 v154, 16, v40
	v_and_b32_e32 v155, 0xffff0000, v40
	v_lshlrev_b32_e32 v156, 16, v41
	v_and_b32_e32 v157, 0xffff0000, v41
	v_lshlrev_b32_e32 v158, 16, v42
	v_and_b32_e32 v159, 0xffff0000, v42
	v_lshlrev_b32_e32 v160, 16, v43
	v_and_b32_e32 v161, 0xffff0000, v43
	v_lshlrev_b32_e32 v162, 16, v44
	v_and_b32_e32 v163, 0xffff0000, v44
	v_lshlrev_b32_e32 v164, 16, v45
	v_and_b32_e32 v165, 0xffff0000, v45
	v_lshlrev_b32_e32 v166, 16, v46
	v_and_b32_e32 v167, 0xffff0000, v46
	v_lshlrev_b32_e32 v168, 16, v47
	v_and_b32_e32 v169, 0xffff0000, v47
	v_pk_add_f32 v[146:147], v[146:147], v[154:155]
	v_pk_add_f32 v[148:149], v[148:149], v[156:157]
	v_pk_add_f32 v[150:151], v[150:151], v[158:159]
	v_pk_add_f32 v[152:153], v[152:153], v[160:161]
	v_pk_mul_f32 v[170:171], v[162:163], v[162:163]
	v_pk_mul_f32 v[172:173], v[164:165], v[164:165]
	v_pk_mul_f32 v[174:175], v[166:167], v[166:167]
	v_pk_mul_f32 v[176:177], v[168:169], v[168:169]
	v_pk_fma_f32 v[170:171], v[170:171], v[140:141], v[142:143] op_sel_hi:[1,0,0]
	v_pk_fma_f32 v[172:173], v[172:173], v[140:141], v[142:143] op_sel_hi:[1,0,0]
	v_pk_fma_f32 v[174:175], v[174:175], v[140:141], v[142:143] op_sel_hi:[1,0,0]
	v_pk_fma_f32 v[176:177], v[176:177], v[140:141], v[142:143] op_sel_hi:[1,0,0]
	v_pk_mul_f32 v[170:171], v[170:171], v[162:163]
	v_pk_mul_f32 v[172:173], v[172:173], v[164:165]
	v_pk_mul_f32 v[174:175], v[174:175], v[166:167]
	v_pk_mul_f32 v[176:177], v[176:177], v[168:169]
	v_pk_mul_f32 v[154:155], v[146:147], v[162:163]
	v_pk_mul_f32 v[156:157], v[148:149], v[164:165]
	v_pk_mul_f32 v[158:159], v[150:151], v[166:167]
	v_pk_mul_f32 v[160:161], v[152:153], v[168:169]
	v_exp_f32_e32 v170, v170
	v_exp_f32_e32 v171, v171
	v_exp_f32_e32 v172, v172
	v_exp_f32_e32 v173, v173
	v_exp_f32_e32 v174, v174
	v_exp_f32_e32 v175, v175
	v_exp_f32_e32 v176, v176
	v_exp_f32_e32 v177, v177
	v_pk_add_f32 v[170:171], v[170:171], 1.0 op_sel_hi:[1,0]
	v_pk_add_f32 v[172:173], v[172:173], 1.0 op_sel_hi:[1,0]
	v_pk_add_f32 v[174:175], v[174:175], 1.0 op_sel_hi:[1,0]
	v_pk_add_f32 v[176:177], v[176:177], 1.0 op_sel_hi:[1,0]
	v_rcp_f32_e32 v170, v170
	v_rcp_f32_e32 v171, v171
	v_rcp_f32_e32 v172, v172
	v_rcp_f32_e32 v173, v173
	v_rcp_f32_e32 v174, v174
	v_rcp_f32_e32 v175, v175
	v_rcp_f32_e32 v176, v176
	v_rcp_f32_e32 v177, v177
	v_pk_mul_f32 v[96:97], v[154:155], v[170:171]
	v_pk_mul_f32 v[98:99], v[156:157], v[172:173]
	v_pk_mul_f32 v[100:101], v[158:159], v[174:175]
	v_pk_mul_f32 v[102:103], v[160:161], v[176:177]
	v_pk_mul_f32 v[112:113], v[96:97], v[96:97]
	v_pk_mul_f32 v[114:115], v[98:99], v[98:99]
	v_pk_fma_f32 v[112:113], v[100:101], v[100:101], v[112:113]
	v_pk_fma_f32 v[114:115], v[102:103], v[102:103], v[114:115]
	v_pk_add_f32 v[112:113], v[112:113], v[114:115]
	v_add_f32_e32 v112, v112, v113
	s_nop 1
	v_add_f32_dpp v112, v112, v112 quad_perm:[1,0,3,2] row_mask:0xf bank_mask:0xf
	s_nop 1
	v_add_f32_dpp v112, v112, v112 quad_perm:[2,3,0,1] row_mask:0xf bank_mask:0xf
	s_nop 1
	v_add_f32_dpp v112, v112, v112 row_half_mirror row_mask:0xf bank_mask:0xf
	s_nop 1
	v_add_f32_dpp v112, v112, v112 row_mirror row_mask:0xf bank_mask:0xf
	s_nop 1
	v_readlane_b32 s98, v112, 0
	v_readlane_b32 s99, v112, 16
	v_readlane_b32 s100, v112, 32
	v_readlane_b32 vcc_lo, v112, 48
	s_nop 1
	v_mov_b32_e32 v113, s98
	v_add_f32_e32 v113, s99, v113
	v_add_f32_e32 v113, s100, v113
	v_add_f32_e32 v113, vcc_lo, v113
	v_fmamk_f32 v144, v113, 0x3b000000, v131
	v_rsq_f32_e32 v144, v144
	s_nop 0
	v_pk_mul_f32 v[146:147], v[96:97], v[144:145] op_sel_hi:[1,0]
	v_pk_mul_f32 v[148:149], v[98:99], v[144:145] op_sel_hi:[1,0]
	v_pk_mul_f32 v[150:151], v[100:101], v[144:145] op_sel_hi:[1,0]
	v_pk_mul_f32 v[152:153], v[102:103], v[144:145] op_sel_hi:[1,0]
	v_pk_mul_f32 v[146:147], v[146:147], v[120:121]
	v_pk_mul_f32 v[148:149], v[148:149], v[122:123]
	v_pk_mul_f32 v[150:151], v[150:151], v[124:125]
	v_pk_mul_f32 v[152:153], v[152:153], v[126:127]
	v_cvt_pk_bf16_f32 v116, v146, v147
	v_cvt_pk_bf16_f32 v117, v148, v149
	v_cvt_pk_bf16_f32 v118, v150, v151
	v_cvt_pk_bf16_f32 v119, v152, v153
	v_add_u32_e32 v138, 0x2c00000, v135
	global_store_dwordx4 v138, v[116:119], s[34:35]
	s_waitcnt vmcnt(16)
	v_lshlrev_b32_e32 v146, 16, v48
	v_and_b32_e32 v147, 0xffff0000, v48
	v_lshlrev_b32_e32 v148, 16, v49
	v_and_b32_e32 v149, 0xffff0000, v49
	v_lshlrev_b32_e32 v150, 16, v50
	v_and_b32_e32 v151, 0xffff0000, v50
	v_lshlrev_b32_e32 v152, 16, v51
	v_and_b32_e32 v153, 0xffff0000, v51
	v_lshlrev_b32_e32 v154, 16, v52
	v_and_b32_e32 v155, 0xffff0000, v52
	v_lshlrev_b32_e32 v156, 16, v53
	v_and_b32_e32 v157, 0xffff0000, v53
	v_lshlrev_b32_e32 v158, 16, v54
	v_and_b32_e32 v159, 0xffff0000, v54
	v_lshlrev_b32_e32 v160, 16, v55
	v_and_b32_e32 v161, 0xffff0000, v55
	v_lshlrev_b32_e32 v162, 16, v56
	v_and_b32_e32 v163, 0xffff0000, v56
	v_lshlrev_b32_e32 v164, 16, v57
	v_and_b32_e32 v165, 0xffff0000, v57
	v_lshlrev_b32_e32 v166, 16, v58
	v_and_b32_e32 v167, 0xffff0000, v58
	v_lshlrev_b32_e32 v168, 16, v59
	v_and_b32_e32 v169, 0xffff0000, v59
	v_pk_add_f32 v[146:147], v[146:147], v[154:155]
	v_pk_add_f32 v[148:149], v[148:149], v[156:157]
	v_pk_add_f32 v[150:151], v[150:151], v[158:159]
	v_pk_add_f32 v[152:153], v[152:153], v[160:161]
	v_pk_mul_f32 v[170:171], v[162:163], v[162:163]
	v_pk_mul_f32 v[172:173], v[164:165], v[164:165]
	v_pk_mul_f32 v[174:175], v[166:167], v[166:167]
	v_pk_mul_f32 v[176:177], v[168:169], v[168:169]
	v_pk_fma_f32 v[170:171], v[170:171], v[140:141], v[142:143] op_sel_hi:[1,0,0]
	v_pk_fma_f32 v[172:173], v[172:173], v[140:141], v[142:143] op_sel_hi:[1,0,0]
	v_pk_fma_f32 v[174:175], v[174:175], v[140:141], v[142:143] op_sel_hi:[1,0,0]
	v_pk_fma_f32 v[176:177], v[176:177], v[140:141], v[142:143] op_sel_hi:[1,0,0]
	v_pk_mul_f32 v[170:171], v[170:171], v[162:163]
	v_pk_mul_f32 v[172:173], v[172:173], v[164:165]
	v_pk_mul_f32 v[174:175], v[174:175], v[166:167]
	v_pk_mul_f32 v[176:177], v[176:177], v[168:169]
	v_pk_mul_f32 v[154:155], v[146:147], v[162:163]
	v_pk_mul_f32 v[156:157], v[148:149], v[164:165]
	v_pk_mul_f32 v[158:159], v[150:151], v[166:167]
	v_pk_mul_f32 v[160:161], v[152:153], v[168:169]
	v_exp_f32_e32 v170, v170
	v_exp_f32_e32 v171, v171
	v_exp_f32_e32 v172, v172
	v_exp_f32_e32 v173, v173
	v_exp_f32_e32 v174, v174
	v_exp_f32_e32 v175, v175
	v_exp_f32_e32 v176, v176
	v_exp_f32_e32 v177, v177
	v_pk_add_f32 v[170:171], v[170:171], 1.0 op_sel_hi:[1,0]
	v_pk_add_f32 v[172:173], v[172:173], 1.0 op_sel_hi:[1,0]
	v_pk_add_f32 v[174:175], v[174:175], 1.0 op_sel_hi:[1,0]
	v_pk_add_f32 v[176:177], v[176:177], 1.0 op_sel_hi:[1,0]
	v_rcp_f32_e32 v170, v170
	v_rcp_f32_e32 v171, v171
	v_rcp_f32_e32 v172, v172
	v_rcp_f32_e32 v173, v173
	v_rcp_f32_e32 v174, v174
	v_rcp_f32_e32 v175, v175
	v_rcp_f32_e32 v176, v176
	v_rcp_f32_e32 v177, v177
	v_pk_mul_f32 v[96:97], v[154:155], v[170:171]
	v_pk_mul_f32 v[98:99], v[156:157], v[172:173]
	v_pk_mul_f32 v[100:101], v[158:159], v[174:175]
	v_pk_mul_f32 v[102:103], v[160:161], v[176:177]
	v_pk_mul_f32 v[112:113], v[96:97], v[96:97]
	v_pk_mul_f32 v[114:115], v[98:99], v[98:99]
	v_pk_fma_f32 v[112:113], v[100:101], v[100:101], v[112:113]
	v_pk_fma_f32 v[114:115], v[102:103], v[102:103], v[114:115]
	v_pk_add_f32 v[112:113], v[112:113], v[114:115]
	v_add_f32_e32 v112, v112, v113
	s_nop 1
	v_add_f32_dpp v112, v112, v112 quad_perm:[1,0,3,2] row_mask:0xf bank_mask:0xf
	s_nop 1
	v_add_f32_dpp v112, v112, v112 quad_perm:[2,3,0,1] row_mask:0xf bank_mask:0xf
	s_nop 1
	v_add_f32_dpp v112, v112, v112 row_half_mirror row_mask:0xf bank_mask:0xf
	s_nop 1
	v_add_f32_dpp v112, v112, v112 row_mirror row_mask:0xf bank_mask:0xf
	s_nop 1
	v_readlane_b32 s98, v112, 0
	v_readlane_b32 s99, v112, 16
	v_readlane_b32 s100, v112, 32
	v_readlane_b32 vcc_lo, v112, 48
	s_nop 1
	v_mov_b32_e32 v113, s98
	v_add_f32_e32 v113, s99, v113
	v_add_f32_e32 v113, s100, v113
	v_add_f32_e32 v113, vcc_lo, v113
	v_fmamk_f32 v144, v113, 0x3b000000, v131
	v_rsq_f32_e32 v144, v144
	s_nop 0
	v_pk_mul_f32 v[146:147], v[96:97], v[144:145] op_sel_hi:[1,0]
	v_pk_mul_f32 v[148:149], v[98:99], v[144:145] op_sel_hi:[1,0]
	v_pk_mul_f32 v[150:151], v[100:101], v[144:145] op_sel_hi:[1,0]
	v_pk_mul_f32 v[152:153], v[102:103], v[144:145] op_sel_hi:[1,0]
	v_pk_mul_f32 v[146:147], v[146:147], v[120:121]
	v_pk_mul_f32 v[148:149], v[148:149], v[122:123]
	v_pk_mul_f32 v[150:151], v[150:151], v[124:125]
	v_pk_mul_f32 v[152:153], v[152:153], v[126:127]
	v_cvt_pk_bf16_f32 v116, v146, v147
	v_cvt_pk_bf16_f32 v117, v148, v149
	v_cvt_pk_bf16_f32 v118, v150, v151
	v_cvt_pk_bf16_f32 v119, v152, v153
	v_add_u32_e32 v138, 0x3000000, v135
	global_store_dwordx4 v138, v[116:119], s[34:35]
	s_waitcnt vmcnt(13)
	v_lshlrev_b32_e32 v146, 16, v60
	v_and_b32_e32 v147, 0xffff0000, v60
	v_lshlrev_b32_e32 v148, 16, v61
	v_and_b32_e32 v149, 0xffff0000, v61
	v_lshlrev_b32_e32 v150, 16, v62
	v_and_b32_e32 v151, 0xffff0000, v62
	v_lshlrev_b32_e32 v152, 16, v63
	v_and_b32_e32 v153, 0xffff0000, v63
	v_lshlrev_b32_e32 v154, 16, v64
	v_and_b32_e32 v155, 0xffff0000, v64
	v_lshlrev_b32_e32 v156, 16, v65
	v_and_b32_e32 v157, 0xffff0000, v65
	v_lshlrev_b32_e32 v158, 16, v66
	v_and_b32_e32 v159, 0xffff0000, v66
	v_lshlrev_b32_e32 v160, 16, v67
	v_and_b32_e32 v161, 0xffff0000, v67
	v_lshlrev_b32_e32 v162, 16, v68
	v_and_b32_e32 v163, 0xffff0000, v68
	v_lshlrev_b32_e32 v164, 16, v69
	v_and_b32_e32 v165, 0xffff0000, v69
	v_lshlrev_b32_e32 v166, 16, v70
	v_and_b32_e32 v167, 0xffff0000, v70
	v_lshlrev_b32_e32 v168, 16, v71
	v_and_b32_e32 v169, 0xffff0000, v71
	v_pk_add_f32 v[146:147], v[146:147], v[154:155]
	v_pk_add_f32 v[148:149], v[148:149], v[156:157]
	v_pk_add_f32 v[150:151], v[150:151], v[158:159]
	v_pk_add_f32 v[152:153], v[152:153], v[160:161]
	v_pk_mul_f32 v[170:171], v[162:163], v[162:163]
	v_pk_mul_f32 v[172:173], v[164:165], v[164:165]
	v_pk_mul_f32 v[174:175], v[166:167], v[166:167]
	v_pk_mul_f32 v[176:177], v[168:169], v[168:169]
	v_pk_fma_f32 v[170:171], v[170:171], v[140:141], v[142:143] op_sel_hi:[1,0,0]
	v_pk_fma_f32 v[172:173], v[172:173], v[140:141], v[142:143] op_sel_hi:[1,0,0]
	v_pk_fma_f32 v[174:175], v[174:175], v[140:141], v[142:143] op_sel_hi:[1,0,0]
	v_pk_fma_f32 v[176:177], v[176:177], v[140:141], v[142:143] op_sel_hi:[1,0,0]
	v_pk_mul_f32 v[170:171], v[170:171], v[162:163]
	v_pk_mul_f32 v[172:173], v[172:173], v[164:165]
	v_pk_mul_f32 v[174:175], v[174:175], v[166:167]
	v_pk_mul_f32 v[176:177], v[176:177], v[168:169]
	v_pk_mul_f32 v[154:155], v[146:147], v[162:163]
	v_pk_mul_f32 v[156:157], v[148:149], v[164:165]
	v_pk_mul_f32 v[158:159], v[150:151], v[166:167]
	v_pk_mul_f32 v[160:161], v[152:153], v[168:169]
	v_exp_f32_e32 v170, v170
	v_exp_f32_e32 v171, v171
	v_exp_f32_e32 v172, v172
	v_exp_f32_e32 v173, v173
	v_exp_f32_e32 v174, v174
	v_exp_f32_e32 v175, v175
	v_exp_f32_e32 v176, v176
	v_exp_f32_e32 v177, v177
	v_pk_add_f32 v[170:171], v[170:171], 1.0 op_sel_hi:[1,0]
	v_pk_add_f32 v[172:173], v[172:173], 1.0 op_sel_hi:[1,0]
	v_pk_add_f32 v[174:175], v[174:175], 1.0 op_sel_hi:[1,0]
	v_pk_add_f32 v[176:177], v[176:177], 1.0 op_sel_hi:[1,0]
	v_rcp_f32_e32 v170, v170
	v_rcp_f32_e32 v171, v171
	v_rcp_f32_e32 v172, v172
	v_rcp_f32_e32 v173, v173
	v_rcp_f32_e32 v174, v174
	v_rcp_f32_e32 v175, v175
	v_rcp_f32_e32 v176, v176
	v_rcp_f32_e32 v177, v177
	v_pk_mul_f32 v[96:97], v[154:155], v[170:171]
	v_pk_mul_f32 v[98:99], v[156:157], v[172:173]
	v_pk_mul_f32 v[100:101], v[158:159], v[174:175]
	v_pk_mul_f32 v[102:103], v[160:161], v[176:177]
	v_pk_mul_f32 v[112:113], v[96:97], v[96:97]
	v_pk_mul_f32 v[114:115], v[98:99], v[98:99]
	v_pk_fma_f32 v[112:113], v[100:101], v[100:101], v[112:113]
	v_pk_fma_f32 v[114:115], v[102:103], v[102:103], v[114:115]
	v_pk_add_f32 v[112:113], v[112:113], v[114:115]
	v_add_f32_e32 v112, v112, v113
	s_nop 1
	v_add_f32_dpp v112, v112, v112 quad_perm:[1,0,3,2] row_mask:0xf bank_mask:0xf
	s_nop 1
	v_add_f32_dpp v112, v112, v112 quad_perm:[2,3,0,1] row_mask:0xf bank_mask:0xf
	s_nop 1
	v_add_f32_dpp v112, v112, v112 row_half_mirror row_mask:0xf bank_mask:0xf
	s_nop 1
	v_add_f32_dpp v112, v112, v112 row_mirror row_mask:0xf bank_mask:0xf
	s_nop 1
	v_readlane_b32 s98, v112, 0
	v_readlane_b32 s99, v112, 16
	v_readlane_b32 s100, v112, 32
	v_readlane_b32 vcc_lo, v112, 48
	s_nop 1
	v_mov_b32_e32 v113, s98
	v_add_f32_e32 v113, s99, v113
	v_add_f32_e32 v113, s100, v113
	v_add_f32_e32 v113, vcc_lo, v113
	v_fmamk_f32 v144, v113, 0x3b000000, v131
	v_rsq_f32_e32 v144, v144
	s_nop 0
	v_pk_mul_f32 v[146:147], v[96:97], v[144:145] op_sel_hi:[1,0]
	v_pk_mul_f32 v[148:149], v[98:99], v[144:145] op_sel_hi:[1,0]
	v_pk_mul_f32 v[150:151], v[100:101], v[144:145] op_sel_hi:[1,0]
	v_pk_mul_f32 v[152:153], v[102:103], v[144:145] op_sel_hi:[1,0]
	v_pk_mul_f32 v[146:147], v[146:147], v[120:121]
	v_pk_mul_f32 v[148:149], v[148:149], v[122:123]
	v_pk_mul_f32 v[150:151], v[150:151], v[124:125]
	v_pk_mul_f32 v[152:153], v[152:153], v[126:127]
	v_cvt_pk_bf16_f32 v116, v146, v147
	v_cvt_pk_bf16_f32 v117, v148, v149
	v_cvt_pk_bf16_f32 v118, v150, v151
	v_cvt_pk_bf16_f32 v119, v152, v153
	v_add_u32_e32 v138, 0x3400000, v135
	global_store_dwordx4 v138, v[116:119], s[34:35]
	s_waitcnt vmcnt(10)
	v_lshlrev_b32_e32 v146, 16, v72
	v_and_b32_e32 v147, 0xffff0000, v72
	v_lshlrev_b32_e32 v148, 16, v73
	v_and_b32_e32 v149, 0xffff0000, v73
	v_lshlrev_b32_e32 v150, 16, v74
	v_and_b32_e32 v151, 0xffff0000, v74
	v_lshlrev_b32_e32 v152, 16, v75
	v_and_b32_e32 v153, 0xffff0000, v75
	v_lshlrev_b32_e32 v154, 16, v76
	v_and_b32_e32 v155, 0xffff0000, v76
	v_lshlrev_b32_e32 v156, 16, v77
	v_and_b32_e32 v157, 0xffff0000, v77
	v_lshlrev_b32_e32 v158, 16, v78
	v_and_b32_e32 v159, 0xffff0000, v78
	v_lshlrev_b32_e32 v160, 16, v79
	v_and_b32_e32 v161, 0xffff0000, v79
	v_lshlrev_b32_e32 v162, 16, v80
	v_and_b32_e32 v163, 0xffff0000, v80
	v_lshlrev_b32_e32 v164, 16, v81
	v_and_b32_e32 v165, 0xffff0000, v81
	v_lshlrev_b32_e32 v166, 16, v82
	v_and_b32_e32 v167, 0xffff0000, v82
	v_lshlrev_b32_e32 v168, 16, v83
	v_and_b32_e32 v169, 0xffff0000, v83
	v_pk_add_f32 v[146:147], v[146:147], v[154:155]
	v_pk_add_f32 v[148:149], v[148:149], v[156:157]
	v_pk_add_f32 v[150:151], v[150:151], v[158:159]
	v_pk_add_f32 v[152:153], v[152:153], v[160:161]
	v_pk_mul_f32 v[170:171], v[162:163], v[162:163]
	v_pk_mul_f32 v[172:173], v[164:165], v[164:165]
	v_pk_mul_f32 v[174:175], v[166:167], v[166:167]
	v_pk_mul_f32 v[176:177], v[168:169], v[168:169]
	v_pk_fma_f32 v[170:171], v[170:171], v[140:141], v[142:143] op_sel_hi:[1,0,0]
	v_pk_fma_f32 v[172:173], v[172:173], v[140:141], v[142:143] op_sel_hi:[1,0,0]
	v_pk_fma_f32 v[174:175], v[174:175], v[140:141], v[142:143] op_sel_hi:[1,0,0]
	v_pk_fma_f32 v[176:177], v[176:177], v[140:141], v[142:143] op_sel_hi:[1,0,0]
	v_pk_mul_f32 v[170:171], v[170:171], v[162:163]
	v_pk_mul_f32 v[172:173], v[172:173], v[164:165]
	v_pk_mul_f32 v[174:175], v[174:175], v[166:167]
	v_pk_mul_f32 v[176:177], v[176:177], v[168:169]
	v_pk_mul_f32 v[154:155], v[146:147], v[162:163]
	v_pk_mul_f32 v[156:157], v[148:149], v[164:165]
	v_pk_mul_f32 v[158:159], v[150:151], v[166:167]
	v_pk_mul_f32 v[160:161], v[152:153], v[168:169]
	v_exp_f32_e32 v170, v170
	v_exp_f32_e32 v171, v171
	v_exp_f32_e32 v172, v172
	v_exp_f32_e32 v173, v173
	v_exp_f32_e32 v174, v174
	v_exp_f32_e32 v175, v175
	v_exp_f32_e32 v176, v176
	v_exp_f32_e32 v177, v177
	v_pk_add_f32 v[170:171], v[170:171], 1.0 op_sel_hi:[1,0]
	v_pk_add_f32 v[172:173], v[172:173], 1.0 op_sel_hi:[1,0]
	v_pk_add_f32 v[174:175], v[174:175], 1.0 op_sel_hi:[1,0]
	v_pk_add_f32 v[176:177], v[176:177], 1.0 op_sel_hi:[1,0]
	v_rcp_f32_e32 v170, v170
	v_rcp_f32_e32 v171, v171
	v_rcp_f32_e32 v172, v172
	v_rcp_f32_e32 v173, v173
	v_rcp_f32_e32 v174, v174
	v_rcp_f32_e32 v175, v175
	v_rcp_f32_e32 v176, v176
	v_rcp_f32_e32 v177, v177
	v_pk_mul_f32 v[96:97], v[154:155], v[170:171]
	v_pk_mul_f32 v[98:99], v[156:157], v[172:173]
	v_pk_mul_f32 v[100:101], v[158:159], v[174:175]
	v_pk_mul_f32 v[102:103], v[160:161], v[176:177]
	v_pk_mul_f32 v[112:113], v[96:97], v[96:97]
	v_pk_mul_f32 v[114:115], v[98:99], v[98:99]
	v_pk_fma_f32 v[112:113], v[100:101], v[100:101], v[112:113]
	v_pk_fma_f32 v[114:115], v[102:103], v[102:103], v[114:115]
	v_pk_add_f32 v[112:113], v[112:113], v[114:115]
	v_add_f32_e32 v112, v112, v113
	s_nop 1
	v_add_f32_dpp v112, v112, v112 quad_perm:[1,0,3,2] row_mask:0xf bank_mask:0xf
	s_nop 1
	v_add_f32_dpp v112, v112, v112 quad_perm:[2,3,0,1] row_mask:0xf bank_mask:0xf
	s_nop 1
	v_add_f32_dpp v112, v112, v112 row_half_mirror row_mask:0xf bank_mask:0xf
	s_nop 1
	v_add_f32_dpp v112, v112, v112 row_mirror row_mask:0xf bank_mask:0xf
	s_nop 1
	v_readlane_b32 s98, v112, 0
	v_readlane_b32 s99, v112, 16
	v_readlane_b32 s100, v112, 32
	v_readlane_b32 vcc_lo, v112, 48
	s_nop 1
	v_mov_b32_e32 v113, s98
	v_add_f32_e32 v113, s99, v113
	v_add_f32_e32 v113, s100, v113
	v_add_f32_e32 v113, vcc_lo, v113
	v_fmamk_f32 v144, v113, 0x3b000000, v131
	v_rsq_f32_e32 v144, v144
	s_nop 0
	v_pk_mul_f32 v[146:147], v[96:97], v[144:145] op_sel_hi:[1,0]
	v_pk_mul_f32 v[148:149], v[98:99], v[144:145] op_sel_hi:[1,0]
	v_pk_mul_f32 v[150:151], v[100:101], v[144:145] op_sel_hi:[1,0]
	v_pk_mul_f32 v[152:153], v[102:103], v[144:145] op_sel_hi:[1,0]
	v_pk_mul_f32 v[146:147], v[146:147], v[120:121]
	v_pk_mul_f32 v[148:149], v[148:149], v[122:123]
	v_pk_mul_f32 v[150:151], v[150:151], v[124:125]
	v_pk_mul_f32 v[152:153], v[152:153], v[126:127]
	v_cvt_pk_bf16_f32 v116, v146, v147
	v_cvt_pk_bf16_f32 v117, v148, v149
	v_cvt_pk_bf16_f32 v118, v150, v151
	v_cvt_pk_bf16_f32 v119, v152, v153
	v_add_u32_e32 v138, 0x3800000, v135
	global_store_dwordx4 v138, v[116:119], s[34:35]
	s_waitcnt vmcnt(7)
	v_lshlrev_b32_e32 v146, 16, v84
	v_and_b32_e32 v147, 0xffff0000, v84
	v_lshlrev_b32_e32 v148, 16, v85
	v_and_b32_e32 v149, 0xffff0000, v85
	v_lshlrev_b32_e32 v150, 16, v86
	v_and_b32_e32 v151, 0xffff0000, v86
	v_lshlrev_b32_e32 v152, 16, v87
	v_and_b32_e32 v153, 0xffff0000, v87
	v_lshlrev_b32_e32 v154, 16, v88
	v_and_b32_e32 v155, 0xffff0000, v88
	v_lshlrev_b32_e32 v156, 16, v89
	v_and_b32_e32 v157, 0xffff0000, v89
	v_lshlrev_b32_e32 v158, 16, v90
	v_and_b32_e32 v159, 0xffff0000, v90
	v_lshlrev_b32_e32 v160, 16, v91
	v_and_b32_e32 v161, 0xffff0000, v91
	v_lshlrev_b32_e32 v162, 16, v92
	v_and_b32_e32 v163, 0xffff0000, v92
	v_lshlrev_b32_e32 v164, 16, v93
	v_and_b32_e32 v165, 0xffff0000, v93
	v_lshlrev_b32_e32 v166, 16, v94
	v_and_b32_e32 v167, 0xffff0000, v94
	v_lshlrev_b32_e32 v168, 16, v95
	v_and_b32_e32 v169, 0xffff0000, v95
	v_pk_add_f32 v[146:147], v[146:147], v[154:155]
	v_pk_add_f32 v[148:149], v[148:149], v[156:157]
	v_pk_add_f32 v[150:151], v[150:151], v[158:159]
	v_pk_add_f32 v[152:153], v[152:153], v[160:161]
	v_pk_mul_f32 v[170:171], v[162:163], v[162:163]
	v_pk_mul_f32 v[172:173], v[164:165], v[164:165]
	v_pk_mul_f32 v[174:175], v[166:167], v[166:167]
	v_pk_mul_f32 v[176:177], v[168:169], v[168:169]
	v_pk_fma_f32 v[170:171], v[170:171], v[140:141], v[142:143] op_sel_hi:[1,0,0]
	v_pk_fma_f32 v[172:173], v[172:173], v[140:141], v[142:143] op_sel_hi:[1,0,0]
	v_pk_fma_f32 v[174:175], v[174:175], v[140:141], v[142:143] op_sel_hi:[1,0,0]
	v_pk_fma_f32 v[176:177], v[176:177], v[140:141], v[142:143] op_sel_hi:[1,0,0]
	v_pk_mul_f32 v[170:171], v[170:171], v[162:163]
	v_pk_mul_f32 v[172:173], v[172:173], v[164:165]
	v_pk_mul_f32 v[174:175], v[174:175], v[166:167]
	v_pk_mul_f32 v[176:177], v[176:177], v[168:169]
	v_pk_mul_f32 v[154:155], v[146:147], v[162:163]
	v_pk_mul_f32 v[156:157], v[148:149], v[164:165]
	v_pk_mul_f32 v[158:159], v[150:151], v[166:167]
	v_pk_mul_f32 v[160:161], v[152:153], v[168:169]
	v_exp_f32_e32 v170, v170
	v_exp_f32_e32 v171, v171
	v_exp_f32_e32 v172, v172
	v_exp_f32_e32 v173, v173
	v_exp_f32_e32 v174, v174
	v_exp_f32_e32 v175, v175
	v_exp_f32_e32 v176, v176
	v_exp_f32_e32 v177, v177
	v_pk_add_f32 v[170:171], v[170:171], 1.0 op_sel_hi:[1,0]
	v_pk_add_f32 v[172:173], v[172:173], 1.0 op_sel_hi:[1,0]
	v_pk_add_f32 v[174:175], v[174:175], 1.0 op_sel_hi:[1,0]
	v_pk_add_f32 v[176:177], v[176:177], 1.0 op_sel_hi:[1,0]
	v_rcp_f32_e32 v170, v170
	v_rcp_f32_e32 v171, v171
	v_rcp_f32_e32 v172, v172
	v_rcp_f32_e32 v173, v173
	v_rcp_f32_e32 v174, v174
	v_rcp_f32_e32 v175, v175
	v_rcp_f32_e32 v176, v176
	v_rcp_f32_e32 v177, v177
	v_pk_mul_f32 v[96:97], v[154:155], v[170:171]
	v_pk_mul_f32 v[98:99], v[156:157], v[172:173]
	v_pk_mul_f32 v[100:101], v[158:159], v[174:175]
	v_pk_mul_f32 v[102:103], v[160:161], v[176:177]
	v_pk_mul_f32 v[112:113], v[96:97], v[96:97]
	v_pk_mul_f32 v[114:115], v[98:99], v[98:99]
	v_pk_fma_f32 v[112:113], v[100:101], v[100:101], v[112:113]
	v_pk_fma_f32 v[114:115], v[102:103], v[102:103], v[114:115]
	v_pk_add_f32 v[112:113], v[112:113], v[114:115]
	v_add_f32_e32 v112, v112, v113
	s_nop 1
	v_add_f32_dpp v112, v112, v112 quad_perm:[1,0,3,2] row_mask:0xf bank_mask:0xf
	s_nop 1
	v_add_f32_dpp v112, v112, v112 quad_perm:[2,3,0,1] row_mask:0xf bank_mask:0xf
	s_nop 1
	v_add_f32_dpp v112, v112, v112 row_half_mirror row_mask:0xf bank_mask:0xf
	s_nop 1
	v_add_f32_dpp v112, v112, v112 row_mirror row_mask:0xf bank_mask:0xf
	s_nop 1
	v_readlane_b32 s98, v112, 0
	v_readlane_b32 s99, v112, 16
	v_readlane_b32 s100, v112, 32
	v_readlane_b32 vcc_lo, v112, 48
	s_nop 1
	v_mov_b32_e32 v113, s98
	v_add_f32_e32 v113, s99, v113
	v_add_f32_e32 v113, s100, v113
	v_add_f32_e32 v113, vcc_lo, v113
	v_fmamk_f32 v144, v113, 0x3b000000, v131
	v_rsq_f32_e32 v144, v144
	s_nop 0
	v_pk_mul_f32 v[146:147], v[96:97], v[144:145] op_sel_hi:[1,0]
	v_pk_mul_f32 v[148:149], v[98:99], v[144:145] op_sel_hi:[1,0]
	v_pk_mul_f32 v[150:151], v[100:101], v[144:145] op_sel_hi:[1,0]
	v_pk_mul_f32 v[152:153], v[102:103], v[144:145] op_sel_hi:[1,0]
	v_pk_mul_f32 v[146:147], v[146:147], v[120:121]
	v_pk_mul_f32 v[148:149], v[148:149], v[122:123]
	v_pk_mul_f32 v[150:151], v[150:151], v[124:125]
	v_pk_mul_f32 v[152:153], v[152:153], v[126:127]
	v_cvt_pk_bf16_f32 v116, v146, v147
	v_cvt_pk_bf16_f32 v117, v148, v149
	v_cvt_pk_bf16_f32 v118, v150, v151
	v_cvt_pk_bf16_f32 v119, v152, v153
	v_add_u32_e32 v138, 0x3c00000, v135
	global_store_dwordx4 v138, v[116:119], s[34:35]
	s_cmp_eq_u32 s101, 0
	s_cbranch_scc1 .Lcomb_retA
	s_branch .Lcomb_retB
